# rotated the K-loop back edge in the 7 GEMM loops (taken branch resolved before the loop-back barrier, exit-path barrier copy), asm guide 7.11
# baseline (speedup 1.0000x reference)
; #define PG8_STAGE_A(bufoff, ptr, half, rev) do { if (REVA && (rev)) { const char* _p = (ptr) - ((half) ? hstepA : 0); PG8_STAGE(bufoff, _p, voffAr); } else { const char* _p = (ptr) + ((half) ? hstepA : 0); PG8_STAGE(bufoff, _p, voffA); } } while (0)
; #define PG8_LDA(dst, b, h) do { _Pragma("unroll") for (int m = 0; m < 4; ++m) _Pragma("unroll") for (int k = 0; k < 2; ++k) dst[m][k] = *(const LAS bf16x8*)(lds + PG8_SA(b, h) + aoff + m * 2048 + k * 1024); } while (0)
; #define PG8_LDB(dst, b, h) do { _Pragma("unroll") for (int n = 0; n < 2; ++n) _Pragma("unroll") for (int k = 0; k < 2; ++k) dst[n][k] = *(const LAS bf16x8*)(lds + PG8_SB(b, h) + boff + n * 2048 + k * 1024); } while (0)
; #define PG8_SCHED __builtin_amdgcn_sched_barrier(0)
;     ...
;             PG8_LDB(B0, 0, 0); PG8_SCHED; PG8_LDA(At, 0, 0); PG8_STAGE_A(PG8_SA(1, 1), a1, 1, r1);
;     ...
;         for (int a = 0; a < 2; ++a)
; #pragma unroll
;             for (int b = 0; b < 2; ++b)
; #pragma unroll
;                 for (int m = 0; m < 4; ++m)
; #pragma unroll
;                     for (int n = 0; n < 2; ++n) acc[a][b][m][n] = (f32x4){0.f, 0.f, 0.f, 0.f};
;         cur = nxt; cA = nA; cB = nB; cAr = nAr; cHb = nHb; ++ui;
.LBB0_233:
	s_add_u32 s3, s0, 0x80
	s_addc_u32 s6, s1, 0
	s_add_u32 s8, s38, 0x80080
	s_addc_u32 s9, s39, 0
	s_add_u32 s7, s20, 0x100
	v_mov_b32_e32 v0, 0
	v_lshl_add_u64 v[88:89], s[8:9], 0, v[150:151]
	v_lshl_add_u64 v[90:91], s[8:9], 0, v[152:153]
	s_addc_u32 s8, s21, 0
	s_mov_b32 s9, -2
	s_mov_b64 vcc, 0
	v_mov_b32_e32 v1, v0
	v_pk_mov_b32 v[2:3], v[0:1], v[0:1]
	v_pk_mov_b32 v[4:5], v[0:1], v[0:1]
	v_pk_mov_b32 v[6:7], v[0:1], v[0:1]
	v_pk_mov_b32 v[8:9], v[0:1], v[0:1]
	v_pk_mov_b32 v[10:11], v[0:1], v[0:1]
	v_pk_mov_b32 v[12:13], v[0:1], v[0:1]
	v_pk_mov_b32 v[14:15], v[0:1], v[0:1]
	v_pk_mov_b32 v[16:17], v[0:1], v[0:1]
	v_pk_mov_b32 v[18:19], v[0:1], v[0:1]
	v_pk_mov_b32 v[20:21], v[0:1], v[0:1]
	v_pk_mov_b32 v[22:23], v[0:1], v[0:1]
	v_pk_mov_b32 v[24:25], v[0:1], v[0:1]
	v_pk_mov_b32 v[26:27], v[0:1], v[0:1]
	v_pk_mov_b32 v[28:29], v[0:1], v[0:1]
	v_pk_mov_b32 v[30:31], v[0:1], v[0:1]
	v_pk_mov_b32 v[32:33], v[0:1], v[0:1]
	v_pk_mov_b32 v[34:35], v[0:1], v[0:1]
	v_pk_mov_b32 v[36:37], v[0:1], v[0:1]
	v_pk_mov_b32 v[38:39], v[0:1], v[0:1]
	v_pk_mov_b32 v[40:41], v[0:1], v[0:1]
	v_pk_mov_b32 v[42:43], v[0:1], v[0:1]
	v_pk_mov_b32 v[44:45], v[0:1], v[0:1]
	v_pk_mov_b32 v[46:47], v[0:1], v[0:1]
	v_pk_mov_b32 v[48:49], v[0:1], v[0:1]
	v_pk_mov_b32 v[50:51], v[0:1], v[0:1]
	v_pk_mov_b32 v[52:53], v[0:1], v[0:1]
	v_pk_mov_b32 v[54:55], v[0:1], v[0:1]
	v_pk_mov_b32 v[56:57], v[0:1], v[0:1]
	v_pk_mov_b32 v[58:59], v[0:1], v[0:1]
	v_pk_mov_b32 v[60:61], v[0:1], v[0:1]
	v_pk_mov_b32 v[62:63], v[0:1], v[0:1]
	v_pk_mov_b32 v[64:65], v[0:1], v[0:1]
	v_pk_mov_b32 v[66:67], v[0:1], v[0:1]
	v_pk_mov_b32 v[68:69], v[0:1], v[0:1]
	v_pk_mov_b32 v[70:71], v[0:1], v[0:1]
	v_pk_mov_b32 v[72:73], v[0:1], v[0:1]
	v_pk_mov_b32 v[74:75], v[0:1], v[0:1]
	v_pk_mov_b32 v[76:77], v[0:1], v[0:1]
	v_pk_mov_b32 v[78:79], v[0:1], v[0:1]
	v_pk_mov_b32 v[80:81], v[0:1], v[0:1]
	v_pk_mov_b32 v[82:83], v[0:1], v[0:1]
	v_pk_mov_b32 v[84:85], v[0:1], v[0:1]
	v_pk_mov_b32 v[86:87], v[0:1], v[0:1]
	v_pk_mov_b32 v[100:101], v[0:1], v[0:1]
	v_pk_mov_b32 v[102:103], v[0:1], v[0:1]
	v_pk_mov_b32 v[104:105], v[0:1], v[0:1]
	v_pk_mov_b32 v[106:107], v[0:1], v[0:1]
	v_pk_mov_b32 v[108:109], v[0:1], v[0:1]
	v_pk_mov_b32 v[110:111], v[0:1], v[0:1]
	v_pk_mov_b32 v[112:113], v[0:1], v[0:1]
	v_pk_mov_b32 v[114:115], v[0:1], v[0:1]
	v_pk_mov_b32 v[116:117], v[0:1], v[0:1]
	v_pk_mov_b32 v[118:119], v[0:1], v[0:1]
	v_pk_mov_b32 v[120:121], v[0:1], v[0:1]
	v_pk_mov_b32 v[122:123], v[0:1], v[0:1]
	v_pk_mov_b32 v[124:125], v[0:1], v[0:1]
	v_pk_mov_b32 v[126:127], v[0:1], v[0:1]
	v_pk_mov_b32 v[128:129], v[0:1], v[0:1]
	v_pk_mov_b32 v[130:131], v[0:1], v[0:1]
	v_pk_mov_b32 v[132:133], v[0:1], v[0:1]
	v_pk_mov_b32 v[134:135], v[0:1], v[0:1]
	v_pk_mov_b32 v[136:137], v[0:1], v[0:1]
	v_pk_mov_b32 v[138:139], v[0:1], v[0:1]
	s_nop 0
	v_add_u32_e32 v154, 0x10000, v156
	ds_read_b128 v[92:95], v154
	ds_read_b128 v[96:99], v154 offset:1024
	ds_read_b128 v[172:175], v154 offset:2048
	ds_read_b128 v[176:179], v154 offset:3072
	s_branch .LBB0_234

; #define PG8_STAGE(bufoff, gbase, voff) do { _Pragma("unroll") for (int _i = 0; _i < 2; ++_i) \
;         __builtin_amdgcn_global_load_lds((const unsigned*)((const char*)(gbase) + (voff)[_i]), (LAS unsigned*)(lds + (bufoff) + ldsw + _i * 8192), 16, 0, 0); } while (0)
; #define PG8_STAGE_A(bufoff, ptr, half, rev) do { if (REVA && (rev)) { const char* _p = (ptr) - ((half) ? hstepA : 0); PG8_STAGE(bufoff, _p, voffAr); } else { const char* _p = (ptr) + ((half) ? hstepA : 0); PG8_STAGE(bufoff, _p, voffA); } } while (0)
; #define PG8_LDA(dst, b, h) do { _Pragma("unroll") for (int m = 0; m < 4; ++m) _Pragma("unroll") for (int k = 0; k < 2; ++k) dst[m][k] = *(const LAS bf16x8*)(lds + PG8_SA(b, h) + aoff + m * 2048 + k * 1024); } while (0)
; #define PG8_LDB(dst, b, h) do { _Pragma("unroll") for (int n = 0; n < 2; ++n) _Pragma("unroll") for (int k = 0; k < 2; ++k) dst[n][k] = *(const LAS bf16x8*)(lds + PG8_SB(b, h) + boff + n * 2048 + k * 1024); } while (0)
; #define PG8_MMA(ai, bj, At, Bt) do { __builtin_amdgcn_s_setprio(1); _Pragma("unroll") for (int m = 0; m < 4; ++m) _Pragma("unroll") for (int n = 0; n < 2; ++n) _Pragma("unroll") for (int k = 0; k < 2; ++k) \
;         acc[ai][bj][m][n] = __builtin_amdgcn_mfma_f32_16x16x32_bf16(Bt[n][k], At[m][k], acc[ai][bj][m][n], 0, 0, 0); __builtin_amdgcn_s_setprio(0); } while (0)
; #define PG8_WAIT_L(n) asm volatile("s_waitcnt lgkmcnt(" #n ")" ::: "memory")
; #define PG8_BAR __builtin_amdgcn_s_barrier()
; #define PG8_SCHED __builtin_amdgcn_sched_barrier(0)
;     ...
;             PG8_LDB(B0, 0, 0); PG8_SCHED; PG8_LDA(At, 0, 0); PG8_STAGE_A(PG8_SA(1, 1), a1, 1, r1);
;             PG8_WAIT_L(8); PG8_BAR; PG8_WAIT_L(0); PG8_MMA(0, 0, At, B0); PG8_BAR; PG8_SCHED;
;             PG8_LDB(B1, 0, 1); PG8_STAGE(PG8_SB(0, 0), b2, voffB);
;             PG8_BAR; PG8_WAIT_L(0); PG8_MMA(0, 1, At, B1); PG8_BAR;
;             PG8_LDA(At, 0, 1); PG8_STAGE_A(PG8_SA(0, 0), a2, 0, r2);
;             PG8_BAR; PG8_WAIT_L(0); PG8_MMA(1, 0, At, B0); PG8_BAR; PG8_SCHED;
.LBB0_234:
	s_add_u32 s10, s38, vcc_lo
	s_addc_u32 s11, s39, vcc_hi
	s_add_u32 s16, s10, 0x100
	s_addc_u32 s17, s11, 0
	s_add_u32 s10, s10, 0x180
	s_addc_u32 s11, s11, 0
	s_add_u32 s14, s7, vcc_lo
	s_addc_u32 s15, s8, vcc_hi
	s_add_i32 s27, 0, 0x10000
	s_cmpk_eq_i32 vcc_lo, 0xf00
	s_cselect_b32 s15, s71, s15
	s_cselect_b32 s14, s70, s14
	s_cselect_b32 s21, s1, s17
	s_cselect_b32 s20, s0, s16
	s_cselect_b32 s17, s6, s11
	s_cselect_b32 s16, s3, s10
	v_lshl_add_u64 v[154:155], v[88:89], 0, vcc
	s_add_i32 m0, s91, 0xc000
	ds_read_b128 v[180:183], v171
	ds_read_b128 v[204:207], v171 offset:1024
	ds_read_b128 v[208:211], v171 offset:2048
	ds_read_b128 v[212:215], v171 offset:3072
	ds_read_b128 v[216:219], v171 offset:4096
	ds_read_b128 v[220:223], v171 offset:5120
	ds_read_b128 v[224:227], v171 offset:6144
	ds_read_b128 v[228:231], v171 offset:7168
	global_load_lds_dwordx4 v[154:155], off
	v_lshl_add_u64 v[154:155], v[90:91], 0, vcc
	s_add_i32 m0, s91, 0xe000
	s_nop 0
	global_load_lds_dwordx4 v[154:155], off
	s_waitcnt lgkmcnt(8)
	s_waitcnt vmcnt(10)
	s_barrier
	s_waitcnt lgkmcnt(0)
	v_mfma_f32_16x16x32_bf16 v[104:107], v[92:95], v[180:183], v[104:107]
	v_mfma_f32_16x16x32_bf16 v[136:139], v[172:175], v[180:183], v[136:139]
	v_mfma_f32_16x16x32_bf16 v[84:87], v[92:95], v[208:211], v[84:87]
	v_mfma_f32_16x16x32_bf16 v[128:131], v[172:175], v[208:211], v[128:131]
	v_mfma_f32_16x16x32_bf16 v[76:79], v[92:95], v[216:219], v[76:79]
	v_mfma_f32_16x16x32_bf16 v[120:123], v[172:175], v[216:219], v[120:123]
	v_mfma_f32_16x16x32_bf16 v[68:71], v[92:95], v[224:227], v[68:71]
	v_mfma_f32_16x16x32_bf16 v[112:115], v[172:175], v[224:227], v[112:115]
	v_mfma_f32_16x16x32_bf16 v[104:107], v[96:99], v[204:207], v[104:107]
	v_mfma_f32_16x16x32_bf16 v[136:139], v[176:179], v[204:207], v[136:139]
	v_mfma_f32_16x16x32_bf16 v[84:87], v[96:99], v[212:215], v[84:87]
	v_mfma_f32_16x16x32_bf16 v[128:131], v[176:179], v[212:215], v[128:131]
	v_mfma_f32_16x16x32_bf16 v[76:79], v[96:99], v[220:223], v[76:79]
	v_mfma_f32_16x16x32_bf16 v[120:123], v[176:179], v[220:223], v[120:123]
	v_mfma_f32_16x16x32_bf16 v[68:71], v[96:99], v[228:231], v[68:71]
	v_mfma_f32_16x16x32_bf16 v[112:115], v[176:179], v[228:231], v[112:115]
	s_barrier
	s_add_i32 s37, 0, 0x14000
	v_add_u32_e32 v154, s37, v156
	s_add_i32 s10, s27, s90
	ds_read_b128 v[232:235], v154
	ds_read_b128 v[236:239], v154 offset:1024
	ds_read_b128 v[240:243], v154 offset:2048
	ds_read_b128 v[244:247], v154 offset:3072
	v_lshl_add_u64 v[154:155], s[14:15], 0, v[160:161]
	s_mov_b32 m0, s10
	v_lshl_add_u64 v[184:185], s[14:15], 0, v[140:141]
	global_load_lds_dwordx4 v[154:155], off
	s_add_i32 m0, s10, 0x2000
	s_nop 0
	global_load_lds_dwordx4 v[184:185], off
	s_waitcnt vmcnt(10)
	s_barrier
	s_waitcnt lgkmcnt(0)
	v_mfma_f32_16x16x32_bf16 v[132:135], v[232:235], v[180:183], v[132:135]
	v_mfma_f32_16x16x32_bf16 v[100:103], v[240:243], v[180:183], v[100:103]
	v_mfma_f32_16x16x32_bf16 v[124:127], v[232:235], v[208:211], v[124:127]
	v_mfma_f32_16x16x32_bf16 v[80:83], v[240:243], v[208:211], v[80:83]
	v_mfma_f32_16x16x32_bf16 v[116:119], v[232:235], v[216:219], v[116:119]
	v_mfma_f32_16x16x32_bf16 v[72:75], v[240:243], v[216:219], v[72:75]
	v_mfma_f32_16x16x32_bf16 v[108:111], v[232:235], v[224:227], v[108:111]
	v_mfma_f32_16x16x32_bf16 v[64:67], v[240:243], v[224:227], v[64:67]
	v_mfma_f32_16x16x32_bf16 v[132:135], v[236:239], v[204:207], v[132:135]
	v_mfma_f32_16x16x32_bf16 v[100:103], v[244:247], v[204:207], v[100:103]
	v_mfma_f32_16x16x32_bf16 v[124:127], v[236:239], v[212:215], v[124:127]
	v_mfma_f32_16x16x32_bf16 v[80:83], v[244:247], v[212:215], v[80:83]
	v_mfma_f32_16x16x32_bf16 v[116:119], v[236:239], v[220:223], v[116:119]
	v_mfma_f32_16x16x32_bf16 v[72:75], v[244:247], v[220:223], v[72:75]
	v_mfma_f32_16x16x32_bf16 v[108:111], v[236:239], v[228:231], v[108:111]
	v_mfma_f32_16x16x32_bf16 v[64:67], v[244:247], v[228:231], v[64:67]
	s_mov_b32 m0, s91
	v_lshl_add_u64 v[190:191], s[20:21], 0, v[160:161]
	s_barrier
	ds_read_b128 v[180:183], v171 offset:16384
	ds_read_b128 v[204:207], v171 offset:17408
	ds_read_b128 v[208:211], v171 offset:18432
	ds_read_b128 v[212:215], v171 offset:19456
	ds_read_b128 v[216:219], v171 offset:20480
	ds_read_b128 v[220:223], v171 offset:21504
	ds_read_b128 v[224:227], v171 offset:22528
	ds_read_b128 v[228:231], v171 offset:23552
	global_load_lds_dwordx4 v[190:191], off
	v_lshl_add_u64 v[190:191], s[20:21], 0, v[140:141]
	s_mov_b32 m0, s92
	s_nop 0
	global_load_lds_dwordx4 v[190:191], off
	s_waitcnt vmcnt(10)
	s_barrier
	s_waitcnt lgkmcnt(0)
	v_mfma_f32_16x16x32_bf16 v[28:31], v[92:95], v[180:183], v[28:31]
	v_mfma_f32_16x16x32_bf16 v[60:63], v[172:175], v[180:183], v[60:63]
	v_mfma_f32_16x16x32_bf16 v[20:23], v[92:95], v[208:211], v[20:23]
	v_mfma_f32_16x16x32_bf16 v[52:55], v[172:175], v[208:211], v[52:55]
	v_mfma_f32_16x16x32_bf16 v[12:15], v[92:95], v[216:219], v[12:15]
	v_mfma_f32_16x16x32_bf16 v[44:47], v[172:175], v[216:219], v[44:47]
	v_mfma_f32_16x16x32_bf16 v[4:7], v[92:95], v[224:227], v[4:7]
	v_mfma_f32_16x16x32_bf16 v[36:39], v[172:175], v[224:227], v[36:39]
	v_mfma_f32_16x16x32_bf16 v[28:31], v[96:99], v[204:207], v[28:31]
	v_mfma_f32_16x16x32_bf16 v[60:63], v[176:179], v[204:207], v[60:63]
	v_mfma_f32_16x16x32_bf16 v[20:23], v[96:99], v[212:215], v[20:23]
	v_mfma_f32_16x16x32_bf16 v[52:55], v[176:179], v[212:215], v[52:55]
	v_mfma_f32_16x16x32_bf16 v[12:15], v[96:99], v[220:223], v[12:15]
	v_mfma_f32_16x16x32_bf16 v[44:47], v[176:179], v[220:223], v[44:47]
	v_mfma_f32_16x16x32_bf16 v[4:7], v[96:99], v[228:231], v[4:7]
	v_mfma_f32_16x16x32_bf16 v[36:39], v[176:179], v[228:231], v[36:39]
	s_barrier
; #define PG8_STAGE(bufoff, gbase, voff) do { _Pragma("unroll") for (int _i = 0; _i < 2; ++_i) \
;         __builtin_amdgcn_global_load_lds((const unsigned*)((const char*)(gbase) + (voff)[_i]), (LAS unsigned*)(lds + (bufoff) + ldsw + _i * 8192), 16, 0, 0); } while (0)
; #define PG8_STAGE_A(bufoff, ptr, half, rev) do { if (REVA && (rev)) { const char* _p = (ptr) - ((half) ? hstepA : 0); PG8_STAGE(bufoff, _p, voffAr); } else { const char* _p = (ptr) + ((half) ? hstepA : 0); PG8_STAGE(bufoff, _p, voffA); } } while (0)
; #define PG8_LDA(dst, b, h) do { _Pragma("unroll") for (int m = 0; m < 4; ++m) _Pragma("unroll") for (int k = 0; k < 2; ++k) dst[m][k] = *(const LAS bf16x8*)(lds + PG8_SA(b, h) + aoff + m * 2048 + k * 1024); } while (0)
; #define PG8_LDB(dst, b, h) do { _Pragma("unroll") for (int n = 0; n < 2; ++n) _Pragma("unroll") for (int k = 0; k < 2; ++k) dst[n][k] = *(const LAS bf16x8*)(lds + PG8_SB(b, h) + boff + n * 2048 + k * 1024); } while (0)
; #define PG8_MMA(ai, bj, At, Bt) do { __builtin_amdgcn_s_setprio(1); _Pragma("unroll") for (int m = 0; m < 4; ++m) _Pragma("unroll") for (int n = 0; n < 2; ++n) _Pragma("unroll") for (int k = 0; k < 2; ++k) \
;         acc[ai][bj][m][n] = __builtin_amdgcn_mfma_f32_16x16x32_bf16(Bt[n][k], At[m][k], acc[ai][bj][m][n], 0, 0, 0); __builtin_amdgcn_s_setprio(0); } while (0)
; #define PG8_WAIT_V(n) asm volatile("s_waitcnt vmcnt(" #n ")" ::: "memory")
; #define PG8_WAIT_L(n) asm volatile("s_waitcnt lgkmcnt(" #n ")" ::: "memory")
; #define PG8_BAR __builtin_amdgcn_s_barrier()
; #define PG8_SCHED __builtin_amdgcn_sched_barrier(0)
;     ...
;             PG8_BAR; PG8_WAIT_L(0); PG8_MMA(1, 0, At, B0); PG8_BAR; PG8_SCHED;
;             PG8_STAGE(PG8_SB(0, 1), b2 + hb2, voffB);
;             PG8_WAIT_V(6); PG8_BAR; PG8_MMA(1, 1, At, B1); PG8_BAR;
;             PG8_LDB(B0, 1, 0); PG8_SCHED; PG8_LDA(At, 1, 0); PG8_STAGE_A(PG8_SA(0, 1), a2, 1, r2);
;             PG8_WAIT_L(8); PG8_BAR; PG8_WAIT_L(0); PG8_MMA(0, 0, At, B0); PG8_BAR; PG8_SCHED;
;             PG8_LDB(B1, 1, 1); PG8_STAGE(PG8_SB(1, 0), b3, voffB);
;             PG8_BAR; PG8_WAIT_L(0); PG8_MMA(0, 1, At, B1); PG8_BAR;
;             PG8_LDA(At, 1, 1); PG8_STAGE_A(PG8_SA(1, 0), a3, 0, r3);
;             PG8_BAR; PG8_WAIT_L(0); PG8_MMA(1, 0, At, B0); PG8_BAR; PG8_SCHED;
	s_add_u32 s10, s14, 0x80000
	s_addc_u32 s11, s15, 0
	s_add_i32 s27, s37, s90
	v_lshl_add_u64 v[92:93], s[10:11], 0, v[160:161]
	s_mov_b32 m0, s27
	s_nop 0
	global_load_lds_dwordx4 v[92:93], off
	v_lshl_add_u64 v[92:93], s[10:11], 0, v[140:141]
	s_add_i32 m0, s27, 0x2000
	s_nop 0
	global_load_lds_dwordx4 v[92:93], off
	v_add_u32_e32 v176, 0x18000, v156
	ds_read_b128 v[92:95], v176
	ds_read_b128 v[96:99], v176 offset:1024
	ds_read_b128 v[172:175], v176 offset:2048
	ds_read_b128 v[176:179], v176 offset:3072
	s_waitcnt vmcnt(10)
	s_barrier
	v_mfma_f32_16x16x32_bf16 v[56:59], v[232:235], v[180:183], v[56:59]
	v_mfma_f32_16x16x32_bf16 v[24:27], v[240:243], v[180:183], v[24:27]
	v_mfma_f32_16x16x32_bf16 v[48:51], v[232:235], v[208:211], v[48:51]
	v_mfma_f32_16x16x32_bf16 v[16:19], v[240:243], v[208:211], v[16:19]
	v_mfma_f32_16x16x32_bf16 v[40:43], v[232:235], v[216:219], v[40:43]
	v_mfma_f32_16x16x32_bf16 v[8:11], v[240:243], v[216:219], v[8:11]
	v_mfma_f32_16x16x32_bf16 v[32:35], v[232:235], v[224:227], v[32:35]
	v_mfma_f32_16x16x32_bf16 v[0:3], v[240:243], v[224:227], v[0:3]
	v_mfma_f32_16x16x32_bf16 v[56:59], v[236:239], v[204:207], v[56:59]
	v_mfma_f32_16x16x32_bf16 v[24:27], v[244:247], v[204:207], v[24:27]
	v_mfma_f32_16x16x32_bf16 v[48:51], v[236:239], v[212:215], v[48:51]
	v_mfma_f32_16x16x32_bf16 v[16:19], v[244:247], v[212:215], v[16:19]
	v_mfma_f32_16x16x32_bf16 v[40:43], v[236:239], v[220:223], v[40:43]
	v_mfma_f32_16x16x32_bf16 v[8:11], v[244:247], v[220:223], v[8:11]
	v_mfma_f32_16x16x32_bf16 v[32:35], v[236:239], v[228:231], v[32:35]
	v_mfma_f32_16x16x32_bf16 v[0:3], v[244:247], v[228:231], v[0:3]
	s_add_i32 s27, 0, 0x18000
	s_barrier
	s_add_u32 s10, s20, 0x80000
	s_addc_u32 s11, s21, 0
	s_mov_b32 m0, s93
	v_lshl_add_u64 v[190:191], s[10:11], 0, v[160:161]
	ds_read_b128 v[180:183], v171 offset:32768
	ds_read_b128 v[204:207], v171 offset:33792
	ds_read_b128 v[208:211], v171 offset:34816
	ds_read_b128 v[212:215], v171 offset:35840
	ds_read_b128 v[216:219], v171 offset:36864
	ds_read_b128 v[220:223], v171 offset:37888
	ds_read_b128 v[224:227], v171 offset:38912
	ds_read_b128 v[228:231], v171 offset:39936
	global_load_lds_dwordx4 v[190:191], off
	v_lshl_add_u64 v[190:191], s[10:11], 0, v[140:141]
	s_mov_b32 m0, s94
	s_nop 0
	global_load_lds_dwordx4 v[190:191], off
	s_waitcnt lgkmcnt(8)
	s_waitcnt vmcnt(10)
	s_barrier
	s_waitcnt lgkmcnt(0)
	v_mfma_f32_16x16x32_bf16 v[104:107], v[92:95], v[180:183], v[104:107]
	v_mfma_f32_16x16x32_bf16 v[136:139], v[172:175], v[180:183], v[136:139]
	v_mfma_f32_16x16x32_bf16 v[84:87], v[92:95], v[208:211], v[84:87]
	v_mfma_f32_16x16x32_bf16 v[128:131], v[172:175], v[208:211], v[128:131]
	v_mfma_f32_16x16x32_bf16 v[76:79], v[92:95], v[216:219], v[76:79]
	v_mfma_f32_16x16x32_bf16 v[120:123], v[172:175], v[216:219], v[120:123]
	v_mfma_f32_16x16x32_bf16 v[68:71], v[92:95], v[224:227], v[68:71]
	v_mfma_f32_16x16x32_bf16 v[112:115], v[172:175], v[224:227], v[112:115]
	v_mfma_f32_16x16x32_bf16 v[104:107], v[96:99], v[204:207], v[104:107]
	v_mfma_f32_16x16x32_bf16 v[136:139], v[176:179], v[204:207], v[136:139]
	v_mfma_f32_16x16x32_bf16 v[84:87], v[96:99], v[212:215], v[84:87]
	v_mfma_f32_16x16x32_bf16 v[128:131], v[176:179], v[212:215], v[128:131]
	v_mfma_f32_16x16x32_bf16 v[76:79], v[96:99], v[220:223], v[76:79]
	v_mfma_f32_16x16x32_bf16 v[120:123], v[176:179], v[220:223], v[120:123]
	v_mfma_f32_16x16x32_bf16 v[68:71], v[96:99], v[228:231], v[68:71]
	v_mfma_f32_16x16x32_bf16 v[112:115], v[176:179], v[228:231], v[112:115]
	s_barrier
	s_add_i32 s20, 0, 0x1c000
	s_add_i32 s10, s27, s90
	v_add_u32_e32 v190, s20, v156
	v_lshl_add_u64 v[154:155], v[154:155], 0, s[28:29]
	s_mov_b32 m0, s10
	ds_read_b128 v[232:235], v190
	ds_read_b128 v[236:239], v190 offset:1024
	ds_read_b128 v[240:243], v190 offset:2048
	ds_read_b128 v[244:247], v190 offset:3072
	global_load_lds_dwordx4 v[154:155], off
	v_lshl_add_u64 v[154:155], v[184:185], 0, s[28:29]
	s_add_i32 m0, s10, 0x2000
	s_nop 0
	global_load_lds_dwordx4 v[154:155], off
	s_waitcnt vmcnt(10)
	s_barrier
	s_waitcnt lgkmcnt(0)
	v_mfma_f32_16x16x32_bf16 v[132:135], v[232:235], v[180:183], v[132:135]
	v_mfma_f32_16x16x32_bf16 v[100:103], v[240:243], v[180:183], v[100:103]
	v_mfma_f32_16x16x32_bf16 v[124:127], v[232:235], v[208:211], v[124:127]
	v_mfma_f32_16x16x32_bf16 v[80:83], v[240:243], v[208:211], v[80:83]
	v_mfma_f32_16x16x32_bf16 v[116:119], v[232:235], v[216:219], v[116:119]
	v_mfma_f32_16x16x32_bf16 v[72:75], v[240:243], v[216:219], v[72:75]
	v_mfma_f32_16x16x32_bf16 v[108:111], v[232:235], v[224:227], v[108:111]
	v_mfma_f32_16x16x32_bf16 v[64:67], v[240:243], v[224:227], v[64:67]
	v_mfma_f32_16x16x32_bf16 v[132:135], v[236:239], v[204:207], v[132:135]
	v_mfma_f32_16x16x32_bf16 v[100:103], v[244:247], v[204:207], v[100:103]
	v_mfma_f32_16x16x32_bf16 v[124:127], v[236:239], v[212:215], v[124:127]
	v_mfma_f32_16x16x32_bf16 v[80:83], v[244:247], v[212:215], v[80:83]
	v_mfma_f32_16x16x32_bf16 v[116:119], v[236:239], v[220:223], v[116:119]
	v_mfma_f32_16x16x32_bf16 v[72:75], v[244:247], v[220:223], v[72:75]
	v_mfma_f32_16x16x32_bf16 v[108:111], v[236:239], v[228:231], v[108:111]
	v_mfma_f32_16x16x32_bf16 v[64:67], v[244:247], v[228:231], v[64:67]
	s_mov_b32 m0, s95
	v_lshl_add_u64 v[154:155], s[16:17], 0, v[160:161]
	s_barrier
	ds_read_b128 v[180:183], v171 offset:49152
	ds_read_b128 v[204:207], v171 offset:50176
	ds_read_b128 v[208:211], v171 offset:51200
	ds_read_b128 v[212:215], v171 offset:52224
	ds_read_b128 v[216:219], v171 offset:53248
	ds_read_b128 v[220:223], v171 offset:54272
	ds_read_b128 v[224:227], v171 offset:55296
	ds_read_b128 v[228:231], v171 offset:56320
	global_load_lds_dwordx4 v[154:155], off
	v_lshl_add_u64 v[154:155], s[16:17], 0, v[140:141]
	s_mov_b32 m0, s96
	s_nop 0
	global_load_lds_dwordx4 v[154:155], off
	s_waitcnt vmcnt(10)
	s_barrier
; #define PG8_STAGE(bufoff, gbase, voff) do { _Pragma("unroll") for (int _i = 0; _i < 2; ++_i) \
;         __builtin_amdgcn_global_load_lds((const unsigned*)((const char*)(gbase) + (voff)[_i]), (LAS unsigned*)(lds + (bufoff) + ldsw + _i * 8192), 16, 0, 0); } while (0)
; #define PG8_MMA(ai, bj, At, Bt) do { __builtin_amdgcn_s_setprio(1); _Pragma("unroll") for (int m = 0; m < 4; ++m) _Pragma("unroll") for (int n = 0; n < 2; ++n) _Pragma("unroll") for (int k = 0; k < 2; ++k) \
;         acc[ai][bj][m][n] = __builtin_amdgcn_mfma_f32_16x16x32_bf16(Bt[n][k], At[m][k], acc[ai][bj][m][n], 0, 0, 0); __builtin_amdgcn_s_setprio(0); } while (0)
; #define PG8_WAIT_V(n) asm volatile("s_waitcnt vmcnt(" #n ")" ::: "memory")
; #define PG8_WAIT_L(n) asm volatile("s_waitcnt lgkmcnt(" #n ")" ::: "memory")
; #define PG8_BAR __builtin_amdgcn_s_barrier()
; #define PG8_SCHED __builtin_amdgcn_sched_barrier(0)
;     ...
;             PG8_BAR; PG8_WAIT_L(0); PG8_MMA(1, 0, At, B0); PG8_BAR; PG8_SCHED;
;             PG8_STAGE(PG8_SB(1, 1), b3 + hb2, voffB);
;             PG8_WAIT_V(6); PG8_BAR; PG8_MMA(1, 1, At, B1); PG8_BAR;
;         }
;         E(acc, cur, wr, wc, fr, fq, lane);
;     __device__ __forceinline__ void operator()(const f32x4 (&acc)[2][2][4][2], const Unit& u, int wr, int wc, int fr, int fq, int lane) const {
;         const int ch = u.pn * 64 + wc * 16 + 4 * fq;
;         const f32x4 w0 = *(const f32x4*)(cw + ch), w1 = *(const f32x4*)(cw + 4096 + ch), w2 = *(const f32x4*)(cw + 8192 + ch);
; #pragma unroll
;         for (int ai = 0; ai < 2; ++ai) {
;             f32x4 z[4], up[4], dn[4];
; #pragma unroll
;             for (int m = 0; m < 4; ++m) {
;                 z[m] = acc[ai][0][m][1] * acc[ai][1][m][0];
; #pragma unroll
;                 for (int j = 0; j < 4; ++j) { up[m][j] = __int_as_float(__builtin_amdgcn_update_dpp(0, __float_as_int(z[m][j]), 0x121, 0xF, 0xF, false));
;                                               dn[m][j] = __int_as_float(__builtin_amdgcn_update_dpp(0, __float_as_int(z[m][j]), 0x12F, 0xF, 0xF, false)); }
;             }
	s_waitcnt lgkmcnt(0)
	v_mfma_f32_16x16x32_bf16 v[28:31], v[92:95], v[180:183], v[28:31]
	v_mfma_f32_16x16x32_bf16 v[60:63], v[172:175], v[180:183], v[60:63]
	v_mfma_f32_16x16x32_bf16 v[20:23], v[92:95], v[208:211], v[20:23]
	v_mfma_f32_16x16x32_bf16 v[52:55], v[172:175], v[208:211], v[52:55]
	v_mfma_f32_16x16x32_bf16 v[12:15], v[92:95], v[216:219], v[12:15]
	v_mfma_f32_16x16x32_bf16 v[44:47], v[172:175], v[216:219], v[44:47]
	v_mfma_f32_16x16x32_bf16 v[4:7], v[92:95], v[224:227], v[4:7]
	v_mfma_f32_16x16x32_bf16 v[36:39], v[172:175], v[224:227], v[36:39]
	v_mfma_f32_16x16x32_bf16 v[28:31], v[96:99], v[204:207], v[28:31]
	v_mfma_f32_16x16x32_bf16 v[60:63], v[176:179], v[204:207], v[60:63]
	v_mfma_f32_16x16x32_bf16 v[20:23], v[96:99], v[212:215], v[20:23]
	v_mfma_f32_16x16x32_bf16 v[52:55], v[176:179], v[212:215], v[52:55]
	v_mfma_f32_16x16x32_bf16 v[12:15], v[96:99], v[220:223], v[12:15]
	v_mfma_f32_16x16x32_bf16 v[44:47], v[176:179], v[220:223], v[44:47]
	v_mfma_f32_16x16x32_bf16 v[4:7], v[96:99], v[228:231], v[4:7]
	v_mfma_f32_16x16x32_bf16 v[36:39], v[176:179], v[228:231], v[36:39]
	s_barrier
	s_add_u32 s10, s14, 0x80080
	s_addc_u32 s11, s15, 0
	s_add_i32 s14, s20, s90
	v_lshl_add_u64 v[92:93], s[10:11], 0, v[160:161]
	s_mov_b32 m0, s14
	s_nop 0
	global_load_lds_dwordx4 v[92:93], off
	v_lshl_add_u64 v[92:93], s[10:11], 0, v[140:141]
	s_add_i32 m0, s14, 0x2000
	s_nop 0
	global_load_lds_dwordx4 v[92:93], off
	v_add_u32_e32 v154, 0x10000, v156
	ds_read_b128 v[92:95], v154
	ds_read_b128 v[96:99], v154 offset:1024
	ds_read_b128 v[172:175], v154 offset:2048
	ds_read_b128 v[176:179], v154 offset:3072
	s_waitcnt vmcnt(10)
	s_barrier
	v_mfma_f32_16x16x32_bf16 v[56:59], v[232:235], v[180:183], v[56:59]
	v_mfma_f32_16x16x32_bf16 v[24:27], v[240:243], v[180:183], v[24:27]
	v_mfma_f32_16x16x32_bf16 v[48:51], v[232:235], v[208:211], v[48:51]
	v_mfma_f32_16x16x32_bf16 v[16:19], v[240:243], v[208:211], v[16:19]
	v_mfma_f32_16x16x32_bf16 v[40:43], v[232:235], v[216:219], v[40:43]
	v_mfma_f32_16x16x32_bf16 v[8:11], v[240:243], v[216:219], v[8:11]
	v_mfma_f32_16x16x32_bf16 v[32:35], v[232:235], v[224:227], v[32:35]
	v_mfma_f32_16x16x32_bf16 v[0:3], v[240:243], v[224:227], v[0:3]
	v_mfma_f32_16x16x32_bf16 v[56:59], v[236:239], v[204:207], v[56:59]
	v_mfma_f32_16x16x32_bf16 v[24:27], v[244:247], v[204:207], v[24:27]
	v_mfma_f32_16x16x32_bf16 v[48:51], v[236:239], v[212:215], v[48:51]
	v_mfma_f32_16x16x32_bf16 v[16:19], v[244:247], v[212:215], v[16:19]
	v_mfma_f32_16x16x32_bf16 v[40:43], v[236:239], v[220:223], v[40:43]
	v_mfma_f32_16x16x32_bf16 v[8:11], v[244:247], v[220:223], v[8:11]
	v_mfma_f32_16x16x32_bf16 v[32:35], v[236:239], v[228:231], v[32:35]
	v_mfma_f32_16x16x32_bf16 v[0:3], v[244:247], v[228:231], v[0:3]
	s_add_i32 s9, s9, 2
	s_add_u32 vcc_lo, vcc_lo, 0x100
	s_addc_u32 vcc_hi, vcc_hi, 0
	s_cmp_gt_u32 s9, 29
	s_cbranch_scc0 .Lrot_234_bar
	s_barrier
	s_waitcnt lgkmcnt(0)
	s_nop 0
	v_lshl_or_b32 v154, s5, 6, v158
	v_ashrrev_i32_e32 v155, 31, v154
	v_lshlrev_b64 v[92:93], 2, v[154:155]
	v_lshl_add_u64 v[88:89], v[142:143], 0, v[92:93]
	v_lshl_add_u64 v[90:91], v[144:145], 0, v[92:93]
	global_load_dwordx4 v[96:99], v[88:89], off
	s_nop 0
	global_load_dwordx4 v[88:91], v[90:91], off
	v_lshl_add_u64 v[92:93], v[146:147], 0, v[92:93]
	global_load_dwordx4 v[92:95], v[92:93], off
	v_pk_mul_f32 v[134:135], v[138:139], v[134:135]
	v_mov_b32_e32 v172, v161
	v_mov_b32_e32 v174, v161
	v_mov_b32_e32 v173, v161
	v_mov_b32_dpp v172, v134 row_ror:1 row_mask:0xf bank_mask:0xf
	v_mov_b32_dpp v174, v135 row_ror:1 row_mask:0xf bank_mask:0xf
	v_mov_b32_e32 v175, v161
	v_pk_mul_f32 v[126:127], v[130:131], v[126:127]
	v_mov_b32_e32 v177, v161
	v_mov_b32_e32 v179, v161
	v_pk_mul_f32 v[116:117], v[120:121], v[116:117]
	v_cndmask_b32_e64 v120, v172, 0, s[42:43]
	v_cndmask_b32_e64 v121, v174, 0, s[42:43]
	v_mov_b32_dpp v173, v134 row_ror:15 row_mask:0xf bank_mask:0xf
	v_mov_b32_dpp v175, v135 row_ror:15 row_mask:0xf bank_mask:0xf
	v_mov_b32_dpp v177, v126 row_ror:15 row_mask:0xf bank_mask:0xf
	v_mov_b32_dpp v179, v127 row_ror:15 row_mask:0xf bank_mask:0xf
	v_pk_mul_f32 v[132:133], v[136:137], v[132:133]
	v_mov_b32_e32 v136, v161
	v_mov_b32_e32 v138, v161
	v_pk_mul_f32 v[118:119], v[122:123], v[118:119]
	v_cndmask_b32_e64 v122, v173, v177, s[44:45]
	v_cndmask_b32_e64 v123, v175, v179, s[44:45]
	v_mov_b32_dpp v136, v132 row_ror:1 row_mask:0xf bank_mask:0xf
	v_mov_b32_dpp v138, v133 row_ror:1 row_mask:0xf bank_mask:0xf
	v_mov_b32_e32 v137, v161
	v_mov_b32_e32 v139, v161
	v_pk_mul_f32 v[124:125], v[128:129], v[124:125]
	v_mov_b32_e32 v129, v161
	v_mov_b32_e32 v131, v161
	v_pk_mul_f32 v[108:109], v[112:113], v[108:109]
	v_cndmask_b32_e64 v112, v136, 0, s[42:43]
	v_cndmask_b32_e64 v113, v138, 0, s[42:43]
	v_mov_b32_dpp v137, v132 row_ror:15 row_mask:0xf bank_mask:0xf
	v_mov_b32_dpp v139, v133 row_ror:15 row_mask:0xf bank_mask:0xf
	v_mov_b32_dpp v129, v124 row_ror:15 row_mask:0xf bank_mask:0xf
	v_mov_b32_dpp v131, v125 row_ror:15 row_mask:0xf bank_mask:0xf
	v_pk_mul_f32 v[110:111], v[114:115], v[110:111]
	v_cndmask_b32_e64 v114, v137, v129, s[44:45]
	v_cndmask_b32_e64 v115, v139, v131, s[44:45]
	v_mov_b32_e32 v176, v161
	v_mov_b32_e32 v178, v161
	v_mov_b32_e32 v185, v161
	v_mov_b32_dpp v176, v126 row_ror:1 row_mask:0xf bank_mask:0xf
	v_mov_b32_dpp v178, v127 row_ror:1 row_mask:0xf bank_mask:0xf
	v_mov_b32_e32 v191, v161
	v_mov_b32_dpp v185, v118 row_ror:15 row_mask:0xf bank_mask:0xf
	v_mov_b32_e32 v128, v161
	v_mov_b32_dpp v191, v119 row_ror:15 row_mask:0xf bank_mask:0xf
	v_mov_b32_e32 v130, v161
	v_mov_b32_dpp v128, v124 row_ror:1 row_mask:0xf bank_mask:0xf
	v_mov_b32_e32 v181, v161
	v_mov_b32_dpp v130, v125 row_ror:1 row_mask:0xf bank_mask:0xf
	v_mov_b32_e32 v183, v161
	v_mov_b32_dpp v181, v116 row_ror:15 row_mask:0xf bank_mask:0xf
	v_mov_b32_e32 v184, v161
	v_mov_b32_dpp v183, v117 row_ror:15 row_mask:0xf bank_mask:0xf
	v_mov_b32_e32 v190, v161
	v_mov_b32_dpp v184, v118 row_ror:1 row_mask:0xf bank_mask:0xf
	v_mov_b32_e32 v209, v161
	v_mov_b32_dpp v190, v119 row_ror:1 row_mask:0xf bank_mask:0xf
	v_mov_b32_e32 v211, v161
	v_mov_b32_dpp v209, v110 row_ror:15 row_mask:0xf bank_mask:0xf
	v_mov_b32_e32 v180, v161
	v_mov_b32_dpp v211, v111 row_ror:15 row_mask:0xf bank_mask:0xf
	v_mov_b32_e32 v182, v161
	v_mov_b32_dpp v180, v116 row_ror:1 row_mask:0xf bank_mask:0xf
	v_mov_b32_e32 v205, v161
	v_mov_b32_dpp v182, v117 row_ror:1 row_mask:0xf bank_mask:0xf
	v_mov_b32_e32 v207, v161
	v_mov_b32_dpp v205, v108 row_ror:15 row_mask:0xf bank_mask:0xf
	v_mov_b32_e32 v208, v161
	v_mov_b32_dpp v207, v109 row_ror:15 row_mask:0xf bank_mask:0xf
	v_mov_b32_e32 v210, v161
	v_mov_b32_dpp v208, v110 row_ror:1 row_mask:0xf bank_mask:0xf
	v_mov_b32_e32 v204, v161
	s_waitcnt vmcnt(0)
; __device__ __forceinline__ unsigned cvt_pk_bf16(float lo, float hi) { unsigned r; asm volatile("v_cvt_pk_bf16_f32 %0, %1, %2" : "=v"(r) : "v"(lo), "v"(hi)); return r; }
; __device__ __forceinline__ float silu_f(float x) { return x * __builtin_amdgcn_rcpf(1.f + __expf(-x)); }
;     __device__ __forceinline__ void operator()(const f32x4 (&acc)[2][2][4][2], const Unit& u, int wr, int wc, int fr, int fq, int lane) const {
;     ...
;             for (int m = 0; m < 4; ++m) {
;                 f32x4 zp, zn;
; #pragma unroll
;                 for (int j = 0; j < 4; ++j) {
;                     zp[j] = (fr > 0) ? up[m][j] : (m > 0 ? up[m > 0 ? m - 1 : 0][j] : 0.f);
;                     zn[j] = (fr < 15) ? dn[m][j] : (m < 3 ? dn[m < 3 ? m + 1 : 3][j] : 0.f);
;                 }
;                 f32x4 y = w0 * zp + w1 * z[m] + w2 * zn;
;                 const f32x4 bg = acc[ai][0][m][0], g = acc[ai][1][m][1];
; #pragma unroll
;                 for (int j = 0; j < 4; ++j) y[j] = y[j] * bg[j] * silu_f(g[j]);
;                 wv[m].x = cvt_pk_bf16(y[0], y[1]); wv[m].y = cvt_pk_bf16(y[2], y[3]);
;             }
;             if (u.pm < 128) {
	v_pk_mul_f32 v[120:121], v[98:99], v[120:121]
	v_pk_mul_f32 v[112:113], v[96:97], v[112:113]
	v_pk_fma_f32 v[120:121], v[134:135], v[90:91], v[120:121]
	v_mul_f32_e32 v134, 0xbfb8aa3b, v100
	v_exp_f32_e32 v134, v134
	v_pk_fma_f32 v[120:121], v[94:95], v[122:123], v[120:121]
	v_mov_b32_e32 v122, v100
	v_mul_f32_e32 v100, 0xbfb8aa3b, v101
	v_exp_f32_e32 v100, v100
	v_pk_fma_f32 v[112:113], v[132:133], v[88:89], v[112:113]
	v_mov_b32_e32 v123, v104
	v_pk_fma_f32 v[112:113], v[92:93], v[114:115], v[112:113]
	v_add_f32_e32 v114, 1.0, v134
	v_rcp_f32_e32 v114, v114
	v_add_f32_e32 v100, 1.0, v100
	v_mov_b32_e32 v115, v112
	v_rcp_f32_e32 v112, v100
	v_pk_mul_f32 v[114:115], v[122:123], v[114:115]
	v_mul_f32_e32 v100, 0xbfb8aa3b, v102
	v_mov_b32_e32 v104, v101
	v_mul_f32_e32 v114, v114, v115
	v_exp_f32_e32 v115, v100
	v_pk_mul_f32 v[100:101], v[104:105], v[112:113]
	v_mov_b32_e32 v104, v102
	v_mul_f32_e32 v112, v100, v101
	v_mul_f32_e32 v101, 0xbfb8aa3b, v103
	v_exp_f32_e32 v113, v101
	v_add_f32_e32 v100, 1.0, v115
	v_rcp_f32_e32 v100, v100
	v_mov_b32_e32 v101, v120
	v_add_f32_e32 v102, 1.0, v113
	v_rcp_f32_e32 v120, v102
	v_mov_b32_e32 v105, v106
	v_pk_mul_f32 v[100:101], v[104:105], v[100:101]
	v_mov_b32_e32 v106, v103
	v_mul_f32_e32 v102, v100, v101
	v_pk_mul_f32 v[100:101], v[106:107], v[120:121]
	v_cndmask_b32_e64 v106, v176, v172, s[42:43]
	v_cndmask_b32_e64 v107, v178, v174, s[42:43]
	v_pk_mul_f32 v[106:107], v[98:99], v[106:107]
	v_mul_f32_e32 v101, v100, v101
	v_cvt_pk_bf16_f32 v100, v114, v112
	v_cndmask_b32_e64 v112, v177, v185, s[44:45]
	v_cndmask_b32_e64 v113, v179, v191, s[44:45]
	v_pk_fma_f32 v[106:107], v[126:127], v[90:91], v[106:107]
	v_mul_f32_e32 v114, 0xbfb8aa3b, v80
	v_exp_f32_e32 v114, v114
	v_pk_fma_f32 v[106:107], v[94:95], v[112:113], v[106:107]
	v_mov_b32_e32 v112, v80
	v_mul_f32_e32 v80, 0xbfb8aa3b, v81
	v_cvt_pk_bf16_f32 v101, v102, v101
	v_cndmask_b32_e64 v102, v128, v136, s[42:43]
	v_cndmask_b32_e64 v103, v130, v138, s[42:43]
	v_exp_f32_e32 v80, v80
	v_pk_mul_f32 v[102:103], v[96:97], v[102:103]
	v_cndmask_b32_e64 v104, v129, v181, s[44:45]
	v_cndmask_b32_e64 v105, v131, v183, s[44:45]
	v_pk_fma_f32 v[102:103], v[124:125], v[88:89], v[102:103]
	v_add_f32_e32 v80, 1.0, v80
	v_pk_fma_f32 v[102:103], v[92:93], v[104:105], v[102:103]
	v_add_f32_e32 v104, 1.0, v114
	v_rcp_f32_e32 v104, v104
	v_mov_b32_e32 v105, v102
	v_rcp_f32_e32 v102, v80
	v_mov_b32_e32 v113, v84
	v_pk_mul_f32 v[104:105], v[112:113], v[104:105]
	v_mul_f32_e32 v80, 0xbfb8aa3b, v82
	v_mov_b32_e32 v84, v81
	v_mul_f32_e32 v104, v104, v105
	v_exp_f32_e32 v105, v80
	v_pk_mul_f32 v[80:81], v[84:85], v[102:103]
	v_mov_b32_e32 v84, v82
	v_mul_f32_e32 v102, v80, v81
	v_mul_f32_e32 v81, 0xbfb8aa3b, v83
	v_exp_f32_e32 v103, v81
	v_add_f32_e32 v80, 1.0, v105
	v_rcp_f32_e32 v80, v80
	v_mov_b32_e32 v81, v106
	v_add_f32_e32 v82, 1.0, v103
	v_rcp_f32_e32 v106, v82
	v_mov_b32_e32 v85, v86
	v_pk_mul_f32 v[80:81], v[84:85], v[80:81]
	v_mov_b32_e32 v86, v83
	v_mul_f32_e32 v82, v80, v81
	v_pk_mul_f32 v[80:81], v[86:87], v[106:107]
	v_cndmask_b32_e64 v86, v184, v176, s[42:43]
	v_cndmask_b32_e64 v87, v190, v178, s[42:43]
	v_pk_mul_f32 v[86:87], v[98:99], v[86:87]
	v_mul_f32_e32 v81, v80, v81
	v_cvt_pk_bf16_f32 v80, v104, v102
	v_cndmask_b32_e64 v102, v185, v209, s[44:45]
	v_cndmask_b32_e64 v103, v191, v211, s[44:45]
	v_pk_fma_f32 v[86:87], v[118:119], v[90:91], v[86:87]
	v_mul_f32_e32 v104, 0xbfb8aa3b, v72
	v_exp_f32_e32 v104, v104
	v_pk_fma_f32 v[86:87], v[94:95], v[102:103], v[86:87]
	v_mov_b32_e32 v102, v72
	v_mul_f32_e32 v72, 0xbfb8aa3b, v73
	v_cvt_pk_bf16_f32 v81, v82, v81
	v_cndmask_b32_e64 v82, v180, v128, s[42:43]
	v_cndmask_b32_e64 v83, v182, v130, s[42:43]
	v_exp_f32_e32 v72, v72
	v_pk_mul_f32 v[82:83], v[96:97], v[82:83]
	v_cndmask_b32_e64 v84, v181, v205, s[44:45]
	v_cndmask_b32_e64 v85, v183, v207, s[44:45]
	v_pk_fma_f32 v[82:83], v[116:117], v[88:89], v[82:83]
	v_add_f32_e32 v72, 1.0, v72
	v_pk_fma_f32 v[82:83], v[92:93], v[84:85], v[82:83]
	v_add_f32_e32 v84, 1.0, v104
	v_rcp_f32_e32 v84, v84
	v_mov_b32_e32 v85, v82
	v_rcp_f32_e32 v82, v72
	v_mov_b32_e32 v103, v76
	v_pk_mul_f32 v[84:85], v[102:103], v[84:85]
	v_mul_f32_e32 v72, 0xbfb8aa3b, v74
	v_mov_b32_e32 v76, v73
	v_mul_f32_e32 v84, v84, v85
	v_exp_f32_e32 v85, v72
	v_pk_mul_f32 v[72:73], v[76:77], v[82:83]
	v_mov_b32_e32 v76, v74
	v_mul_f32_e32 v82, v72, v73
	v_mul_f32_e32 v73, 0xbfb8aa3b, v75
	v_exp_f32_e32 v83, v73
	v_add_f32_e32 v72, 1.0, v85
	v_rcp_f32_e32 v72, v72
	v_mov_b32_e32 v73, v86
	v_add_f32_e32 v74, 1.0, v83
	v_rcp_f32_e32 v86, v74
	v_mov_b32_e32 v77, v78
	v_mov_b32_dpp v210, v111 row_ror:1 row_mask:0xf bank_mask:0xf
	v_pk_mul_f32 v[72:73], v[76:77], v[72:73]
	v_mov_b32_e32 v78, v75
	v_mul_f32_e32 v74, v72, v73
	v_pk_mul_f32 v[72:73], v[78:79], v[86:87]
	v_cndmask_b32_e64 v78, v208, v184, s[42:43]
	v_cndmask_b32_e64 v79, v210, v190, s[42:43]
	v_pk_mul_f32 v[78:79], v[98:99], v[78:79]
	v_mov_b32_e32 v206, v161
	v_mul_f32_e32 v73, v72, v73
	v_cvt_pk_bf16_f32 v72, v84, v82
	v_cndmask_b32_e64 v82, v209, 0, s[44:45]
	v_cndmask_b32_e64 v83, v211, 0, s[44:45]
	v_pk_fma_f32 v[78:79], v[110:111], v[90:91], v[78:79]
	v_mul_f32_e32 v84, 0xbfb8aa3b, v64
	v_mov_b32_dpp v204, v108 row_ror:1 row_mask:0xf bank_mask:0xf
	v_mov_b32_dpp v206, v109 row_ror:1 row_mask:0xf bank_mask:0xf
	v_exp_f32_e32 v84, v84
	v_pk_fma_f32 v[78:79], v[94:95], v[82:83], v[78:79]
	v_mov_b32_e32 v82, v64
	v_mul_f32_e32 v64, 0xbfb8aa3b, v65
	v_cvt_pk_bf16_f32 v73, v74, v73
	v_cndmask_b32_e64 v74, v204, v180, s[42:43]
	v_cndmask_b32_e64 v75, v206, v182, s[42:43]
	v_exp_f32_e32 v64, v64
	v_pk_mul_f32 v[74:75], v[96:97], v[74:75]
	v_cndmask_b32_e64 v76, v205, 0, s[44:45]
	v_cndmask_b32_e64 v77, v207, 0, s[44:45]
	v_pk_fma_f32 v[74:75], v[108:109], v[88:89], v[74:75]
	v_add_f32_e32 v64, 1.0, v64
	v_pk_fma_f32 v[74:75], v[92:93], v[76:77], v[74:75]
	v_add_f32_e32 v76, 1.0, v84
	v_rcp_f32_e32 v76, v76
	v_mov_b32_e32 v77, v74
	v_rcp_f32_e32 v74, v64
	v_mov_b32_e32 v83, v68
	v_pk_mul_f32 v[76:77], v[82:83], v[76:77]
	v_mul_f32_e32 v64, 0xbfb8aa3b, v66
	v_mov_b32_e32 v68, v65
	v_mul_f32_e32 v76, v76, v77
	v_exp_f32_e32 v77, v64
	v_pk_mul_f32 v[64:65], v[68:69], v[74:75]
	v_mov_b32_e32 v68, v66
	v_mul_f32_e32 v74, v64, v65
	v_mul_f32_e32 v65, 0xbfb8aa3b, v67
	v_exp_f32_e32 v75, v65
	v_add_f32_e32 v64, 1.0, v77
	v_rcp_f32_e32 v64, v64
	v_mov_b32_e32 v65, v78
	v_add_f32_e32 v66, 1.0, v75
	v_rcp_f32_e32 v78, v66
	s_cmpk_gt_i32 s36, 0x7f
	v_mov_b32_e32 v69, v70
	s_cselect_b64 s[38:39], -1, 0
	s_lshl_b32 s3, s36, 2
	v_pk_mul_f32 v[64:65], v[68:69], v[64:65]
	v_mov_b32_e32 v70, v67
	s_add_i32 s3, s4, s3
	v_mul_f32_e32 v68, v64, v65
	v_pk_mul_f32 v[64:65], v[70:71], v[78:79]
	s_and_b64 vcc, exec, s[38:39]
	v_mul_f32_e32 v64, v64, v65
	v_cvt_pk_bf16_f32 v66, v76, v74
	v_cvt_pk_bf16_f32 v67, v68, v64
	s_cbranch_vccz .LBB0_241
;     __device__ __forceinline__ void operator()(const f32x4 (&acc)[2][2][4][2], const Unit& u, int wr, int wc, int fr, int fq, int lane) const {
;     ...
;                 const int gidx = (u.pm - 128) * 4 + ai * 2 + wr, b = gidx / 5, g5 = gidx - b * 5, t0 = 62 * g5 - 1;
;                 bf16_t* p = O + ((size_t)(TL + b * 256 + t0 + fr)) * 4096 + ch;
; #pragma unroll
;                 for (int m = 0; m < 4; ++m) { const int i2 = m * 16 + fr; if (i2 >= 1 && i2 <= 62 && t0 + i2 < 256) *(u32x2*)(p + (size_t)(m * 16) * 4096) = wv[m]; }
	s_mul_hi_i32 s5, s3, 0x66666667
	s_lshr_b32 s6, s5, 31
	s_ashr_i32 s5, s5, 1
	s_add_i32 s6, s5, s6
	s_mul_i32 s5, s6, -5
	s_add_i32 s5, s5, s3
	s_mul_i32 s5, s5, 62
	s_lshl_b32 s6, s6, 8
	s_add_i32 s6, s5, s6
	v_add_u32_e32 v64, s6, v170
	v_ashrrev_i32_e32 v65, 31, v64
	v_lshlrev_b64 v[68:69], 13, v[64:65]
	v_lshl_add_u64 v[64:65], s[24:25], 0, v[68:69]
	v_cmp_le_i32_e32 vcc, s5, v157
	v_lshl_add_u64 v[64:65], v[154:155], 1, v[64:65]
	s_and_b64 s[6:7], s[46:47], vcc
	s_and_saveexec_b64 s[14:15], s[6:7]
	s_cbranch_execnz .LBB0_256
	s_or_b64 exec, exec, s[14:15]
	v_cmp_le_i32_e32 vcc, s5, v159
	s_and_saveexec_b64 s[14:15], vcc
	s_cbranch_execnz .LBB0_257

; #define PG8_STAGE_A(bufoff, ptr, half, rev) do { if (REVA && (rev)) { const char* _p = (ptr) - ((half) ? hstepA : 0); PG8_STAGE(bufoff, _p, voffAr); } else { const char* _p = (ptr) + ((half) ? hstepA : 0); PG8_STAGE(bufoff, _p, voffA); } } while (0)
; #define PG8_LDA(dst, b, h) do { _Pragma("unroll") for (int m = 0; m < 4; ++m) _Pragma("unroll") for (int k = 0; k < 2; ++k) dst[m][k] = *(const LAS bf16x8*)(lds + PG8_SA(b, h) + aoff + m * 2048 + k * 1024); } while (0)
; #define PG8_LDB(dst, b, h) do { _Pragma("unroll") for (int n = 0; n < 2; ++n) _Pragma("unroll") for (int k = 0; k < 2; ++k) dst[n][k] = *(const LAS bf16x8*)(lds + PG8_SB(b, h) + boff + n * 2048 + k * 1024); } while (0)
; #define PG8_SCHED __builtin_amdgcn_sched_barrier(0)
;     ...
;             PG8_LDB(B0, 0, 0); PG8_SCHED; PG8_LDA(At, 0, 0); PG8_STAGE_A(PG8_SA(1, 1), a1, 1, r1);
;     ...
;         for (int a = 0; a < 2; ++a)
; #pragma unroll
;             for (int b = 0; b < 2; ++b)
; #pragma unroll
;                 for (int m = 0; m < 4; ++m)
; #pragma unroll
;                     for (int n = 0; n < 2; ++n) acc[a][b][m][n] = (f32x4){0.f, 0.f, 0.f, 0.f};
;         cur = nxt; cA = nA; cB = nB; cAr = nAr; cHb = nHb; ++ui;
.LBB0_334:
	s_add_u32 s3, s36, 0x80
	s_addc_u32 s9, s37, 0
	s_add_u32 s10, s44, 0x100080
	s_addc_u32 s11, s45, 0
	s_add_u32 s27, s20, 0x100
	v_mov_b32_e32 v0, 0
	v_lshl_add_u64 v[128:129], s[10:11], 0, v[150:151]
	v_lshl_add_u64 v[130:131], s[10:11], 0, v[152:153]
	s_addc_u32 s91, s21, 0
	s_mov_b32 s92, -2
	s_mov_b64 s[46:47], 0
	v_mov_b32_e32 v1, v0
	v_pk_mov_b32 v[2:3], v[0:1], v[0:1]
	v_pk_mov_b32 v[4:5], v[0:1], v[0:1]
	v_pk_mov_b32 v[6:7], v[0:1], v[0:1]
	v_pk_mov_b32 v[8:9], v[0:1], v[0:1]
	v_pk_mov_b32 v[10:11], v[0:1], v[0:1]
	v_pk_mov_b32 v[12:13], v[0:1], v[0:1]
	v_pk_mov_b32 v[14:15], v[0:1], v[0:1]
	v_pk_mov_b32 v[16:17], v[0:1], v[0:1]
	v_pk_mov_b32 v[18:19], v[0:1], v[0:1]
	v_pk_mov_b32 v[20:21], v[0:1], v[0:1]
	v_pk_mov_b32 v[22:23], v[0:1], v[0:1]
	v_pk_mov_b32 v[24:25], v[0:1], v[0:1]
	v_pk_mov_b32 v[26:27], v[0:1], v[0:1]
	v_pk_mov_b32 v[28:29], v[0:1], v[0:1]
	v_pk_mov_b32 v[30:31], v[0:1], v[0:1]
	v_pk_mov_b32 v[32:33], v[0:1], v[0:1]
	v_pk_mov_b32 v[34:35], v[0:1], v[0:1]
	v_pk_mov_b32 v[36:37], v[0:1], v[0:1]
	v_pk_mov_b32 v[38:39], v[0:1], v[0:1]
	v_pk_mov_b32 v[40:41], v[0:1], v[0:1]
	v_pk_mov_b32 v[42:43], v[0:1], v[0:1]
	v_pk_mov_b32 v[44:45], v[0:1], v[0:1]
	v_pk_mov_b32 v[46:47], v[0:1], v[0:1]
	v_pk_mov_b32 v[48:49], v[0:1], v[0:1]
	v_pk_mov_b32 v[50:51], v[0:1], v[0:1]
	v_pk_mov_b32 v[52:53], v[0:1], v[0:1]
	v_pk_mov_b32 v[54:55], v[0:1], v[0:1]
	v_pk_mov_b32 v[56:57], v[0:1], v[0:1]
	v_pk_mov_b32 v[58:59], v[0:1], v[0:1]
	v_pk_mov_b32 v[60:61], v[0:1], v[0:1]
	v_pk_mov_b32 v[62:63], v[0:1], v[0:1]
	v_pk_mov_b32 v[64:65], v[0:1], v[0:1]
	v_pk_mov_b32 v[66:67], v[0:1], v[0:1]
	v_pk_mov_b32 v[68:69], v[0:1], v[0:1]
	v_pk_mov_b32 v[70:71], v[0:1], v[0:1]
	v_pk_mov_b32 v[72:73], v[0:1], v[0:1]
	v_pk_mov_b32 v[74:75], v[0:1], v[0:1]
	v_pk_mov_b32 v[76:77], v[0:1], v[0:1]
	v_pk_mov_b32 v[78:79], v[0:1], v[0:1]
	v_pk_mov_b32 v[80:81], v[0:1], v[0:1]
	v_pk_mov_b32 v[82:83], v[0:1], v[0:1]
	v_pk_mov_b32 v[84:85], v[0:1], v[0:1]
	v_pk_mov_b32 v[86:87], v[0:1], v[0:1]
	v_pk_mov_b32 v[88:89], v[0:1], v[0:1]
	v_pk_mov_b32 v[90:91], v[0:1], v[0:1]
	v_pk_mov_b32 v[92:93], v[0:1], v[0:1]
	v_pk_mov_b32 v[94:95], v[0:1], v[0:1]
	v_pk_mov_b32 v[96:97], v[0:1], v[0:1]
	v_pk_mov_b32 v[98:99], v[0:1], v[0:1]
	v_pk_mov_b32 v[100:101], v[0:1], v[0:1]
	v_pk_mov_b32 v[102:103], v[0:1], v[0:1]
	v_pk_mov_b32 v[104:105], v[0:1], v[0:1]
	v_pk_mov_b32 v[106:107], v[0:1], v[0:1]
	v_pk_mov_b32 v[108:109], v[0:1], v[0:1]
	v_pk_mov_b32 v[110:111], v[0:1], v[0:1]
	v_pk_mov_b32 v[112:113], v[0:1], v[0:1]
	v_pk_mov_b32 v[114:115], v[0:1], v[0:1]
	v_pk_mov_b32 v[116:117], v[0:1], v[0:1]
	v_pk_mov_b32 v[118:119], v[0:1], v[0:1]
	v_pk_mov_b32 v[120:121], v[0:1], v[0:1]
	v_pk_mov_b32 v[122:123], v[0:1], v[0:1]
	v_pk_mov_b32 v[124:125], v[0:1], v[0:1]
	v_pk_mov_b32 v[126:127], v[0:1], v[0:1]
	v_add_u32_e32 v154, 0x10000, v157
	ds_read_b128 v[132:135], v154
	ds_read_b128 v[136:139], v154 offset:1024
	ds_read_b128 v[140:143], v154 offset:2048
	ds_read_b128 v[168:171], v154 offset:3072
	s_branch .LBB0_335

; #define PG8_STAGE(bufoff, gbase, voff) do { _Pragma("unroll") for (int _i = 0; _i < 2; ++_i) \
;         __builtin_amdgcn_global_load_lds((const unsigned*)((const char*)(gbase) + (voff)[_i]), (LAS unsigned*)(lds + (bufoff) + ldsw + _i * 8192), 16, 0, 0); } while (0)
; #define PG8_STAGE_A(bufoff, ptr, half, rev) do { if (REVA && (rev)) { const char* _p = (ptr) - ((half) ? hstepA : 0); PG8_STAGE(bufoff, _p, voffAr); } else { const char* _p = (ptr) + ((half) ? hstepA : 0); PG8_STAGE(bufoff, _p, voffA); } } while (0)
; #define PG8_LDA(dst, b, h) do { _Pragma("unroll") for (int m = 0; m < 4; ++m) _Pragma("unroll") for (int k = 0; k < 2; ++k) dst[m][k] = *(const LAS bf16x8*)(lds + PG8_SA(b, h) + aoff + m * 2048 + k * 1024); } while (0)
; #define PG8_LDB(dst, b, h) do { _Pragma("unroll") for (int n = 0; n < 2; ++n) _Pragma("unroll") for (int k = 0; k < 2; ++k) dst[n][k] = *(const LAS bf16x8*)(lds + PG8_SB(b, h) + boff + n * 2048 + k * 1024); } while (0)
; #define PG8_MMA(ai, bj, At, Bt) do { __builtin_amdgcn_s_setprio(1); _Pragma("unroll") for (int m = 0; m < 4; ++m) _Pragma("unroll") for (int n = 0; n < 2; ++n) _Pragma("unroll") for (int k = 0; k < 2; ++k) \
;         acc[ai][bj][m][n] = __builtin_amdgcn_mfma_f32_16x16x32_bf16(Bt[n][k], At[m][k], acc[ai][bj][m][n], 0, 0, 0); __builtin_amdgcn_s_setprio(0); } while (0)
; #define PG8_WAIT_V(n) asm volatile("s_waitcnt vmcnt(" #n ")" ::: "memory")
; #define PG8_WAIT_L(n) asm volatile("s_waitcnt lgkmcnt(" #n ")" ::: "memory")
; #define PG8_BAR __builtin_amdgcn_s_barrier()
; #define PG8_SCHED __builtin_amdgcn_sched_barrier(0)
;     ...
;             PG8_LDB(B0, 0, 0); PG8_SCHED; PG8_LDA(At, 0, 0); PG8_STAGE_A(PG8_SA(1, 1), a1, 1, r1);
;             PG8_WAIT_L(8); PG8_BAR; PG8_WAIT_L(0); PG8_MMA(0, 0, At, B0); PG8_BAR; PG8_SCHED;
;             PG8_LDB(B1, 0, 1); PG8_STAGE(PG8_SB(0, 0), b2, voffB);
;             PG8_BAR; PG8_WAIT_L(0); PG8_MMA(0, 1, At, B1); PG8_BAR;
;             PG8_LDA(At, 0, 1); PG8_STAGE_A(PG8_SA(0, 0), a2, 0, r2);
;             PG8_BAR; PG8_WAIT_L(0); PG8_MMA(1, 0, At, B0); PG8_BAR; PG8_SCHED;
;             PG8_STAGE(PG8_SB(0, 1), b2 + hb2, voffB);
;             PG8_WAIT_V(6); PG8_BAR; PG8_MMA(1, 1, At, B1); PG8_BAR;
.LBB0_335:
	s_add_u32 s10, s44, s46
	s_addc_u32 s11, s45, s47
	s_add_u32 s16, s10, 0x100
	s_addc_u32 s17, s11, 0
	s_add_u32 s10, s10, 0x180
	s_addc_u32 s11, s11, 0
	s_add_u32 s14, s27, s46
	s_addc_u32 s15, s91, s47
	s_add_i32 s93, 0, 0x10000
	s_cmpk_eq_i32 s46, 0x1f00
	s_cselect_b32 s15, s39, s15
	s_cselect_b32 s14, s38, s14
	s_cselect_b32 s21, s37, s17
	s_cselect_b32 s20, s36, s16
	s_cselect_b32 s17, s9, s11
	s_cselect_b32 s16, s3, s10
	v_lshl_add_u64 v[154:155], v[128:129], 0, s[46:47]
	s_add_i32 m0, s1, 0xc000
	ds_read_b128 v[172:175], v158
	ds_read_b128 v[176:179], v158 offset:1024
	ds_read_b128 v[180:183], v158 offset:2048
	ds_read_b128 v[204:207], v158 offset:3072
	ds_read_b128 v[208:211], v158 offset:4096
	ds_read_b128 v[212:215], v158 offset:5120
	ds_read_b128 v[216:219], v158 offset:6144
	ds_read_b128 v[220:223], v158 offset:7168
	global_load_lds_dwordx4 v[154:155], off
	v_lshl_add_u64 v[154:155], v[130:131], 0, s[46:47]
	s_add_i32 m0, s1, 0xe000
	s_nop 0
	global_load_lds_dwordx4 v[154:155], off
	s_waitcnt lgkmcnt(8)
	s_waitcnt vmcnt(10)
	s_barrier
	s_waitcnt lgkmcnt(0)
	v_mfma_f32_16x16x32_bf16 v[124:127], v[132:135], v[172:175], v[124:127]
	v_mfma_f32_16x16x32_bf16 v[120:123], v[140:143], v[172:175], v[120:123]
	v_mfma_f32_16x16x32_bf16 v[116:119], v[132:135], v[180:183], v[116:119]
	v_mfma_f32_16x16x32_bf16 v[108:111], v[140:143], v[180:183], v[108:111]
	v_mfma_f32_16x16x32_bf16 v[92:95], v[132:135], v[208:211], v[92:95]
	v_mfma_f32_16x16x32_bf16 v[88:91], v[140:143], v[208:211], v[88:91]
	v_mfma_f32_16x16x32_bf16 v[84:87], v[132:135], v[216:219], v[84:87]
	v_mfma_f32_16x16x32_bf16 v[76:79], v[140:143], v[216:219], v[76:79]
	v_mfma_f32_16x16x32_bf16 v[124:127], v[136:139], v[176:179], v[124:127]
	v_mfma_f32_16x16x32_bf16 v[120:123], v[168:171], v[176:179], v[120:123]
	v_mfma_f32_16x16x32_bf16 v[116:119], v[136:139], v[204:207], v[116:119]
	v_mfma_f32_16x16x32_bf16 v[108:111], v[168:171], v[204:207], v[108:111]
	v_mfma_f32_16x16x32_bf16 v[92:95], v[136:139], v[212:215], v[92:95]
	v_mfma_f32_16x16x32_bf16 v[88:91], v[168:171], v[212:215], v[88:91]
	v_mfma_f32_16x16x32_bf16 v[84:87], v[136:139], v[220:223], v[84:87]
	v_mfma_f32_16x16x32_bf16 v[76:79], v[168:171], v[220:223], v[76:79]
	s_barrier
	s_add_i32 s94, 0, 0x14000
	v_add_u32_e32 v154, s94, v157
	s_add_i32 s10, s93, s52
	ds_read_b128 v[224:227], v154
	ds_read_b128 v[228:231], v154 offset:1024
	ds_read_b128 v[232:235], v154 offset:2048
	ds_read_b128 v[236:239], v154 offset:3072
	v_lshl_add_u64 v[154:155], s[14:15], 0, v[146:147]
	s_mov_b32 m0, s10
	v_lshl_add_u64 v[184:185], s[14:15], 0, v[144:145]
	global_load_lds_dwordx4 v[154:155], off
	s_add_i32 m0, s10, 0x2000
	s_nop 0
	global_load_lds_dwordx4 v[184:185], off
	s_waitcnt vmcnt(10)
	s_barrier
	s_waitcnt lgkmcnt(0)
	v_mfma_f32_16x16x32_bf16 v[112:115], v[224:227], v[172:175], v[112:115]
	v_mfma_f32_16x16x32_bf16 v[104:107], v[232:235], v[172:175], v[104:107]
	v_mfma_f32_16x16x32_bf16 v[100:103], v[224:227], v[180:183], v[100:103]
	v_mfma_f32_16x16x32_bf16 v[96:99], v[232:235], v[180:183], v[96:99]
	v_mfma_f32_16x16x32_bf16 v[80:83], v[224:227], v[208:211], v[80:83]
	v_mfma_f32_16x16x32_bf16 v[72:75], v[232:235], v[208:211], v[72:75]
	v_mfma_f32_16x16x32_bf16 v[68:71], v[224:227], v[216:219], v[68:71]
	v_mfma_f32_16x16x32_bf16 v[64:67], v[232:235], v[216:219], v[64:67]
	v_mfma_f32_16x16x32_bf16 v[112:115], v[228:231], v[176:179], v[112:115]
	v_mfma_f32_16x16x32_bf16 v[104:107], v[236:239], v[176:179], v[104:107]
	v_mfma_f32_16x16x32_bf16 v[100:103], v[228:231], v[204:207], v[100:103]
	v_mfma_f32_16x16x32_bf16 v[96:99], v[236:239], v[204:207], v[96:99]
	v_mfma_f32_16x16x32_bf16 v[80:83], v[228:231], v[212:215], v[80:83]
	v_mfma_f32_16x16x32_bf16 v[72:75], v[236:239], v[212:215], v[72:75]
	v_mfma_f32_16x16x32_bf16 v[68:71], v[228:231], v[220:223], v[68:71]
	v_mfma_f32_16x16x32_bf16 v[64:67], v[236:239], v[220:223], v[64:67]
	s_mov_b32 m0, s1
	v_lshl_add_u64 v[190:191], s[20:21], 0, v[146:147]
	s_barrier
	ds_read_b128 v[172:175], v158 offset:16384
	ds_read_b128 v[176:179], v158 offset:17408
	ds_read_b128 v[180:183], v158 offset:18432
	ds_read_b128 v[204:207], v158 offset:19456
	ds_read_b128 v[208:211], v158 offset:20480
	ds_read_b128 v[212:215], v158 offset:21504
	ds_read_b128 v[216:219], v158 offset:22528
	ds_read_b128 v[220:223], v158 offset:23552
	global_load_lds_dwordx4 v[190:191], off
	v_lshl_add_u64 v[190:191], s[20:21], 0, v[144:145]
	s_mov_b32 m0, s53
	s_nop 0
	global_load_lds_dwordx4 v[190:191], off
	s_waitcnt vmcnt(10)
	s_barrier
	s_waitcnt lgkmcnt(0)
	v_mfma_f32_16x16x32_bf16 v[60:63], v[132:135], v[172:175], v[60:63]
	v_mfma_f32_16x16x32_bf16 v[56:59], v[140:143], v[172:175], v[56:59]
	v_mfma_f32_16x16x32_bf16 v[52:55], v[132:135], v[180:183], v[52:55]
	v_mfma_f32_16x16x32_bf16 v[44:47], v[140:143], v[180:183], v[44:47]
	v_mfma_f32_16x16x32_bf16 v[28:31], v[132:135], v[208:211], v[28:31]
	v_mfma_f32_16x16x32_bf16 v[24:27], v[140:143], v[208:211], v[24:27]
	v_mfma_f32_16x16x32_bf16 v[20:23], v[132:135], v[216:219], v[20:23]
	v_mfma_f32_16x16x32_bf16 v[12:15], v[140:143], v[216:219], v[12:15]
	v_mfma_f32_16x16x32_bf16 v[60:63], v[136:139], v[176:179], v[60:63]
	v_mfma_f32_16x16x32_bf16 v[56:59], v[168:171], v[176:179], v[56:59]
	v_mfma_f32_16x16x32_bf16 v[52:55], v[136:139], v[204:207], v[52:55]
	v_mfma_f32_16x16x32_bf16 v[44:47], v[168:171], v[204:207], v[44:47]
	v_mfma_f32_16x16x32_bf16 v[28:31], v[136:139], v[212:215], v[28:31]
	v_mfma_f32_16x16x32_bf16 v[24:27], v[168:171], v[212:215], v[24:27]
	v_mfma_f32_16x16x32_bf16 v[20:23], v[136:139], v[220:223], v[20:23]
	v_mfma_f32_16x16x32_bf16 v[12:15], v[168:171], v[220:223], v[12:15]
	s_barrier
; #define PG8_STAGE(bufoff, gbase, voff) do { _Pragma("unroll") for (int _i = 0; _i < 2; ++_i) \
;         __builtin_amdgcn_global_load_lds((const unsigned*)((const char*)(gbase) + (voff)[_i]), (LAS unsigned*)(lds + (bufoff) + ldsw + _i * 8192), 16, 0, 0); } while (0)
; #define PG8_STAGE_A(bufoff, ptr, half, rev) do { if (REVA && (rev)) { const char* _p = (ptr) - ((half) ? hstepA : 0); PG8_STAGE(bufoff, _p, voffAr); } else { const char* _p = (ptr) + ((half) ? hstepA : 0); PG8_STAGE(bufoff, _p, voffA); } } while (0)
; #define PG8_LDA(dst, b, h) do { _Pragma("unroll") for (int m = 0; m < 4; ++m) _Pragma("unroll") for (int k = 0; k < 2; ++k) dst[m][k] = *(const LAS bf16x8*)(lds + PG8_SA(b, h) + aoff + m * 2048 + k * 1024); } while (0)
; #define PG8_LDB(dst, b, h) do { _Pragma("unroll") for (int n = 0; n < 2; ++n) _Pragma("unroll") for (int k = 0; k < 2; ++k) dst[n][k] = *(const LAS bf16x8*)(lds + PG8_SB(b, h) + boff + n * 2048 + k * 1024); } while (0)
; #define PG8_WAIT_V(n) asm volatile("s_waitcnt vmcnt(" #n ")" ::: "memory")
; #define PG8_WAIT_L(n) asm volatile("s_waitcnt lgkmcnt(" #n ")" ::: "memory")
; #define PG8_BAR __builtin_amdgcn_s_barrier()
;     ...
;             PG8_LDB(B0, 0, 0); PG8_SCHED; PG8_LDA(At, 0, 0); PG8_STAGE_A(PG8_SA(1, 1), a1, 1, r1);
;             PG8_WAIT_L(8); PG8_BAR; PG8_WAIT_L(0); PG8_MMA(0, 0, At, B0); PG8_BAR; PG8_SCHED;
;             PG8_LDB(B1, 0, 1); PG8_STAGE(PG8_SB(0, 0), b2, voffB);
;             PG8_BAR; PG8_WAIT_L(0); PG8_MMA(0, 1, At, B1); PG8_BAR;
;             PG8_LDA(At, 0, 1); PG8_STAGE_A(PG8_SA(0, 0), a2, 0, r2);
;             PG8_BAR; PG8_WAIT_L(0); PG8_MMA(1, 0, At, B0); PG8_BAR; PG8_SCHED;
;             PG8_STAGE(PG8_SB(0, 1), b2 + hb2, voffB);
;             PG8_WAIT_V(6); PG8_BAR; PG8_MMA(1, 1, At, B1); PG8_BAR;
;             PG8_LDB(B0, 1, 0); PG8_SCHED; PG8_LDA(At, 1, 0); PG8_STAGE_A(PG8_SA(0, 1), a2, 1, r2);
;             PG8_WAIT_L(8); PG8_BAR; PG8_WAIT_L(0); PG8_MMA(0, 0, At, B0); PG8_BAR; PG8_SCHED;
;             PG8_LDB(B1, 1, 1); PG8_STAGE(PG8_SB(1, 0), b3, voffB);
;             PG8_BAR; PG8_WAIT_L(0); PG8_MMA(0, 1, At, B1); PG8_BAR;
;             PG8_LDA(At, 1, 1); PG8_STAGE_A(PG8_SA(1, 0), a3, 0, r3);
;             PG8_BAR; PG8_WAIT_L(0); PG8_MMA(1, 0, At, B0); PG8_BAR; PG8_SCHED;
;             PG8_STAGE(PG8_SB(1, 1), b3 + hb2, voffB);
;             PG8_WAIT_V(6); PG8_BAR; PG8_MMA(1, 1, At, B1); PG8_BAR;
	s_add_u32 s10, s14, 0x100000
	s_addc_u32 s11, s15, 0
	s_add_i32 s93, s94, s52
	v_lshl_add_u64 v[132:133], s[10:11], 0, v[146:147]
	s_mov_b32 m0, s93
	s_nop 0
	global_load_lds_dwordx4 v[132:133], off
	v_lshl_add_u64 v[132:133], s[10:11], 0, v[144:145]
	s_add_i32 m0, s93, 0x2000
	s_nop 0
	global_load_lds_dwordx4 v[132:133], off
	v_add_u32_e32 v159, 0x18000, v157
	ds_read_b128 v[132:135], v159
	ds_read_b128 v[136:139], v159 offset:1024
	ds_read_b128 v[140:143], v159 offset:2048
	ds_read_b128 v[168:171], v159 offset:3072
	s_waitcnt vmcnt(10)
	s_barrier
	v_mfma_f32_16x16x32_bf16 v[48:51], v[224:227], v[172:175], v[48:51]
	v_mfma_f32_16x16x32_bf16 v[40:43], v[232:235], v[172:175], v[40:43]
	v_mfma_f32_16x16x32_bf16 v[36:39], v[224:227], v[180:183], v[36:39]
	v_mfma_f32_16x16x32_bf16 v[32:35], v[232:235], v[180:183], v[32:35]
	v_mfma_f32_16x16x32_bf16 v[16:19], v[224:227], v[208:211], v[16:19]
	v_mfma_f32_16x16x32_bf16 v[8:11], v[232:235], v[208:211], v[8:11]
	v_mfma_f32_16x16x32_bf16 v[4:7], v[224:227], v[216:219], v[4:7]
	v_mfma_f32_16x16x32_bf16 v[0:3], v[232:235], v[216:219], v[0:3]
	v_mfma_f32_16x16x32_bf16 v[48:51], v[228:231], v[176:179], v[48:51]
	v_mfma_f32_16x16x32_bf16 v[40:43], v[236:239], v[176:179], v[40:43]
	v_mfma_f32_16x16x32_bf16 v[36:39], v[228:231], v[204:207], v[36:39]
	v_mfma_f32_16x16x32_bf16 v[32:35], v[236:239], v[204:207], v[32:35]
	v_mfma_f32_16x16x32_bf16 v[16:19], v[228:231], v[212:215], v[16:19]
	v_mfma_f32_16x16x32_bf16 v[8:11], v[236:239], v[212:215], v[8:11]
	v_mfma_f32_16x16x32_bf16 v[4:7], v[228:231], v[220:223], v[4:7]
	v_mfma_f32_16x16x32_bf16 v[0:3], v[236:239], v[220:223], v[0:3]
	s_add_i32 s93, 0, 0x18000
	s_barrier
	s_add_u32 s10, s20, 0x100000
	s_addc_u32 s11, s21, 0
	s_mov_b32 m0, s6
	v_lshl_add_u64 v[190:191], s[10:11], 0, v[146:147]
	ds_read_b128 v[172:175], v158 offset:32768
	ds_read_b128 v[176:179], v158 offset:33792
	ds_read_b128 v[180:183], v158 offset:34816
	ds_read_b128 v[204:207], v158 offset:35840
	ds_read_b128 v[208:211], v158 offset:36864
	ds_read_b128 v[212:215], v158 offset:37888
	ds_read_b128 v[216:219], v158 offset:38912
	ds_read_b128 v[220:223], v158 offset:39936
	global_load_lds_dwordx4 v[190:191], off
	v_lshl_add_u64 v[190:191], s[10:11], 0, v[144:145]
	s_mov_b32 m0, s7
	s_nop 0
	global_load_lds_dwordx4 v[190:191], off
	s_waitcnt lgkmcnt(8)
	s_waitcnt vmcnt(10)
	s_barrier
	s_waitcnt lgkmcnt(0)
	v_mfma_f32_16x16x32_bf16 v[124:127], v[132:135], v[172:175], v[124:127]
	v_mfma_f32_16x16x32_bf16 v[120:123], v[140:143], v[172:175], v[120:123]
	v_mfma_f32_16x16x32_bf16 v[116:119], v[132:135], v[180:183], v[116:119]
	v_mfma_f32_16x16x32_bf16 v[108:111], v[140:143], v[180:183], v[108:111]
	v_mfma_f32_16x16x32_bf16 v[92:95], v[132:135], v[208:211], v[92:95]
	v_mfma_f32_16x16x32_bf16 v[88:91], v[140:143], v[208:211], v[88:91]
	v_mfma_f32_16x16x32_bf16 v[84:87], v[132:135], v[216:219], v[84:87]
	v_mfma_f32_16x16x32_bf16 v[76:79], v[140:143], v[216:219], v[76:79]
	v_mfma_f32_16x16x32_bf16 v[124:127], v[136:139], v[176:179], v[124:127]
	v_mfma_f32_16x16x32_bf16 v[120:123], v[168:171], v[176:179], v[120:123]
	v_mfma_f32_16x16x32_bf16 v[116:119], v[136:139], v[204:207], v[116:119]
	v_mfma_f32_16x16x32_bf16 v[108:111], v[168:171], v[204:207], v[108:111]
	v_mfma_f32_16x16x32_bf16 v[92:95], v[136:139], v[212:215], v[92:95]
	v_mfma_f32_16x16x32_bf16 v[88:91], v[168:171], v[212:215], v[88:91]
	v_mfma_f32_16x16x32_bf16 v[84:87], v[136:139], v[220:223], v[84:87]
	v_mfma_f32_16x16x32_bf16 v[76:79], v[168:171], v[220:223], v[76:79]
	s_barrier
	s_add_i32 s20, 0, 0x1c000
	s_add_i32 s10, s93, s52
	v_add_u32_e32 v159, s20, v157
	v_lshl_add_u64 v[154:155], v[154:155], 0, s[28:29]
	s_mov_b32 m0, s10
	ds_read_b128 v[224:227], v159
	ds_read_b128 v[228:231], v159 offset:1024
	ds_read_b128 v[232:235], v159 offset:2048
	ds_read_b128 v[236:239], v159 offset:3072
	global_load_lds_dwordx4 v[154:155], off
	v_lshl_add_u64 v[154:155], v[184:185], 0, s[28:29]
	s_add_i32 m0, s10, 0x2000
	s_nop 0
	global_load_lds_dwordx4 v[154:155], off
	s_waitcnt vmcnt(10)
	s_barrier
	s_waitcnt lgkmcnt(0)
	v_mfma_f32_16x16x32_bf16 v[112:115], v[224:227], v[172:175], v[112:115]
	v_mfma_f32_16x16x32_bf16 v[104:107], v[232:235], v[172:175], v[104:107]
	v_mfma_f32_16x16x32_bf16 v[100:103], v[224:227], v[180:183], v[100:103]
	v_mfma_f32_16x16x32_bf16 v[96:99], v[232:235], v[180:183], v[96:99]
	v_mfma_f32_16x16x32_bf16 v[80:83], v[224:227], v[208:211], v[80:83]
	v_mfma_f32_16x16x32_bf16 v[72:75], v[232:235], v[208:211], v[72:75]
	v_mfma_f32_16x16x32_bf16 v[68:71], v[224:227], v[216:219], v[68:71]
	v_mfma_f32_16x16x32_bf16 v[64:67], v[232:235], v[216:219], v[64:67]
	v_mfma_f32_16x16x32_bf16 v[112:115], v[228:231], v[176:179], v[112:115]
	v_mfma_f32_16x16x32_bf16 v[104:107], v[236:239], v[176:179], v[104:107]
	v_mfma_f32_16x16x32_bf16 v[100:103], v[228:231], v[204:207], v[100:103]
	v_mfma_f32_16x16x32_bf16 v[96:99], v[236:239], v[204:207], v[96:99]
	v_mfma_f32_16x16x32_bf16 v[80:83], v[228:231], v[212:215], v[80:83]
	v_mfma_f32_16x16x32_bf16 v[72:75], v[236:239], v[212:215], v[72:75]
	v_mfma_f32_16x16x32_bf16 v[68:71], v[228:231], v[220:223], v[68:71]
	v_mfma_f32_16x16x32_bf16 v[64:67], v[236:239], v[220:223], v[64:67]
	s_mov_b32 m0, s70
	v_lshl_add_u64 v[154:155], s[16:17], 0, v[146:147]
	s_barrier
	ds_read_b128 v[172:175], v158 offset:49152
	ds_read_b128 v[176:179], v158 offset:50176
	ds_read_b128 v[180:183], v158 offset:51200
	ds_read_b128 v[204:207], v158 offset:52224
	ds_read_b128 v[208:211], v158 offset:53248
	ds_read_b128 v[212:215], v158 offset:54272
	ds_read_b128 v[216:219], v158 offset:55296
	ds_read_b128 v[220:223], v158 offset:56320
	global_load_lds_dwordx4 v[154:155], off
	v_lshl_add_u64 v[154:155], s[16:17], 0, v[144:145]
	s_mov_b32 m0, s71
	s_nop 0
	global_load_lds_dwordx4 v[154:155], off
	s_waitcnt vmcnt(10)
	s_barrier
; #define PG8_STAGE(bufoff, gbase, voff) do { _Pragma("unroll") for (int _i = 0; _i < 2; ++_i) \
;         __builtin_amdgcn_global_load_lds((const unsigned*)((const char*)(gbase) + (voff)[_i]), (LAS unsigned*)(lds + (bufoff) + ldsw + _i * 8192), 16, 0, 0); } while (0)
; #define PG8_STAGE_A(bufoff, ptr, half, rev) do { if (REVA && (rev)) { const char* _p = (ptr) - ((half) ? hstepA : 0); PG8_STAGE(bufoff, _p, voffAr); } else { const char* _p = (ptr) + ((half) ? hstepA : 0); PG8_STAGE(bufoff, _p, voffA); } } while (0)
; #define PG8_LDA(dst, b, h) do { _Pragma("unroll") for (int m = 0; m < 4; ++m) _Pragma("unroll") for (int k = 0; k < 2; ++k) dst[m][k] = *(const LAS bf16x8*)(lds + PG8_SA(b, h) + aoff + m * 2048 + k * 1024); } while (0)
; #define PG8_WAIT_V(n) asm volatile("s_waitcnt vmcnt(" #n ")" ::: "memory")
; #define PG8_WAIT_L(n) asm volatile("s_waitcnt lgkmcnt(" #n ")" ::: "memory")
; #define PG8_BAR __builtin_amdgcn_s_barrier()
;     ...
;             PG8_WAIT_V(6); PG8_BAR; PG8_MMA(1, 1, At, B1); PG8_BAR;
;             PG8_LDB(B0, 1, 0); PG8_SCHED; PG8_LDA(At, 1, 0); PG8_STAGE_A(PG8_SA(0, 1), a2, 1, r2);
;             PG8_WAIT_L(8); PG8_BAR; PG8_WAIT_L(0); PG8_MMA(0, 0, At, B0); PG8_BAR; PG8_SCHED;
;             PG8_LDB(B1, 1, 1); PG8_STAGE(PG8_SB(1, 0), b3, voffB);
;             PG8_BAR; PG8_WAIT_L(0); PG8_MMA(0, 1, At, B1); PG8_BAR;
;             PG8_LDA(At, 1, 1); PG8_STAGE_A(PG8_SA(1, 0), a3, 0, r3);
;             PG8_BAR; PG8_WAIT_L(0); PG8_MMA(1, 0, At, B0); PG8_BAR; PG8_SCHED;
;             PG8_STAGE(PG8_SB(1, 1), b3 + hb2, voffB);
;             PG8_WAIT_V(6); PG8_BAR; PG8_MMA(1, 1, At, B1); PG8_BAR;
;     __device__ __forceinline__ void operator()(const f32x4 (&acc)[2][2][4][2], const Unit& u, int wr, int wc, int fr, int fq, int lane) const {
;         const bool lat = u.pm < 128;
;         const int s = lat ? (u.pm >> 4) : 8;
;         const float* gate = modi + s * 6144 + 4096 + u.pn * BM + wc * 32 + 4 * fq;
;         const size_t r0 = lat ? (size_t)u.pm * BM : (size_t)(u.pm - 128) * BM;
;         const float* base = (lat ? baseL : baseC) + u.pn * BM + wc * 32 + 4 * fq;
;         float* out = (lat ? outL : outC) + u.pn * BM + wc * 32 + 4 * fq;
;         f32x4 gv[2][2];
; #pragma unroll
;         for (int bj = 0; bj < 2; ++bj)
; #pragma unroll
;             for (int n = 0; n < 2; ++n) gv[bj][n] = *(const f32x4*)(gate + bj * HALF + n * 16);
	s_waitcnt lgkmcnt(0)
	v_mfma_f32_16x16x32_bf16 v[60:63], v[132:135], v[172:175], v[60:63]
	v_mfma_f32_16x16x32_bf16 v[56:59], v[140:143], v[172:175], v[56:59]
	v_mfma_f32_16x16x32_bf16 v[52:55], v[132:135], v[180:183], v[52:55]
	v_mfma_f32_16x16x32_bf16 v[44:47], v[140:143], v[180:183], v[44:47]
	v_mfma_f32_16x16x32_bf16 v[28:31], v[132:135], v[208:211], v[28:31]
	v_mfma_f32_16x16x32_bf16 v[24:27], v[140:143], v[208:211], v[24:27]
	v_mfma_f32_16x16x32_bf16 v[20:23], v[132:135], v[216:219], v[20:23]
	v_mfma_f32_16x16x32_bf16 v[12:15], v[140:143], v[216:219], v[12:15]
	v_mfma_f32_16x16x32_bf16 v[60:63], v[136:139], v[176:179], v[60:63]
	v_mfma_f32_16x16x32_bf16 v[56:59], v[168:171], v[176:179], v[56:59]
	v_mfma_f32_16x16x32_bf16 v[52:55], v[136:139], v[204:207], v[52:55]
	v_mfma_f32_16x16x32_bf16 v[44:47], v[168:171], v[204:207], v[44:47]
	v_mfma_f32_16x16x32_bf16 v[28:31], v[136:139], v[212:215], v[28:31]
	v_mfma_f32_16x16x32_bf16 v[24:27], v[168:171], v[212:215], v[24:27]
	v_mfma_f32_16x16x32_bf16 v[20:23], v[136:139], v[220:223], v[20:23]
	v_mfma_f32_16x16x32_bf16 v[12:15], v[168:171], v[220:223], v[12:15]
	s_barrier
	s_add_u32 s10, s14, 0x100080
	s_addc_u32 s11, s15, 0
	s_add_i32 s14, s20, s52
	v_lshl_add_u64 v[132:133], s[10:11], 0, v[146:147]
	s_mov_b32 m0, s14
	s_nop 0
	global_load_lds_dwordx4 v[132:133], off
	v_lshl_add_u64 v[132:133], s[10:11], 0, v[144:145]
	s_add_i32 m0, s14, 0x2000
	s_nop 0
	global_load_lds_dwordx4 v[132:133], off
	v_add_u32_e32 v154, 0x10000, v157
	ds_read_b128 v[132:135], v154
	ds_read_b128 v[136:139], v154 offset:1024
	ds_read_b128 v[140:143], v154 offset:2048
	ds_read_b128 v[168:171], v154 offset:3072
	s_waitcnt vmcnt(10)
	s_barrier
	v_mfma_f32_16x16x32_bf16 v[48:51], v[224:227], v[172:175], v[48:51]
	v_mfma_f32_16x16x32_bf16 v[40:43], v[232:235], v[172:175], v[40:43]
	v_mfma_f32_16x16x32_bf16 v[36:39], v[224:227], v[180:183], v[36:39]
	v_mfma_f32_16x16x32_bf16 v[32:35], v[232:235], v[180:183], v[32:35]
	v_mfma_f32_16x16x32_bf16 v[16:19], v[224:227], v[208:211], v[16:19]
	v_mfma_f32_16x16x32_bf16 v[8:11], v[232:235], v[208:211], v[8:11]
	v_mfma_f32_16x16x32_bf16 v[4:7], v[224:227], v[216:219], v[4:7]
	v_mfma_f32_16x16x32_bf16 v[0:3], v[232:235], v[216:219], v[0:3]
	v_mfma_f32_16x16x32_bf16 v[48:51], v[228:231], v[176:179], v[48:51]
	v_mfma_f32_16x16x32_bf16 v[40:43], v[236:239], v[176:179], v[40:43]
	v_mfma_f32_16x16x32_bf16 v[36:39], v[228:231], v[204:207], v[36:39]
	v_mfma_f32_16x16x32_bf16 v[32:35], v[236:239], v[204:207], v[32:35]
	v_mfma_f32_16x16x32_bf16 v[16:19], v[228:231], v[212:215], v[16:19]
	v_mfma_f32_16x16x32_bf16 v[8:11], v[236:239], v[212:215], v[8:11]
	v_mfma_f32_16x16x32_bf16 v[4:7], v[228:231], v[220:223], v[4:7]
	v_mfma_f32_16x16x32_bf16 v[0:3], v[236:239], v[220:223], v[0:3]
	s_add_i32 s92, s92, 2
	s_add_u32 s46, s46, 0x100
	s_addc_u32 s47, s47, 0
	s_cmp_gt_u32 s92, 61
	s_cbranch_scc0 .Lrot_335_bar
	s_barrier
	s_waitcnt lgkmcnt(0)
	s_cmpk_lt_i32 s0, 0x80
	s_cselect_b32 s3, s61, s67
	s_cselect_b32 s16, s60, s66
	s_add_i32 s9, s0, 0xffffff80
	s_cmpk_lt_i32 s0, 0x80
	s_cselect_b32 s10, s0, s9
	s_lshr_b32 s9, s0, 4
	s_cmpk_lt_i32 s0, 0x80
	s_mulk_i32 s9, 0x1800
	s_cselect_b32 s14, s9, 0xc000
	s_ashr_i32 s15, s14, 31
	s_lshl_b64 s[14:15], s[14:15], 2
	s_add_u32 s0, s68, s14
	s_addc_u32 s11, s69, s15
	s_lshl_b32 s8, s8, 8
	s_ashr_i32 s9, s8, 31
	s_lshl_b64 s[8:9], s[8:9], 2
	s_add_u32 s0, s0, s8
	s_addc_u32 s11, s11, s9
	s_add_u32 s14, s0, s90
	s_addc_u32 s15, s11, 0
	s_ashr_i32 s11, s10, 31
	s_add_u32 s0, s16, s8
	s_addc_u32 s3, s3, s9
	s_add_u32 s8, s0, s90
	s_addc_u32 s9, s3, 0
	v_lshl_add_u64 v[128:129], s[14:15], 0, v[160:161]
	s_mov_b64 s[14:15], 0x704000
	s_mov_b32 s0, 0x704000
	v_lshl_add_u64 v[154:155], s[8:9], 0, v[160:161]
	s_lshl_b64 s[8:9], s[10:11], 21
	v_lshl_add_u64 v[130:131], v[128:129], 0, s[14:15]
	v_add_co_u32_e32 v128, vcc, s0, v128
	v_lshl_add_u64 v[154:155], v[154:155], 0, s[8:9]
	s_nop 0
	v_addc_co_u32_e32 v129, vcc, 0, v129, vcc
	v_lshl_add_u64 v[154:155], v[154:155], 0, v[148:149]
	s_mov_b32 s0, 0x20000
	v_add_co_u32_e32 v184, vcc, s0, v154
	global_load_dwordx4 v[136:139], v[130:131], off offset:64
	global_load_dwordx4 v[132:135], v[130:131], off offset:512
	global_load_dwordx4 v[140:143], v[128:129], off
	s_nop 0
	global_load_dwordx4 v[128:131], v[130:131], off offset:576
	v_addc_co_u32_e32 v185, vcc, 0, v155, vcc
	global_load_dwordx4 v[168:171], v[154:155], off
	global_load_dwordx4 v[172:175], v[154:155], off offset:64
	global_load_dwordx4 v[176:179], v[154:155], off offset:512
	global_load_dwordx4 v[180:183], v[154:155], off offset:576
	global_load_dwordx4 v[204:207], v[184:185], off
	global_load_dwordx4 v[208:211], v[184:185], off offset:64
	global_load_dwordx4 v[212:215], v[184:185], off offset:512
	global_load_dwordx4 v[216:219], v[184:185], off offset:576
	s_waitcnt vmcnt(0)
;     __device__ __forceinline__ void operator()(const f32x4 (&acc)[2][2][4][2], const Unit& u, int wr, int wc, int fr, int fq, int lane) const {
;     ...
; #pragma unroll
;         for (int ai = 0; ai < 2; ++ai)
; #pragma unroll
;           for (int mh = 0; mh < 2; ++mh) {
;             f32x4 bs[2][2][2];
; #pragma unroll
;             for (int m2 = 0; m2 < 2; ++m2) {
;                 const size_t ro = (r0 + ai * HALF + wr * 64 + (mh * 2 + m2) * 16 + fr) * (size_t)D;
; #pragma unroll
;                 for (int bj = 0; bj < 2; ++bj)
; #pragma unroll
;                     for (int n = 0; n < 2; ++n) bs[m2][bj][n] = *(const f32x4*)(base + ro + bj * HALF + n * 16);
;             }
;             __builtin_amdgcn_sched_barrier(0);
; #pragma unroll
;             for (int m2 = 0; m2 < 2; ++m2) {
;                 const size_t ro = (r0 + ai * HALF + wr * 64 + (mh * 2 + m2) * 16 + fr) * (size_t)D;
; #pragma unroll
;                 for (int bj = 0; bj < 2; ++bj)
; #pragma unroll
;                     for (int n = 0; n < 2; ++n) *(f32x4*)(out + ro + bj * HALF + n * 16) = bs[m2][bj][n] + gv[bj][n] * acc[ai][bj][mh * 2 + m2][n];
;             }
;             __builtin_amdgcn_sched_barrier(0);
	v_pk_fma_f32 v[106:107], v[106:107], v[130:131], v[182:183]
	v_pk_fma_f32 v[104:105], v[104:105], v[128:129], v[180:181]
	global_store_dwordx4 v[154:155], v[104:107], off offset:576
	v_pk_fma_f32 v[126:127], v[126:127], v[142:143], v[170:171]
	v_pk_fma_f32 v[124:125], v[124:125], v[140:141], v[168:169]
	v_pk_fma_f32 v[106:107], v[118:119], v[142:143], v[206:207]
	v_pk_fma_f32 v[104:105], v[116:117], v[140:141], v[204:205]
	v_pk_fma_f32 v[122:123], v[122:123], v[138:139], v[174:175]
	v_pk_fma_f32 v[120:121], v[120:121], v[136:137], v[172:173]
	v_pk_fma_f32 v[114:115], v[114:115], v[134:135], v[178:179]
	v_pk_fma_f32 v[112:113], v[112:113], v[132:133], v[176:177]
	global_store_dwordx4 v[184:185], v[104:107], off
	v_pk_fma_f32 v[102:103], v[102:103], v[134:135], v[214:215]
	v_pk_fma_f32 v[100:101], v[100:101], v[132:133], v[212:213]
	v_pk_fma_f32 v[106:107], v[110:111], v[138:139], v[210:211]
	v_pk_fma_f32 v[104:105], v[108:109], v[136:137], v[208:209]
	v_pk_fma_f32 v[98:99], v[98:99], v[130:131], v[218:219]
	v_pk_fma_f32 v[96:97], v[96:97], v[128:129], v[216:217]
	global_store_dwordx4 v[154:155], v[124:127], off
	global_store_dwordx4 v[154:155], v[120:123], off offset:64
	global_store_dwordx4 v[154:155], v[112:115], off offset:512
	global_store_dwordx4 v[184:185], v[104:107], off offset:64
	global_store_dwordx4 v[184:185], v[100:103], off offset:512
	global_store_dwordx4 v[184:185], v[96:99], off offset:576
	s_mov_b32 s0, 0x40000
	v_add_co_u32_e32 v168, vcc, s0, v154
	s_mov_b32 s0, 0x60000
	s_nop 0
	v_addc_co_u32_e32 v169, vcc, 0, v155, vcc
	v_add_co_u32_e32 v170, vcc, s0, v154
	global_load_dwordx4 v[96:99], v[168:169], off
	global_load_dwordx4 v[100:103], v[168:169], off offset:64
	global_load_dwordx4 v[104:107], v[168:169], off offset:512
	global_load_dwordx4 v[108:111], v[168:169], off offset:576
	v_addc_co_u32_e32 v171, vcc, 0, v155, vcc
	global_load_dwordx4 v[112:115], v[170:171], off
	global_load_dwordx4 v[116:119], v[170:171], off offset:64
	global_load_dwordx4 v[120:123], v[170:171], off offset:512
	global_load_dwordx4 v[124:127], v[170:171], off offset:576
	s_waitcnt vmcnt(0)
	v_pk_fma_f32 v[74:75], v[74:75], v[130:131], v[110:111]
	v_pk_fma_f32 v[72:73], v[72:73], v[128:129], v[108:109]
	global_store_dwordx4 v[168:169], v[72:75], off offset:576
	v_pk_fma_f32 v[94:95], v[94:95], v[142:143], v[98:99]
	v_pk_fma_f32 v[92:93], v[92:93], v[140:141], v[96:97]
	v_pk_fma_f32 v[74:75], v[86:87], v[142:143], v[114:115]
	v_pk_fma_f32 v[72:73], v[84:85], v[140:141], v[112:113]
	v_pk_fma_f32 v[90:91], v[90:91], v[138:139], v[102:103]
	v_pk_fma_f32 v[88:89], v[88:89], v[136:137], v[100:101]
	v_pk_fma_f32 v[82:83], v[82:83], v[134:135], v[106:107]
	v_pk_fma_f32 v[80:81], v[80:81], v[132:133], v[104:105]
	global_store_dwordx4 v[170:171], v[72:75], off
	v_pk_fma_f32 v[70:71], v[70:71], v[134:135], v[122:123]
	v_pk_fma_f32 v[68:69], v[68:69], v[132:133], v[120:121]
	v_pk_fma_f32 v[74:75], v[78:79], v[138:139], v[118:119]
	v_pk_fma_f32 v[72:73], v[76:77], v[136:137], v[116:117]
	v_pk_fma_f32 v[66:67], v[66:67], v[130:131], v[126:127]
	v_pk_fma_f32 v[64:65], v[64:65], v[128:129], v[124:125]
	global_store_dwordx4 v[168:169], v[92:95], off
	global_store_dwordx4 v[168:169], v[88:91], off offset:64
	global_store_dwordx4 v[168:169], v[80:83], off offset:512
	global_store_dwordx4 v[170:171], v[72:75], off offset:64
	global_store_dwordx4 v[170:171], v[68:71], off offset:512
	global_store_dwordx4 v[170:171], v[64:67], off offset:576
	v_add_co_u32_e32 v96, vcc, s76, v154
	s_nop 1
	v_addc_co_u32_e32 v97, vcc, 0, v155, vcc
	v_add_co_u32_e32 v98, vcc, s77, v154
	global_load_dwordx4 v[64:67], v[96:97], off
	global_load_dwordx4 v[68:71], v[96:97], off offset:64
	global_load_dwordx4 v[72:75], v[96:97], off offset:512
	global_load_dwordx4 v[76:79], v[96:97], off offset:576
	v_addc_co_u32_e32 v99, vcc, 0, v155, vcc
	global_load_dwordx4 v[80:83], v[98:99], off
	global_load_dwordx4 v[84:87], v[98:99], off offset:64
	global_load_dwordx4 v[88:91], v[98:99], off offset:512
	global_load_dwordx4 v[92:95], v[98:99], off offset:576
	s_waitcnt vmcnt(0)
; #define PG8_WAIT_V(n) asm volatile("s_waitcnt vmcnt(" #n ")" ::: "memory")
; #define PG8_BAR __builtin_amdgcn_s_barrier()
;     ...
;         if (!has_next) break;
; #pragma unroll
;         for (int a = 0; a < 2; ++a)
; #pragma unroll
;             for (int b = 0; b < 2; ++b)
; #pragma unroll
;                 for (int m = 0; m < 4; ++m)
; #pragma unroll
;                     for (int n = 0; n < 2; ++n) acc[a][b][m][n] = (f32x4){0.f, 0.f, 0.f, 0.f};
;         cur = nxt; cA = nA; cB = nB; cAr = nAr; cHb = nHb; ++ui;
;     }
;     PG8_WAIT_V(0);
;     if (wr == 0) PG8_BAR;
;     PG8_BAR;
;     __device__ __forceinline__ void operator()(const f32x4 (&acc)[2][2][4][2], const Unit& u, int wr, int wc, int fr, int fq, int lane) const {
;     ...
; #pragma unroll
;         for (int ai = 0; ai < 2; ++ai)
; #pragma unroll
;           for (int mh = 0; mh < 2; ++mh) {
;             f32x4 bs[2][2][2];
; #pragma unroll
;             for (int m2 = 0; m2 < 2; ++m2) {
;                 const size_t ro = (r0 + ai * HALF + wr * 64 + (mh * 2 + m2) * 16 + fr) * (size_t)D;
; #pragma unroll
;                 for (int bj = 0; bj < 2; ++bj)
; #pragma unroll
;                     for (int n = 0; n < 2; ++n) bs[m2][bj][n] = *(const f32x4*)(base + ro + bj * HALF + n * 16);
;             }
;             __builtin_amdgcn_sched_barrier(0);
; #pragma unroll
;             for (int m2 = 0; m2 < 2; ++m2) {
;                 const size_t ro = (r0 + ai * HALF + wr * 64 + (mh * 2 + m2) * 16 + fr) * (size_t)D;
; #pragma unroll
;                 for (int bj = 0; bj < 2; ++bj)
; #pragma unroll
;                     for (int n = 0; n < 2; ++n) *(f32x4*)(out + ro + bj * HALF + n * 16) = bs[m2][bj][n] + gv[bj][n] * acc[ai][bj][mh * 2 + m2][n];
;             }
;             __builtin_amdgcn_sched_barrier(0);
	v_pk_fma_f32 v[42:43], v[42:43], v[130:131], v[78:79]
	v_pk_fma_f32 v[40:41], v[40:41], v[128:129], v[76:77]
	global_store_dwordx4 v[96:97], v[40:43], off offset:576
	v_pk_fma_f32 v[62:63], v[62:63], v[142:143], v[66:67]
	v_pk_fma_f32 v[60:61], v[60:61], v[140:141], v[64:65]
	v_pk_fma_f32 v[42:43], v[54:55], v[142:143], v[82:83]
	v_pk_fma_f32 v[40:41], v[52:53], v[140:141], v[80:81]
	v_pk_fma_f32 v[58:59], v[58:59], v[138:139], v[70:71]
	v_pk_fma_f32 v[56:57], v[56:57], v[136:137], v[68:69]
	v_pk_fma_f32 v[50:51], v[50:51], v[134:135], v[74:75]
	v_pk_fma_f32 v[48:49], v[48:49], v[132:133], v[72:73]
	global_store_dwordx4 v[98:99], v[40:43], off
	v_pk_fma_f32 v[38:39], v[38:39], v[134:135], v[90:91]
	v_pk_fma_f32 v[36:37], v[36:37], v[132:133], v[88:89]
	v_pk_fma_f32 v[42:43], v[46:47], v[138:139], v[86:87]
	v_pk_fma_f32 v[40:41], v[44:45], v[136:137], v[84:85]
	v_pk_fma_f32 v[34:35], v[34:35], v[130:131], v[94:95]
	v_pk_fma_f32 v[32:33], v[32:33], v[128:129], v[92:93]
	global_store_dwordx4 v[96:97], v[60:63], off
	global_store_dwordx4 v[96:97], v[56:59], off offset:64
	global_store_dwordx4 v[96:97], v[48:51], off offset:512
	global_store_dwordx4 v[98:99], v[40:43], off offset:64
	global_store_dwordx4 v[98:99], v[36:39], off offset:512
	global_store_dwordx4 v[98:99], v[32:35], off offset:576
	v_add_co_u32_e32 v64, vcc, s18, v154
	s_nop 1
	v_addc_co_u32_e32 v65, vcc, 0, v155, vcc
	v_add_co_u32_e32 v66, vcc, s54, v154
	global_load_dwordx4 v[32:35], v[64:65], off
	global_load_dwordx4 v[36:39], v[64:65], off offset:64
	global_load_dwordx4 v[40:43], v[64:65], off offset:512
	global_load_dwordx4 v[44:47], v[64:65], off offset:576
	v_addc_co_u32_e32 v67, vcc, 0, v155, vcc
	global_load_dwordx4 v[48:51], v[66:67], off
	global_load_dwordx4 v[52:55], v[66:67], off offset:64
	global_load_dwordx4 v[56:59], v[66:67], off offset:512
	global_load_dwordx4 v[60:63], v[66:67], off offset:576
	s_waitcnt vmcnt(0)
	v_pk_fma_f32 v[10:11], v[10:11], v[130:131], v[46:47]
	v_pk_fma_f32 v[8:9], v[8:9], v[128:129], v[44:45]
	global_store_dwordx4 v[64:65], v[8:11], off offset:576
	v_pk_fma_f32 v[30:31], v[30:31], v[142:143], v[34:35]
	v_pk_fma_f32 v[28:29], v[28:29], v[140:141], v[32:33]
	v_pk_fma_f32 v[10:11], v[22:23], v[142:143], v[50:51]
	v_pk_fma_f32 v[8:9], v[20:21], v[140:141], v[48:49]
	v_pk_fma_f32 v[26:27], v[26:27], v[138:139], v[38:39]
	v_pk_fma_f32 v[24:25], v[24:25], v[136:137], v[36:37]
	v_pk_fma_f32 v[18:19], v[18:19], v[134:135], v[42:43]
	v_pk_fma_f32 v[16:17], v[16:17], v[132:133], v[40:41]
	global_store_dwordx4 v[66:67], v[8:11], off
	v_pk_fma_f32 v[6:7], v[6:7], v[134:135], v[58:59]
	v_pk_fma_f32 v[4:5], v[4:5], v[132:133], v[56:57]
	v_pk_fma_f32 v[10:11], v[14:15], v[138:139], v[54:55]
	v_pk_fma_f32 v[8:9], v[12:13], v[136:137], v[52:53]
	v_pk_fma_f32 v[2:3], v[2:3], v[130:131], v[62:63]
	v_pk_fma_f32 v[0:1], v[0:1], v[128:129], v[60:61]
	global_store_dwordx4 v[64:65], v[28:31], off
	global_store_dwordx4 v[64:65], v[24:27], off offset:64
	global_store_dwordx4 v[64:65], v[16:19], off offset:512
	global_store_dwordx4 v[66:67], v[8:11], off offset:64
	global_store_dwordx4 v[66:67], v[4:7], off offset:512
	global_store_dwordx4 v[66:67], v[0:3], off offset:576
	s_and_b64 vcc, exec, s[42:43]
	s_mov_b32 s8, s2
	s_mov_b32 s0, s26
	s_mov_b64 s[20:21], s[38:39]
	s_mov_b64 s[44:45], s[36:37]
	s_cbranch_vccz .LBB0_332
	s_waitcnt vmcnt(0)
	s_cmpk_gt_u32 s5, 0xff
	s_cbranch_scc1 .LBB0_339
	s_barrier

; #define PG8_STAGE_A(bufoff, ptr, half, rev) do { if (REVA && (rev)) { const char* _p = (ptr) - ((half) ? hstepA : 0); PG8_STAGE(bufoff, _p, voffAr); } else { const char* _p = (ptr) + ((half) ? hstepA : 0); PG8_STAGE(bufoff, _p, voffA); } } while (0)
; #define PG8_LDA(dst, b, h) do { _Pragma("unroll") for (int m = 0; m < 4; ++m) _Pragma("unroll") for (int k = 0; k < 2; ++k) dst[m][k] = *(const LAS bf16x8*)(lds + PG8_SA(b, h) + aoff + m * 2048 + k * 1024); } while (0)
; #define PG8_LDB(dst, b, h) do { _Pragma("unroll") for (int n = 0; n < 2; ++n) _Pragma("unroll") for (int k = 0; k < 2; ++k) dst[n][k] = *(const LAS bf16x8*)(lds + PG8_SB(b, h) + boff + n * 2048 + k * 1024); } while (0)
; #define PG8_SCHED __builtin_amdgcn_sched_barrier(0)
;     ...
;         const bool has_next = next_unit(ui + 1, nM, nN, MP, nxt, rot);
;         const char* nA = has_next ? nxt.a : cA; const char* nB = has_next ? nxt.b : cB; const char* nAr = has_next ? nxt.ar : cAr; const size_t nHb = has_next ? nxt.hb : cHb;
;         for (int t = 0; t < nt; t += 2) {
;             const bool last = (t == nt - 2);
;             const char* a1 = PG8_APTR(cA, cAr, t + 1); const bool r1 = REVA && ((t + 1) & 4);
;             const char* a2 = last ? nA : PG8_APTR(cA, cAr, t + 2); const bool r2 = REVA && !last && ((t + 2) & 4);
;             const char* a3 = last ? nA + kstep : PG8_APTR(cA, cAr, t + 3); const bool r3 = REVA && !last && ((t + 3) & 4);
;             const char* b2 = last ? nB : cB + (size_t)(t + 2) * kstep; const char* b3 = b2 + kstep; const size_t hb2 = last ? nHb : cHb;
;             PG8_LDB(B0, 0, 0); PG8_SCHED; PG8_LDA(At, 0, 0); PG8_STAGE_A(PG8_SA(1, 1), a1, 1, r1);
;     ...
; #pragma unroll
;         for (int a = 0; a < 2; ++a)
; #pragma unroll
;             for (int b = 0; b < 2; ++b)
; #pragma unroll
;                 for (int m = 0; m < 4; ++m)
; #pragma unroll
;                     for (int n = 0; n < 2; ++n) acc[a][b][m][n] = (f32x4){0.f, 0.f, 0.f, 0.f};
;         cur = nxt; cA = nA; cB = nB; cAr = nAr; cHb = nHb; ++ui;
.LBB0_521:
	s_add_u32 s6, s38, 0x80
	s_addc_u32 s7, s39, 0
	s_add_u32 s8, s44, 0x80080
	s_addc_u32 s9, s45, 0
	v_lshl_add_u64 v[144:145], s[8:9], 0, v[140:141]
	v_lshl_add_u64 v[146:147], s[8:9], 0, v[142:143]
	s_add_u32 s8, s0, 0x100
	v_mov_b32_e32 v0, 0
	s_addc_u32 s9, s1, 0
	s_mov_b32 s22, -2
	s_mov_b64 s[0:1], 0
	v_mov_b32_e32 v1, v0
	v_pk_mov_b32 v[2:3], v[0:1], v[0:1]
	v_pk_mov_b32 v[4:5], v[0:1], v[0:1]
	v_pk_mov_b32 v[6:7], v[0:1], v[0:1]
	v_pk_mov_b32 v[8:9], v[0:1], v[0:1]
	v_pk_mov_b32 v[10:11], v[0:1], v[0:1]
	v_pk_mov_b32 v[12:13], v[0:1], v[0:1]
	v_pk_mov_b32 v[14:15], v[0:1], v[0:1]
	v_pk_mov_b32 v[16:17], v[0:1], v[0:1]
	v_pk_mov_b32 v[18:19], v[0:1], v[0:1]
	v_pk_mov_b32 v[20:21], v[0:1], v[0:1]
	v_pk_mov_b32 v[22:23], v[0:1], v[0:1]
	v_pk_mov_b32 v[24:25], v[0:1], v[0:1]
	v_pk_mov_b32 v[26:27], v[0:1], v[0:1]
	v_pk_mov_b32 v[28:29], v[0:1], v[0:1]
	v_pk_mov_b32 v[30:31], v[0:1], v[0:1]
	v_pk_mov_b32 v[32:33], v[0:1], v[0:1]
	v_pk_mov_b32 v[34:35], v[0:1], v[0:1]
	v_pk_mov_b32 v[36:37], v[0:1], v[0:1]
	v_pk_mov_b32 v[38:39], v[0:1], v[0:1]
	v_pk_mov_b32 v[40:41], v[0:1], v[0:1]
	v_pk_mov_b32 v[42:43], v[0:1], v[0:1]
	v_pk_mov_b32 v[44:45], v[0:1], v[0:1]
	v_pk_mov_b32 v[46:47], v[0:1], v[0:1]
	v_pk_mov_b32 v[48:49], v[0:1], v[0:1]
	v_pk_mov_b32 v[50:51], v[0:1], v[0:1]
	v_pk_mov_b32 v[52:53], v[0:1], v[0:1]
	v_pk_mov_b32 v[54:55], v[0:1], v[0:1]
	v_pk_mov_b32 v[56:57], v[0:1], v[0:1]
	v_pk_mov_b32 v[58:59], v[0:1], v[0:1]
	v_pk_mov_b32 v[60:61], v[0:1], v[0:1]
	v_pk_mov_b32 v[62:63], v[0:1], v[0:1]
	v_pk_mov_b32 v[64:65], v[0:1], v[0:1]
	v_pk_mov_b32 v[66:67], v[0:1], v[0:1]
	v_pk_mov_b32 v[68:69], v[0:1], v[0:1]
	v_pk_mov_b32 v[70:71], v[0:1], v[0:1]
	v_pk_mov_b32 v[72:73], v[0:1], v[0:1]
	v_pk_mov_b32 v[74:75], v[0:1], v[0:1]
	v_pk_mov_b32 v[76:77], v[0:1], v[0:1]
	v_pk_mov_b32 v[78:79], v[0:1], v[0:1]
	v_pk_mov_b32 v[80:81], v[0:1], v[0:1]
	v_pk_mov_b32 v[82:83], v[0:1], v[0:1]
	v_pk_mov_b32 v[84:85], v[0:1], v[0:1]
	v_pk_mov_b32 v[86:87], v[0:1], v[0:1]
	v_pk_mov_b32 v[88:89], v[0:1], v[0:1]
	v_pk_mov_b32 v[90:91], v[0:1], v[0:1]
	v_pk_mov_b32 v[92:93], v[0:1], v[0:1]
	v_pk_mov_b32 v[94:95], v[0:1], v[0:1]
	v_pk_mov_b32 v[96:97], v[0:1], v[0:1]
	v_pk_mov_b32 v[98:99], v[0:1], v[0:1]
	v_pk_mov_b32 v[100:101], v[0:1], v[0:1]
	v_pk_mov_b32 v[102:103], v[0:1], v[0:1]
	v_pk_mov_b32 v[104:105], v[0:1], v[0:1]
	v_pk_mov_b32 v[106:107], v[0:1], v[0:1]
	v_pk_mov_b32 v[108:109], v[0:1], v[0:1]
	v_pk_mov_b32 v[110:111], v[0:1], v[0:1]
	v_pk_mov_b32 v[112:113], v[0:1], v[0:1]
	v_pk_mov_b32 v[114:115], v[0:1], v[0:1]
	v_pk_mov_b32 v[116:117], v[0:1], v[0:1]
	v_pk_mov_b32 v[118:119], v[0:1], v[0:1]
	v_pk_mov_b32 v[120:121], v[0:1], v[0:1]
	v_pk_mov_b32 v[122:123], v[0:1], v[0:1]
	v_pk_mov_b32 v[124:125], v[0:1], v[0:1]
	v_pk_mov_b32 v[126:127], v[0:1], v[0:1]
	v_add_u32_e32 v160, 0x10000, v139
	ds_read_b128 v[156:159], v160
	ds_read_b128 v[168:171], v160 offset:1024
	ds_read_b128 v[172:175], v160 offset:2048
	ds_read_b128 v[176:179], v160 offset:3072
	s_branch .LBB0_522

; #define PG8_STAGE(bufoff, gbase, voff) do { _Pragma("unroll") for (int _i = 0; _i < 2; ++_i) \
;         __builtin_amdgcn_global_load_lds((const unsigned*)((const char*)(gbase) + (voff)[_i]), (LAS unsigned*)(lds + (bufoff) + ldsw + _i * 8192), 16, 0, 0); } while (0)
; #define PG8_STAGE_A(bufoff, ptr, half, rev) do { if (REVA && (rev)) { const char* _p = (ptr) - ((half) ? hstepA : 0); PG8_STAGE(bufoff, _p, voffAr); } else { const char* _p = (ptr) + ((half) ? hstepA : 0); PG8_STAGE(bufoff, _p, voffA); } } while (0)
; #define PG8_LDA(dst, b, h) do { _Pragma("unroll") for (int m = 0; m < 4; ++m) _Pragma("unroll") for (int k = 0; k < 2; ++k) dst[m][k] = *(const LAS bf16x8*)(lds + PG8_SA(b, h) + aoff + m * 2048 + k * 1024); } while (0)
; #define PG8_LDB(dst, b, h) do { _Pragma("unroll") for (int n = 0; n < 2; ++n) _Pragma("unroll") for (int k = 0; k < 2; ++k) dst[n][k] = *(const LAS bf16x8*)(lds + PG8_SB(b, h) + boff + n * 2048 + k * 1024); } while (0)
; #define PG8_WAIT_V(n) asm volatile("s_waitcnt vmcnt(" #n ")" ::: "memory")
; #define PG8_WAIT_L(n) asm volatile("s_waitcnt lgkmcnt(" #n ")" ::: "memory")
; #define PG8_BAR __builtin_amdgcn_s_barrier()
;     ...
;         for (int t = 0; t < nt; t += 2) {
;             const bool last = (t == nt - 2);
;             const char* a1 = PG8_APTR(cA, cAr, t + 1); const bool r1 = REVA && ((t + 1) & 4);
;             const char* a2 = last ? nA : PG8_APTR(cA, cAr, t + 2); const bool r2 = REVA && !last && ((t + 2) & 4);
;             const char* a3 = last ? nA + kstep : PG8_APTR(cA, cAr, t + 3); const bool r3 = REVA && !last && ((t + 3) & 4);
;             const char* b2 = last ? nB : cB + (size_t)(t + 2) * kstep; const char* b3 = b2 + kstep; const size_t hb2 = last ? nHb : cHb;
;             PG8_LDB(B0, 0, 0); PG8_SCHED; PG8_LDA(At, 0, 0); PG8_STAGE_A(PG8_SA(1, 1), a1, 1, r1);
;             PG8_WAIT_L(8); PG8_BAR; PG8_WAIT_L(0); PG8_MMA(0, 0, At, B0); PG8_BAR; PG8_SCHED;
;             PG8_LDB(B1, 0, 1); PG8_STAGE(PG8_SB(0, 0), b2, voffB);
;             PG8_BAR; PG8_WAIT_L(0); PG8_MMA(0, 1, At, B1); PG8_BAR;
;             PG8_LDA(At, 0, 1); PG8_STAGE_A(PG8_SA(0, 0), a2, 0, r2);
;             PG8_BAR; PG8_WAIT_L(0); PG8_MMA(1, 0, At, B0); PG8_BAR; PG8_SCHED;
;             PG8_STAGE(PG8_SB(0, 1), b2 + hb2, voffB);
;             PG8_WAIT_V(6); PG8_BAR; PG8_MMA(1, 1, At, B1); PG8_BAR;
.LBB0_522:
	s_add_u32 s10, s44, s0
	s_addc_u32 s11, s45, s1
	s_add_u32 s14, s10, 0x100
	s_addc_u32 s15, s11, 0
	s_add_u32 s10, s10, 0x180
	s_addc_u32 s11, s11, 0
	s_add_u32 s16, s8, s0
	s_addc_u32 s17, s9, s1
	s_add_i32 s27, 0, 0x10000
	s_cmpk_eq_i32 s0, 0xf00
	s_cselect_b32 s21, s47, s17
	s_cselect_b32 s20, s46, s16
	s_cselect_b32 s17, s39, s15
	s_cselect_b32 s16, s38, s14
	s_cselect_b32 s90, s37, s3
	s_cselect_b32 s91, s36, s2
	s_cselect_b32 s15, s7, s11
	s_cselect_b32 s14, s6, s10
	v_lshl_add_u64 v[184:185], v[144:145], 0, s[0:1]
	s_add_i32 m0, s66, 0xc000
	ds_read_b128 v[180:183], v155
	ds_read_b128 v[204:207], v155 offset:1024
	ds_read_b128 v[208:211], v155 offset:2048
	ds_read_b128 v[212:215], v155 offset:3072
	ds_read_b128 v[216:219], v155 offset:4096
	ds_read_b128 v[220:223], v155 offset:5120
	ds_read_b128 v[224:227], v155 offset:6144
	ds_read_b128 v[228:231], v155 offset:7168
	global_load_lds_dwordx4 v[184:185], off
	v_lshl_add_u64 v[184:185], v[146:147], 0, s[0:1]
	s_add_i32 m0, s66, 0xe000
	s_nop 0
	global_load_lds_dwordx4 v[184:185], off
	s_waitcnt lgkmcnt(8)
	s_waitcnt vmcnt(10)
	s_barrier
	s_waitcnt lgkmcnt(0)
	v_mfma_f32_16x16x32_bf16 v[124:127], v[156:159], v[180:183], v[124:127]
	v_mfma_f32_16x16x32_bf16 v[120:123], v[172:175], v[180:183], v[120:123]
	v_mfma_f32_16x16x32_bf16 v[108:111], v[156:159], v[208:211], v[108:111]
	v_mfma_f32_16x16x32_bf16 v[104:107], v[172:175], v[208:211], v[104:107]
	v_mfma_f32_16x16x32_bf16 v[92:95], v[156:159], v[216:219], v[92:95]
	v_mfma_f32_16x16x32_bf16 v[88:91], v[172:175], v[216:219], v[88:91]
	v_mfma_f32_16x16x32_bf16 v[76:79], v[156:159], v[224:227], v[76:79]
	v_mfma_f32_16x16x32_bf16 v[72:75], v[172:175], v[224:227], v[72:75]
	v_mfma_f32_16x16x32_bf16 v[124:127], v[168:171], v[204:207], v[124:127]
	v_mfma_f32_16x16x32_bf16 v[120:123], v[176:179], v[204:207], v[120:123]
	v_mfma_f32_16x16x32_bf16 v[108:111], v[168:171], v[212:215], v[108:111]
	v_mfma_f32_16x16x32_bf16 v[104:107], v[176:179], v[212:215], v[104:107]
	v_mfma_f32_16x16x32_bf16 v[92:95], v[168:171], v[220:223], v[92:95]
	v_mfma_f32_16x16x32_bf16 v[88:91], v[176:179], v[220:223], v[88:91]
	v_mfma_f32_16x16x32_bf16 v[76:79], v[168:171], v[228:231], v[76:79]
	v_mfma_f32_16x16x32_bf16 v[72:75], v[176:179], v[228:231], v[72:75]
	s_barrier
	s_add_i32 s10, 0, 0x14000
	s_add_i32 s11, s27, s53
	v_add_u32_e32 v160, s10, v139
	v_lshl_add_u64 v[184:185], s[20:21], 0, v[130:131]
	s_mov_b32 m0, s11
	ds_read_b128 v[232:235], v160
	ds_read_b128 v[236:239], v160 offset:1024
	ds_read_b128 v[240:243], v160 offset:2048
	ds_read_b128 v[244:247], v160 offset:3072
	global_load_lds_dwordx4 v[184:185], off
	v_lshl_add_u64 v[248:249], s[20:21], 0, v[134:135]
	s_add_i32 m0, s11, 0x2000
	s_nop 0
	global_load_lds_dwordx4 v[248:249], off
	s_waitcnt vmcnt(10)
	s_barrier
	s_waitcnt lgkmcnt(0)
	v_mfma_f32_16x16x32_bf16 v[116:119], v[232:235], v[180:183], v[116:119]
	v_mfma_f32_16x16x32_bf16 v[112:115], v[240:243], v[180:183], v[112:115]
	v_mfma_f32_16x16x32_bf16 v[100:103], v[232:235], v[208:211], v[100:103]
	v_mfma_f32_16x16x32_bf16 v[96:99], v[240:243], v[208:211], v[96:99]
	v_mfma_f32_16x16x32_bf16 v[84:87], v[232:235], v[216:219], v[84:87]
	v_mfma_f32_16x16x32_bf16 v[80:83], v[240:243], v[216:219], v[80:83]
	v_mfma_f32_16x16x32_bf16 v[68:71], v[232:235], v[224:227], v[68:71]
	v_mfma_f32_16x16x32_bf16 v[64:67], v[240:243], v[224:227], v[64:67]
	v_mfma_f32_16x16x32_bf16 v[116:119], v[236:239], v[204:207], v[116:119]
	v_mfma_f32_16x16x32_bf16 v[112:115], v[244:247], v[204:207], v[112:115]
	v_mfma_f32_16x16x32_bf16 v[100:103], v[236:239], v[212:215], v[100:103]
	v_mfma_f32_16x16x32_bf16 v[96:99], v[244:247], v[212:215], v[96:99]
	v_mfma_f32_16x16x32_bf16 v[84:87], v[236:239], v[220:223], v[84:87]
	v_mfma_f32_16x16x32_bf16 v[80:83], v[244:247], v[220:223], v[80:83]
	v_mfma_f32_16x16x32_bf16 v[68:71], v[236:239], v[228:231], v[68:71]
	v_mfma_f32_16x16x32_bf16 v[64:67], v[244:247], v[228:231], v[64:67]
	s_mov_b32 m0, s66
	v_lshl_add_u64 v[250:251], s[16:17], 0, v[128:129]
	s_barrier
	ds_read_b128 v[180:183], v155 offset:16384
	ds_read_b128 v[204:207], v155 offset:17408
	ds_read_b128 v[208:211], v155 offset:18432
	ds_read_b128 v[212:215], v155 offset:19456
	ds_read_b128 v[216:219], v155 offset:20480
	ds_read_b128 v[220:223], v155 offset:21504
	ds_read_b128 v[224:227], v155 offset:22528
	ds_read_b128 v[228:231], v155 offset:23552
	global_load_lds_dwordx4 v[250:251], off
	v_lshl_add_u64 v[250:251], s[16:17], 0, v[132:133]
	s_mov_b32 m0, s67
	s_nop 0
	global_load_lds_dwordx4 v[250:251], off
	s_waitcnt vmcnt(10)
	s_barrier
	s_waitcnt lgkmcnt(0)
	v_mfma_f32_16x16x32_bf16 v[60:63], v[156:159], v[180:183], v[60:63]
	v_mfma_f32_16x16x32_bf16 v[56:59], v[172:175], v[180:183], v[56:59]
	v_mfma_f32_16x16x32_bf16 v[44:47], v[156:159], v[208:211], v[44:47]
	v_mfma_f32_16x16x32_bf16 v[40:43], v[172:175], v[208:211], v[40:43]
	v_mfma_f32_16x16x32_bf16 v[28:31], v[156:159], v[216:219], v[28:31]
	v_mfma_f32_16x16x32_bf16 v[24:27], v[172:175], v[216:219], v[24:27]
	v_mfma_f32_16x16x32_bf16 v[12:15], v[156:159], v[224:227], v[12:15]
	v_mfma_f32_16x16x32_bf16 v[8:11], v[172:175], v[224:227], v[8:11]
	v_mfma_f32_16x16x32_bf16 v[60:63], v[168:171], v[204:207], v[60:63]
	v_mfma_f32_16x16x32_bf16 v[56:59], v[176:179], v[204:207], v[56:59]
	v_mfma_f32_16x16x32_bf16 v[44:47], v[168:171], v[212:215], v[44:47]
	v_mfma_f32_16x16x32_bf16 v[40:43], v[176:179], v[212:215], v[40:43]
	v_mfma_f32_16x16x32_bf16 v[28:31], v[168:171], v[220:223], v[28:31]
	v_mfma_f32_16x16x32_bf16 v[24:27], v[176:179], v[220:223], v[24:27]
	v_mfma_f32_16x16x32_bf16 v[12:15], v[168:171], v[228:231], v[12:15]
	v_mfma_f32_16x16x32_bf16 v[8:11], v[176:179], v[228:231], v[8:11]
	s_barrier
; #define PG8_STAGE(bufoff, gbase, voff) do { _Pragma("unroll") for (int _i = 0; _i < 2; ++_i) \
;         __builtin_amdgcn_global_load_lds((const unsigned*)((const char*)(gbase) + (voff)[_i]), (LAS unsigned*)(lds + (bufoff) + ldsw + _i * 8192), 16, 0, 0); } while (0)
; #define PG8_STAGE_A(bufoff, ptr, half, rev) do { if (REVA && (rev)) { const char* _p = (ptr) - ((half) ? hstepA : 0); PG8_STAGE(bufoff, _p, voffAr); } else { const char* _p = (ptr) + ((half) ? hstepA : 0); PG8_STAGE(bufoff, _p, voffA); } } while (0)
; #define PG8_LDA(dst, b, h) do { _Pragma("unroll") for (int m = 0; m < 4; ++m) _Pragma("unroll") for (int k = 0; k < 2; ++k) dst[m][k] = *(const LAS bf16x8*)(lds + PG8_SA(b, h) + aoff + m * 2048 + k * 1024); } while (0)
; #define PG8_LDB(dst, b, h) do { _Pragma("unroll") for (int n = 0; n < 2; ++n) _Pragma("unroll") for (int k = 0; k < 2; ++k) dst[n][k] = *(const LAS bf16x8*)(lds + PG8_SB(b, h) + boff + n * 2048 + k * 1024); } while (0)
; #define PG8_MMA(ai, bj, At, Bt) do { __builtin_amdgcn_s_setprio(1); _Pragma("unroll") for (int m = 0; m < 4; ++m) _Pragma("unroll") for (int n = 0; n < 2; ++n) _Pragma("unroll") for (int k = 0; k < 2; ++k) \
;         acc[ai][bj][m][n] = __builtin_amdgcn_mfma_f32_16x16x32_bf16(Bt[n][k], At[m][k], acc[ai][bj][m][n], 0, 0, 0); __builtin_amdgcn_s_setprio(0); } while (0)
; #define PG8_WAIT_V(n) asm volatile("s_waitcnt vmcnt(" #n ")" ::: "memory")
; #define PG8_WAIT_L(n) asm volatile("s_waitcnt lgkmcnt(" #n ")" ::: "memory")
; #define PG8_BAR __builtin_amdgcn_s_barrier()
; #define PG8_SCHED __builtin_amdgcn_sched_barrier(0)
;     ...
;             PG8_STAGE(PG8_SB(0, 1), b2 + hb2, voffB);
;             PG8_WAIT_V(6); PG8_BAR; PG8_MMA(1, 1, At, B1); PG8_BAR;
;             PG8_LDB(B0, 1, 0); PG8_SCHED; PG8_LDA(At, 1, 0); PG8_STAGE_A(PG8_SA(0, 1), a2, 1, r2);
;             PG8_WAIT_L(8); PG8_BAR; PG8_WAIT_L(0); PG8_MMA(0, 0, At, B0); PG8_BAR; PG8_SCHED;
;             PG8_LDB(B1, 1, 1); PG8_STAGE(PG8_SB(1, 0), b3, voffB);
;             PG8_BAR; PG8_WAIT_L(0); PG8_MMA(0, 1, At, B1); PG8_BAR;
;             PG8_LDA(At, 1, 1); PG8_STAGE_A(PG8_SA(1, 0), a3, 0, r3);
;             PG8_BAR; PG8_WAIT_L(0); PG8_MMA(1, 0, At, B0); PG8_BAR; PG8_SCHED;
	s_add_u32 s20, s20, s91
	s_addc_u32 s21, s21, s90
	s_add_i32 s10, s10, s53
	v_lshl_add_u64 v[250:251], s[20:21], 0, v[130:131]
	s_mov_b32 m0, s10
	v_lshl_add_u64 v[190:191], s[20:21], 0, v[134:135]
	global_load_lds_dwordx4 v[250:251], off
	s_add_i32 m0, s10, 0x2000
	s_nop 0
	global_load_lds_dwordx4 v[190:191], off
	v_add_u32_e32 v160, 0x18000, v139
	ds_read_b128 v[156:159], v160
	ds_read_b128 v[168:171], v160 offset:1024
	ds_read_b128 v[172:175], v160 offset:2048
	ds_read_b128 v[176:179], v160 offset:3072
	s_waitcnt vmcnt(10)
	s_barrier
	v_mfma_f32_16x16x32_bf16 v[52:55], v[232:235], v[180:183], v[52:55]
	v_mfma_f32_16x16x32_bf16 v[48:51], v[240:243], v[180:183], v[48:51]
	v_mfma_f32_16x16x32_bf16 v[36:39], v[232:235], v[208:211], v[36:39]
	v_mfma_f32_16x16x32_bf16 v[32:35], v[240:243], v[208:211], v[32:35]
	v_mfma_f32_16x16x32_bf16 v[20:23], v[232:235], v[216:219], v[20:23]
	v_mfma_f32_16x16x32_bf16 v[16:19], v[240:243], v[216:219], v[16:19]
	v_mfma_f32_16x16x32_bf16 v[4:7], v[232:235], v[224:227], v[4:7]
	v_mfma_f32_16x16x32_bf16 v[0:3], v[240:243], v[224:227], v[0:3]
	v_mfma_f32_16x16x32_bf16 v[52:55], v[236:239], v[204:207], v[52:55]
	v_mfma_f32_16x16x32_bf16 v[48:51], v[244:247], v[204:207], v[48:51]
	v_mfma_f32_16x16x32_bf16 v[36:39], v[236:239], v[212:215], v[36:39]
	v_mfma_f32_16x16x32_bf16 v[32:35], v[244:247], v[212:215], v[32:35]
	v_mfma_f32_16x16x32_bf16 v[20:23], v[236:239], v[220:223], v[20:23]
	v_mfma_f32_16x16x32_bf16 v[16:19], v[244:247], v[220:223], v[16:19]
	v_mfma_f32_16x16x32_bf16 v[4:7], v[236:239], v[228:231], v[4:7]
	v_mfma_f32_16x16x32_bf16 v[0:3], v[244:247], v[228:231], v[0:3]
	s_add_i32 s10, 0, 0x18000
	s_barrier
	s_add_u32 s16, s16, 0x80000
	s_addc_u32 s17, s17, 0
	s_mov_b32 m0, s68
	v_lshl_add_u64 v[232:233], s[16:17], 0, v[128:129]
	ds_read_b128 v[180:183], v155 offset:32768
	ds_read_b128 v[204:207], v155 offset:33792
	ds_read_b128 v[208:211], v155 offset:34816
	ds_read_b128 v[212:215], v155 offset:35840
	ds_read_b128 v[216:219], v155 offset:36864
	ds_read_b128 v[220:223], v155 offset:37888
	ds_read_b128 v[224:227], v155 offset:38912
	ds_read_b128 v[228:231], v155 offset:39936
	global_load_lds_dwordx4 v[232:233], off
	v_lshl_add_u64 v[232:233], s[16:17], 0, v[132:133]
	s_mov_b32 m0, s69
	s_nop 0
	global_load_lds_dwordx4 v[232:233], off
	s_waitcnt lgkmcnt(8)
	s_waitcnt vmcnt(10)
	s_barrier
	s_waitcnt lgkmcnt(0)
	v_mfma_f32_16x16x32_bf16 v[124:127], v[156:159], v[180:183], v[124:127]
	v_mfma_f32_16x16x32_bf16 v[120:123], v[172:175], v[180:183], v[120:123]
	v_mfma_f32_16x16x32_bf16 v[108:111], v[156:159], v[208:211], v[108:111]
	v_mfma_f32_16x16x32_bf16 v[104:107], v[172:175], v[208:211], v[104:107]
	v_mfma_f32_16x16x32_bf16 v[92:95], v[156:159], v[216:219], v[92:95]
	v_mfma_f32_16x16x32_bf16 v[88:91], v[172:175], v[216:219], v[88:91]
	v_mfma_f32_16x16x32_bf16 v[76:79], v[156:159], v[224:227], v[76:79]
	v_mfma_f32_16x16x32_bf16 v[72:75], v[172:175], v[224:227], v[72:75]
	v_mfma_f32_16x16x32_bf16 v[124:127], v[168:171], v[204:207], v[124:127]
	v_mfma_f32_16x16x32_bf16 v[120:123], v[176:179], v[204:207], v[120:123]
	v_mfma_f32_16x16x32_bf16 v[108:111], v[168:171], v[212:215], v[108:111]
	v_mfma_f32_16x16x32_bf16 v[104:107], v[176:179], v[212:215], v[104:107]
	v_mfma_f32_16x16x32_bf16 v[92:95], v[168:171], v[220:223], v[92:95]
	v_mfma_f32_16x16x32_bf16 v[88:91], v[176:179], v[220:223], v[88:91]
	v_mfma_f32_16x16x32_bf16 v[76:79], v[168:171], v[228:231], v[76:79]
	v_mfma_f32_16x16x32_bf16 v[72:75], v[176:179], v[228:231], v[72:75]
	s_barrier
	s_add_i32 s11, 0, 0x1c000
	s_add_i32 s10, s10, s53
	v_add_u32_e32 v160, s11, v139
	v_lshl_add_u64 v[184:185], v[184:185], 0, s[28:29]
	s_mov_b32 m0, s10
	ds_read_b128 v[232:235], v160
	ds_read_b128 v[236:239], v160 offset:1024
	ds_read_b128 v[240:243], v160 offset:2048
	ds_read_b128 v[244:247], v160 offset:3072
	global_load_lds_dwordx4 v[184:185], off
	v_lshl_add_u64 v[184:185], v[248:249], 0, s[28:29]
	s_add_i32 m0, s10, 0x2000
	s_nop 0
	global_load_lds_dwordx4 v[184:185], off
	s_waitcnt vmcnt(10)
	s_barrier
	s_waitcnt lgkmcnt(0)
	v_mfma_f32_16x16x32_bf16 v[116:119], v[232:235], v[180:183], v[116:119]
	v_mfma_f32_16x16x32_bf16 v[112:115], v[240:243], v[180:183], v[112:115]
	v_mfma_f32_16x16x32_bf16 v[100:103], v[232:235], v[208:211], v[100:103]
	v_mfma_f32_16x16x32_bf16 v[96:99], v[240:243], v[208:211], v[96:99]
	v_mfma_f32_16x16x32_bf16 v[84:87], v[232:235], v[216:219], v[84:87]
	v_mfma_f32_16x16x32_bf16 v[80:83], v[240:243], v[216:219], v[80:83]
	v_mfma_f32_16x16x32_bf16 v[68:71], v[232:235], v[224:227], v[68:71]
	v_mfma_f32_16x16x32_bf16 v[64:67], v[240:243], v[224:227], v[64:67]
	v_mfma_f32_16x16x32_bf16 v[116:119], v[236:239], v[204:207], v[116:119]
	v_mfma_f32_16x16x32_bf16 v[112:115], v[244:247], v[204:207], v[112:115]
	v_mfma_f32_16x16x32_bf16 v[100:103], v[236:239], v[212:215], v[100:103]
	v_mfma_f32_16x16x32_bf16 v[96:99], v[244:247], v[212:215], v[96:99]
	v_mfma_f32_16x16x32_bf16 v[84:87], v[236:239], v[220:223], v[84:87]
	v_mfma_f32_16x16x32_bf16 v[80:83], v[244:247], v[220:223], v[80:83]
	v_mfma_f32_16x16x32_bf16 v[68:71], v[236:239], v[228:231], v[68:71]
	v_mfma_f32_16x16x32_bf16 v[64:67], v[244:247], v[228:231], v[64:67]
	s_mov_b32 m0, s70
	v_lshl_add_u64 v[184:185], s[14:15], 0, v[128:129]
	s_barrier
; __device__ __forceinline__ unsigned cvt_pk_bf16(float lo, float hi) { unsigned r; asm volatile("v_cvt_pk_bf16_f32 %0, %1, %2" : "=v"(r) : "v"(lo), "v"(hi)); return r; }
; #define PG8_STAGE(bufoff, gbase, voff) do { _Pragma("unroll") for (int _i = 0; _i < 2; ++_i) \
;         __builtin_amdgcn_global_load_lds((const unsigned*)((const char*)(gbase) + (voff)[_i]), (LAS unsigned*)(lds + (bufoff) + ldsw + _i * 8192), 16, 0, 0); } while (0)
; #define PG8_WAIT_V(n) asm volatile("s_waitcnt vmcnt(" #n ")" ::: "memory")
; #define PG8_WAIT_L(n) asm volatile("s_waitcnt lgkmcnt(" #n ")" ::: "memory")
; #define PG8_BAR __builtin_amdgcn_s_barrier()
; #define PG8_SCHED __builtin_amdgcn_sched_barrier(0)
;     ...
;             PG8_BAR; PG8_WAIT_L(0); PG8_MMA(1, 0, At, B0); PG8_BAR; PG8_SCHED;
;             PG8_STAGE(PG8_SB(1, 1), b3 + hb2, voffB);
;             PG8_WAIT_V(6); PG8_BAR; PG8_MMA(1, 1, At, B1); PG8_BAR;
;     __device__ __forceinline__ void generic(const f32x4 (&acc)[2][2][4][2], const Unit& u, int wr, int wc, int fr, int fq) const {
;     ...
;                     if (MODE == 4) {
;                         if (u.pm < 8 && u.pn < 128) {
;                             if (bj == 0) {
;                                 const f32x4 a0 = acc[ai][0][m][0], a1 = acc[ai][0][m][1], b0 = acc[ai][1][m][0], b1 = acc[ai][1][m][1];
;                                 const f32x4 e0 = a0 + b0, e1 = a1 + b1, o0 = a0 - b0, o1 = a1 - b1;
;                                 bf16_t* p = O + (size_t)(u.pm * BM + rt) * T + (u.pn >> 4) * 4096 + (u.pn & 15) * 128 + wc * 32 + 8 * fq;
;                                 u32x4 w; w.x = cvt_pk_bf16(e0[0], e0[1]); w.y = cvt_pk_bf16(e0[2], e0[3]); w.z = cvt_pk_bf16(e1[0], e1[1]); w.w = cvt_pk_bf16(e1[2], e1[3]);
;                                 *(u32x4*)p = w;
;                                 w.x = cvt_pk_bf16(o0[0], o0[1]); w.y = cvt_pk_bf16(o0[2], o0[3]); w.z = cvt_pk_bf16(o1[0], o1[1]); w.w = cvt_pk_bf16(o1[2], o1[3]);
;                                 *(u32x4*)(p + 2048) = w;
;                             }
;                         } else {
;                             u32x4 w; w.x = cvt_pk_bf16(v0[0], v0[1]); w.y = cvt_pk_bf16(v0[2], v0[3]); w.z = cvt_pk_bf16(v1[0], v1[1]); w.w = cvt_pk_bf16(v1[2], v1[3]);
;                             *(u32x4*)(O + (size_t)(u.pm * BM + rt) * T + u.pn * BM + ct) = w;
	ds_read_b128 v[180:183], v155 offset:49152
	ds_read_b128 v[204:207], v155 offset:50176
	ds_read_b128 v[208:211], v155 offset:51200
	ds_read_b128 v[212:215], v155 offset:52224
	ds_read_b128 v[216:219], v155 offset:53248
	ds_read_b128 v[220:223], v155 offset:54272
	ds_read_b128 v[224:227], v155 offset:55296
	ds_read_b128 v[228:231], v155 offset:56320
	global_load_lds_dwordx4 v[184:185], off
	v_lshl_add_u64 v[184:185], s[14:15], 0, v[132:133]
	s_mov_b32 m0, s71
	s_nop 0
	global_load_lds_dwordx4 v[184:185], off
	s_waitcnt vmcnt(10)
	s_barrier
	s_waitcnt lgkmcnt(0)
	v_mfma_f32_16x16x32_bf16 v[60:63], v[156:159], v[180:183], v[60:63]
	v_mfma_f32_16x16x32_bf16 v[56:59], v[172:175], v[180:183], v[56:59]
	v_mfma_f32_16x16x32_bf16 v[44:47], v[156:159], v[208:211], v[44:47]
	v_mfma_f32_16x16x32_bf16 v[40:43], v[172:175], v[208:211], v[40:43]
	v_mfma_f32_16x16x32_bf16 v[28:31], v[156:159], v[216:219], v[28:31]
	v_mfma_f32_16x16x32_bf16 v[24:27], v[172:175], v[216:219], v[24:27]
	v_mfma_f32_16x16x32_bf16 v[12:15], v[156:159], v[224:227], v[12:15]
	v_mfma_f32_16x16x32_bf16 v[8:11], v[172:175], v[224:227], v[8:11]
	v_mfma_f32_16x16x32_bf16 v[60:63], v[168:171], v[204:207], v[60:63]
	v_mfma_f32_16x16x32_bf16 v[56:59], v[176:179], v[204:207], v[56:59]
	v_mfma_f32_16x16x32_bf16 v[44:47], v[168:171], v[212:215], v[44:47]
	v_mfma_f32_16x16x32_bf16 v[40:43], v[176:179], v[212:215], v[40:43]
	v_mfma_f32_16x16x32_bf16 v[28:31], v[168:171], v[220:223], v[28:31]
	v_mfma_f32_16x16x32_bf16 v[24:27], v[176:179], v[220:223], v[24:27]
	v_mfma_f32_16x16x32_bf16 v[12:15], v[168:171], v[228:231], v[12:15]
	v_mfma_f32_16x16x32_bf16 v[8:11], v[176:179], v[228:231], v[8:11]
	s_barrier
	s_add_i32 s10, s11, s53
	v_lshl_add_u64 v[156:157], v[250:251], 0, s[28:29]
	s_mov_b32 m0, s10
	s_nop 0
	global_load_lds_dwordx4 v[156:157], off
	v_lshl_add_u64 v[156:157], v[190:191], 0, s[28:29]
	s_add_i32 m0, s10, 0x2000
	s_nop 0
	global_load_lds_dwordx4 v[156:157], off
	v_add_u32_e32 v160, 0x10000, v139
	ds_read_b128 v[156:159], v160
	ds_read_b128 v[168:171], v160 offset:1024
	ds_read_b128 v[172:175], v160 offset:2048
	ds_read_b128 v[176:179], v160 offset:3072
	s_waitcnt vmcnt(10)
	s_barrier
	v_mfma_f32_16x16x32_bf16 v[52:55], v[232:235], v[180:183], v[52:55]
	v_mfma_f32_16x16x32_bf16 v[48:51], v[240:243], v[180:183], v[48:51]
	v_mfma_f32_16x16x32_bf16 v[36:39], v[232:235], v[208:211], v[36:39]
	v_mfma_f32_16x16x32_bf16 v[32:35], v[240:243], v[208:211], v[32:35]
	v_mfma_f32_16x16x32_bf16 v[20:23], v[232:235], v[216:219], v[20:23]
	v_mfma_f32_16x16x32_bf16 v[16:19], v[240:243], v[216:219], v[16:19]
	v_mfma_f32_16x16x32_bf16 v[4:7], v[232:235], v[224:227], v[4:7]
	v_mfma_f32_16x16x32_bf16 v[0:3], v[240:243], v[224:227], v[0:3]
	v_mfma_f32_16x16x32_bf16 v[52:55], v[236:239], v[204:207], v[52:55]
	v_mfma_f32_16x16x32_bf16 v[48:51], v[244:247], v[204:207], v[48:51]
	v_mfma_f32_16x16x32_bf16 v[36:39], v[236:239], v[212:215], v[36:39]
	v_mfma_f32_16x16x32_bf16 v[32:35], v[244:247], v[212:215], v[32:35]
	v_mfma_f32_16x16x32_bf16 v[20:23], v[236:239], v[220:223], v[20:23]
	v_mfma_f32_16x16x32_bf16 v[16:19], v[244:247], v[220:223], v[16:19]
	v_mfma_f32_16x16x32_bf16 v[4:7], v[236:239], v[228:231], v[4:7]
	v_mfma_f32_16x16x32_bf16 v[0:3], v[244:247], v[228:231], v[0:3]
	s_add_i32 s22, s22, 2
	s_add_u32 s0, s0, 0x100
	s_addc_u32 s1, s1, 0
	s_cmp_gt_u32 s22, 29
	s_cbranch_scc0 .Lrot_522_bar
	s_barrier
	s_waitcnt lgkmcnt(0)
	s_cmp_gt_i32 s89, 7
	s_cselect_b64 s[0:1], -1, 0
	s_cmpk_gt_i32 s5, 0x7f
	s_cselect_b64 s[2:3], -1, 0
	s_or_b64 s[0:1], s[0:1], s[2:3]
	s_mov_b64 s[2:3], -1
	s_and_b64 vcc, exec, s[0:1]
	v_lshl_add_u32 v146, s89, 8, v137
	v_lshlrev_b32_e32 v144, 1, v138
	s_cbranch_vccz .LBB0_525
	v_mov_b64_e32 v[168:169], s[24:25]
	v_mad_i64_i32 v[168:169], s[2:3], v146, s80, v[168:169]
	s_lshl_b32 s2, s5, 8
	s_ashr_i32 s3, s2, 31
	v_lshl_add_u64 v[168:169], s[2:3], 1, v[168:169]
	v_mov_b32_e32 v145, v161
	v_lshl_add_u64 v[168:169], v[168:169], 0, v[144:145]
	v_cvt_pk_bf16_f32 v156, v124, v125
	v_cvt_pk_bf16_f32 v157, v126, v127
	v_cvt_pk_bf16_f32 v158, v120, v121
	v_cvt_pk_bf16_f32 v159, v122, v123
	global_store_dwordx4 v[168:169], v[156:159], off
	s_mov_b64 s[2:3], 0

; #define PG8_STAGE_A(bufoff, ptr, half, rev) do { if (REVA && (rev)) { const char* _p = (ptr) - ((half) ? hstepA : 0); PG8_STAGE(bufoff, _p, voffAr); } else { const char* _p = (ptr) + ((half) ? hstepA : 0); PG8_STAGE(bufoff, _p, voffA); } } while (0)
; #define PG8_LDA(dst, b, h) do { _Pragma("unroll") for (int m = 0; m < 4; ++m) _Pragma("unroll") for (int k = 0; k < 2; ++k) dst[m][k] = *(const LAS bf16x8*)(lds + PG8_SA(b, h) + aoff + m * 2048 + k * 1024); } while (0)
; #define PG8_LDB(dst, b, h) do { _Pragma("unroll") for (int n = 0; n < 2; ++n) _Pragma("unroll") for (int k = 0; k < 2; ++k) dst[n][k] = *(const LAS bf16x8*)(lds + PG8_SB(b, h) + boff + n * 2048 + k * 1024); } while (0)
; #define PG8_SCHED __builtin_amdgcn_sched_barrier(0)
;     ...
;         const bool has_next = next_unit(ui + 1, nM, nN, MP, nxt, rot);
;         const char* nA = has_next ? nxt.a : cA; const char* nB = has_next ? nxt.b : cB; const char* nAr = has_next ? nxt.ar : cAr; const size_t nHb = has_next ? nxt.hb : cHb;
;         for (int t = 0; t < nt; t += 2) {
;             const bool last = (t == nt - 2);
;             const char* a1 = PG8_APTR(cA, cAr, t + 1); const bool r1 = REVA && ((t + 1) & 4);
;             const char* a2 = last ? nA : PG8_APTR(cA, cAr, t + 2); const bool r2 = REVA && !last && ((t + 2) & 4);
;             const char* a3 = last ? nA + kstep : PG8_APTR(cA, cAr, t + 3); const bool r3 = REVA && !last && ((t + 3) & 4);
;             const char* b2 = last ? nB : cB + (size_t)(t + 2) * kstep; const char* b3 = b2 + kstep; const size_t hb2 = last ? nHb : cHb;
;             PG8_LDB(B0, 0, 0); PG8_SCHED; PG8_LDA(At, 0, 0); PG8_STAGE_A(PG8_SA(1, 1), a1, 1, r1);
;     ...
; #pragma unroll
;         for (int a = 0; a < 2; ++a)
; #pragma unroll
;             for (int b = 0; b < 2; ++b)
; #pragma unroll
;                 for (int m = 0; m < 4; ++m)
; #pragma unroll
;                     for (int n = 0; n < 2; ++n) acc[a][b][m][n] = (f32x4){0.f, 0.f, 0.f, 0.f};
;         cur = nxt; cA = nA; cB = nB; cAr = nAr; cHb = nHb; ++ui;
.LBB0_566:
	s_add_u32 s25, s36, 0x80
	s_addc_u32 s27, s37, 0
	s_add_u32 s14, s38, 0x80080
	s_addc_u32 s15, s39, 0
	s_add_u32 s52, s0, 0x100
	v_mov_b32_e32 v0, 0
	v_lshl_add_u64 v[140:141], s[14:15], 0, v[136:137]
	v_lshl_add_u64 v[142:143], s[14:15], 0, v[138:139]
	s_addc_u32 s53, s1, 0
	s_mov_b32 s66, -2
	s_mov_b64 s[0:1], 0
	v_mov_b32_e32 v1, v0
	v_pk_mov_b32 v[2:3], v[0:1], v[0:1]
	v_pk_mov_b32 v[4:5], v[0:1], v[0:1]
	v_pk_mov_b32 v[6:7], v[0:1], v[0:1]
	v_pk_mov_b32 v[8:9], v[0:1], v[0:1]
	v_pk_mov_b32 v[10:11], v[0:1], v[0:1]
	v_pk_mov_b32 v[12:13], v[0:1], v[0:1]
	v_pk_mov_b32 v[14:15], v[0:1], v[0:1]
	v_pk_mov_b32 v[16:17], v[0:1], v[0:1]
	v_pk_mov_b32 v[18:19], v[0:1], v[0:1]
	v_pk_mov_b32 v[20:21], v[0:1], v[0:1]
	v_pk_mov_b32 v[22:23], v[0:1], v[0:1]
	v_pk_mov_b32 v[24:25], v[0:1], v[0:1]
	v_pk_mov_b32 v[26:27], v[0:1], v[0:1]
	v_pk_mov_b32 v[28:29], v[0:1], v[0:1]
	v_pk_mov_b32 v[30:31], v[0:1], v[0:1]
	v_pk_mov_b32 v[32:33], v[0:1], v[0:1]
	v_pk_mov_b32 v[34:35], v[0:1], v[0:1]
	v_pk_mov_b32 v[36:37], v[0:1], v[0:1]
	v_pk_mov_b32 v[38:39], v[0:1], v[0:1]
	v_pk_mov_b32 v[40:41], v[0:1], v[0:1]
	v_pk_mov_b32 v[42:43], v[0:1], v[0:1]
	v_pk_mov_b32 v[44:45], v[0:1], v[0:1]
	v_pk_mov_b32 v[46:47], v[0:1], v[0:1]
	v_pk_mov_b32 v[48:49], v[0:1], v[0:1]
	v_pk_mov_b32 v[50:51], v[0:1], v[0:1]
	v_pk_mov_b32 v[52:53], v[0:1], v[0:1]
	v_pk_mov_b32 v[54:55], v[0:1], v[0:1]
	v_pk_mov_b32 v[56:57], v[0:1], v[0:1]
	v_pk_mov_b32 v[58:59], v[0:1], v[0:1]
	v_pk_mov_b32 v[60:61], v[0:1], v[0:1]
	v_pk_mov_b32 v[62:63], v[0:1], v[0:1]
	v_pk_mov_b32 v[64:65], v[0:1], v[0:1]
	v_pk_mov_b32 v[66:67], v[0:1], v[0:1]
	v_pk_mov_b32 v[68:69], v[0:1], v[0:1]
	v_pk_mov_b32 v[70:71], v[0:1], v[0:1]
	v_pk_mov_b32 v[72:73], v[0:1], v[0:1]
	v_pk_mov_b32 v[74:75], v[0:1], v[0:1]
	v_pk_mov_b32 v[76:77], v[0:1], v[0:1]
	v_pk_mov_b32 v[78:79], v[0:1], v[0:1]
	v_pk_mov_b32 v[80:81], v[0:1], v[0:1]
	v_pk_mov_b32 v[82:83], v[0:1], v[0:1]
	v_pk_mov_b32 v[84:85], v[0:1], v[0:1]
	v_pk_mov_b32 v[86:87], v[0:1], v[0:1]
	v_pk_mov_b32 v[88:89], v[0:1], v[0:1]
	v_pk_mov_b32 v[90:91], v[0:1], v[0:1]
	v_pk_mov_b32 v[92:93], v[0:1], v[0:1]
	v_pk_mov_b32 v[94:95], v[0:1], v[0:1]
	v_pk_mov_b32 v[96:97], v[0:1], v[0:1]
	v_pk_mov_b32 v[98:99], v[0:1], v[0:1]
	v_pk_mov_b32 v[100:101], v[0:1], v[0:1]
	v_pk_mov_b32 v[102:103], v[0:1], v[0:1]
	v_pk_mov_b32 v[104:105], v[0:1], v[0:1]
	v_pk_mov_b32 v[106:107], v[0:1], v[0:1]
	v_pk_mov_b32 v[108:109], v[0:1], v[0:1]
	v_pk_mov_b32 v[110:111], v[0:1], v[0:1]
	v_pk_mov_b32 v[112:113], v[0:1], v[0:1]
	v_pk_mov_b32 v[114:115], v[0:1], v[0:1]
	v_pk_mov_b32 v[116:117], v[0:1], v[0:1]
	v_pk_mov_b32 v[118:119], v[0:1], v[0:1]
	v_pk_mov_b32 v[120:121], v[0:1], v[0:1]
	v_pk_mov_b32 v[122:123], v[0:1], v[0:1]
	v_pk_mov_b32 v[124:125], v[0:1], v[0:1]
	v_pk_mov_b32 v[126:127], v[0:1], v[0:1]
	v_add_u32_e32 v158, 0x10000, v145
	ds_read_b128 v[150:153], v158
	ds_read_b128 v[154:157], v158 offset:1024
	ds_read_b128 v[168:171], v158 offset:2048
	ds_read_b128 v[172:175], v158 offset:3072
	s_branch .LBB0_567

; #define PG8_STAGE(bufoff, gbase, voff) do { _Pragma("unroll") for (int _i = 0; _i < 2; ++_i) \
;         __builtin_amdgcn_global_load_lds((const unsigned*)((const char*)(gbase) + (voff)[_i]), (LAS unsigned*)(lds + (bufoff) + ldsw + _i * 8192), 16, 0, 0); } while (0)
; #define PG8_STAGE_A(bufoff, ptr, half, rev) do { if (REVA && (rev)) { const char* _p = (ptr) - ((half) ? hstepA : 0); PG8_STAGE(bufoff, _p, voffAr); } else { const char* _p = (ptr) + ((half) ? hstepA : 0); PG8_STAGE(bufoff, _p, voffA); } } while (0)
; #define PG8_LDA(dst, b, h) do { _Pragma("unroll") for (int m = 0; m < 4; ++m) _Pragma("unroll") for (int k = 0; k < 2; ++k) dst[m][k] = *(const LAS bf16x8*)(lds + PG8_SA(b, h) + aoff + m * 2048 + k * 1024); } while (0)
; #define PG8_LDB(dst, b, h) do { _Pragma("unroll") for (int n = 0; n < 2; ++n) _Pragma("unroll") for (int k = 0; k < 2; ++k) dst[n][k] = *(const LAS bf16x8*)(lds + PG8_SB(b, h) + boff + n * 2048 + k * 1024); } while (0)
; #define PG8_WAIT_V(n) asm volatile("s_waitcnt vmcnt(" #n ")" ::: "memory")
; #define PG8_WAIT_L(n) asm volatile("s_waitcnt lgkmcnt(" #n ")" ::: "memory")
; #define PG8_BAR __builtin_amdgcn_s_barrier()
;     ...
;         for (int t = 0; t < nt; t += 2) {
;             const bool last = (t == nt - 2);
;             const char* a1 = PG8_APTR(cA, cAr, t + 1); const bool r1 = REVA && ((t + 1) & 4);
;             const char* a2 = last ? nA : PG8_APTR(cA, cAr, t + 2); const bool r2 = REVA && !last && ((t + 2) & 4);
;             const char* a3 = last ? nA + kstep : PG8_APTR(cA, cAr, t + 3); const bool r3 = REVA && !last && ((t + 3) & 4);
;             const char* b2 = last ? nB : cB + (size_t)(t + 2) * kstep; const char* b3 = b2 + kstep; const size_t hb2 = last ? nHb : cHb;
;             PG8_LDB(B0, 0, 0); PG8_SCHED; PG8_LDA(At, 0, 0); PG8_STAGE_A(PG8_SA(1, 1), a1, 1, r1);
;             PG8_WAIT_L(8); PG8_BAR; PG8_WAIT_L(0); PG8_MMA(0, 0, At, B0); PG8_BAR; PG8_SCHED;
;             PG8_LDB(B1, 0, 1); PG8_STAGE(PG8_SB(0, 0), b2, voffB);
;             PG8_BAR; PG8_WAIT_L(0); PG8_MMA(0, 1, At, B1); PG8_BAR;
;             PG8_LDA(At, 0, 1); PG8_STAGE_A(PG8_SA(0, 0), a2, 0, r2);
;             PG8_BAR; PG8_WAIT_L(0); PG8_MMA(1, 0, At, B0); PG8_BAR; PG8_SCHED;
;             PG8_STAGE(PG8_SB(0, 1), b2 + hb2, voffB);
;             PG8_WAIT_V(6); PG8_BAR; PG8_MMA(1, 1, At, B1); PG8_BAR;
.LBB0_567:
	s_add_u32 s10, s38, s0
	s_addc_u32 s11, s39, s1
	s_add_u32 s16, s10, 0x100
	s_addc_u32 s17, s11, 0
	s_add_u32 s10, s10, 0x180
	s_addc_u32 s11, s11, 0
	s_add_u32 s14, s52, s0
	s_addc_u32 s15, s53, s1
	s_add_i32 s67, 0, 0x10000
	s_cmpk_eq_i32 s0, 0xf00
	s_cselect_b32 s15, s45, s15
	s_cselect_b32 s14, s44, s14
	s_cselect_b32 s21, s37, s17
	s_cselect_b32 s20, s36, s16
	s_cselect_b32 s17, s27, s11
	s_cselect_b32 s16, s25, s10
	v_lshl_add_u64 v[158:159], v[140:141], 0, s[0:1]
	s_add_i32 m0, s22, 0xc000
	ds_read_b128 v[176:179], v149
	ds_read_b128 v[180:183], v149 offset:1024
	ds_read_b128 v[204:207], v149 offset:2048
	ds_read_b128 v[208:211], v149 offset:3072
	ds_read_b128 v[212:215], v149 offset:4096
	ds_read_b128 v[216:219], v149 offset:5120
	ds_read_b128 v[220:223], v149 offset:6144
	ds_read_b128 v[224:227], v149 offset:7168
	global_load_lds_dwordx4 v[158:159], off
	v_lshl_add_u64 v[158:159], v[142:143], 0, s[0:1]
	s_add_i32 m0, s22, 0xe000
	s_nop 0
	global_load_lds_dwordx4 v[158:159], off
	s_waitcnt lgkmcnt(8)
	s_waitcnt vmcnt(10)
	s_barrier
	s_waitcnt lgkmcnt(0)
	v_mfma_f32_16x16x32_bf16 v[124:127], v[150:153], v[176:179], v[124:127]
	v_mfma_f32_16x16x32_bf16 v[120:123], v[168:171], v[176:179], v[120:123]
	v_mfma_f32_16x16x32_bf16 v[116:119], v[150:153], v[204:207], v[116:119]
	v_mfma_f32_16x16x32_bf16 v[108:111], v[168:171], v[204:207], v[108:111]
	v_mfma_f32_16x16x32_bf16 v[100:103], v[150:153], v[212:215], v[100:103]
	v_mfma_f32_16x16x32_bf16 v[92:95], v[168:171], v[212:215], v[92:95]
	v_mfma_f32_16x16x32_bf16 v[84:87], v[150:153], v[220:223], v[84:87]
	v_mfma_f32_16x16x32_bf16 v[76:79], v[168:171], v[220:223], v[76:79]
	v_mfma_f32_16x16x32_bf16 v[124:127], v[154:157], v[180:183], v[124:127]
	v_mfma_f32_16x16x32_bf16 v[120:123], v[172:175], v[180:183], v[120:123]
	v_mfma_f32_16x16x32_bf16 v[116:119], v[154:157], v[208:211], v[116:119]
	v_mfma_f32_16x16x32_bf16 v[108:111], v[172:175], v[208:211], v[108:111]
	v_mfma_f32_16x16x32_bf16 v[100:103], v[154:157], v[216:219], v[100:103]
	v_mfma_f32_16x16x32_bf16 v[92:95], v[172:175], v[216:219], v[92:95]
	v_mfma_f32_16x16x32_bf16 v[84:87], v[154:157], v[224:227], v[84:87]
	v_mfma_f32_16x16x32_bf16 v[76:79], v[172:175], v[224:227], v[76:79]
	s_barrier
	s_add_i32 s10, 0, 0x14000
	v_add_u32_e32 v158, s10, v145
	s_add_i32 s11, s67, s5
	ds_read_b128 v[228:231], v158
	ds_read_b128 v[232:235], v158 offset:1024
	ds_read_b128 v[236:239], v158 offset:2048
	ds_read_b128 v[240:243], v158 offset:3072
	v_lshl_add_u64 v[158:159], s[14:15], 0, v[132:133]
	s_mov_b32 m0, s11
	v_lshl_add_u64 v[184:185], s[14:15], 0, v[128:129]
	global_load_lds_dwordx4 v[158:159], off
	s_add_i32 m0, s11, 0x2000
	s_nop 0
	global_load_lds_dwordx4 v[184:185], off
	s_waitcnt vmcnt(10)
	s_barrier
	s_waitcnt lgkmcnt(0)
	v_mfma_f32_16x16x32_bf16 v[112:115], v[228:231], v[176:179], v[112:115]
	v_mfma_f32_16x16x32_bf16 v[104:107], v[236:239], v[176:179], v[104:107]
	v_mfma_f32_16x16x32_bf16 v[96:99], v[228:231], v[204:207], v[96:99]
	v_mfma_f32_16x16x32_bf16 v[88:91], v[236:239], v[204:207], v[88:91]
	v_mfma_f32_16x16x32_bf16 v[80:83], v[228:231], v[212:215], v[80:83]
	v_mfma_f32_16x16x32_bf16 v[72:75], v[236:239], v[212:215], v[72:75]
	v_mfma_f32_16x16x32_bf16 v[68:71], v[228:231], v[220:223], v[68:71]
	v_mfma_f32_16x16x32_bf16 v[64:67], v[236:239], v[220:223], v[64:67]
	v_mfma_f32_16x16x32_bf16 v[112:115], v[232:235], v[180:183], v[112:115]
	v_mfma_f32_16x16x32_bf16 v[104:107], v[240:243], v[180:183], v[104:107]
	v_mfma_f32_16x16x32_bf16 v[96:99], v[232:235], v[208:211], v[96:99]
	v_mfma_f32_16x16x32_bf16 v[88:91], v[240:243], v[208:211], v[88:91]
	v_mfma_f32_16x16x32_bf16 v[80:83], v[232:235], v[216:219], v[80:83]
	v_mfma_f32_16x16x32_bf16 v[72:75], v[240:243], v[216:219], v[72:75]
	v_mfma_f32_16x16x32_bf16 v[68:71], v[232:235], v[224:227], v[68:71]
	v_mfma_f32_16x16x32_bf16 v[64:67], v[240:243], v[224:227], v[64:67]
	s_mov_b32 m0, s22
	v_lshl_add_u64 v[190:191], s[20:21], 0, v[134:135]
	s_barrier
	ds_read_b128 v[176:179], v149 offset:16384
	ds_read_b128 v[180:183], v149 offset:17408
	ds_read_b128 v[204:207], v149 offset:18432
	ds_read_b128 v[208:211], v149 offset:19456
	ds_read_b128 v[212:215], v149 offset:20480
	ds_read_b128 v[216:219], v149 offset:21504
	ds_read_b128 v[220:223], v149 offset:22528
	ds_read_b128 v[224:227], v149 offset:23552
	global_load_lds_dwordx4 v[190:191], off
	v_lshl_add_u64 v[190:191], s[20:21], 0, v[130:131]
	s_mov_b32 m0, s46
	s_nop 0
	global_load_lds_dwordx4 v[190:191], off
	s_waitcnt vmcnt(10)
	s_barrier
	s_waitcnt lgkmcnt(0)
	v_mfma_f32_16x16x32_bf16 v[60:63], v[150:153], v[176:179], v[60:63]
	v_mfma_f32_16x16x32_bf16 v[56:59], v[168:171], v[176:179], v[56:59]
	v_mfma_f32_16x16x32_bf16 v[52:55], v[150:153], v[204:207], v[52:55]
	v_mfma_f32_16x16x32_bf16 v[44:47], v[168:171], v[204:207], v[44:47]
	v_mfma_f32_16x16x32_bf16 v[36:39], v[150:153], v[212:215], v[36:39]
	v_mfma_f32_16x16x32_bf16 v[28:31], v[168:171], v[212:215], v[28:31]
	v_mfma_f32_16x16x32_bf16 v[20:23], v[150:153], v[220:223], v[20:23]
	v_mfma_f32_16x16x32_bf16 v[12:15], v[168:171], v[220:223], v[12:15]
	v_mfma_f32_16x16x32_bf16 v[60:63], v[154:157], v[180:183], v[60:63]
	v_mfma_f32_16x16x32_bf16 v[56:59], v[172:175], v[180:183], v[56:59]
	v_mfma_f32_16x16x32_bf16 v[52:55], v[154:157], v[208:211], v[52:55]
	v_mfma_f32_16x16x32_bf16 v[44:47], v[172:175], v[208:211], v[44:47]
	v_mfma_f32_16x16x32_bf16 v[36:39], v[154:157], v[216:219], v[36:39]
	v_mfma_f32_16x16x32_bf16 v[28:31], v[172:175], v[216:219], v[28:31]
	v_mfma_f32_16x16x32_bf16 v[20:23], v[154:157], v[224:227], v[20:23]
	v_mfma_f32_16x16x32_bf16 v[12:15], v[172:175], v[224:227], v[12:15]
	s_barrier
; #define PG8_STAGE(bufoff, gbase, voff) do { _Pragma("unroll") for (int _i = 0; _i < 2; ++_i) \
;         __builtin_amdgcn_global_load_lds((const unsigned*)((const char*)(gbase) + (voff)[_i]), (LAS unsigned*)(lds + (bufoff) + ldsw + _i * 8192), 16, 0, 0); } while (0)
; #define PG8_STAGE_A(bufoff, ptr, half, rev) do { if (REVA && (rev)) { const char* _p = (ptr) - ((half) ? hstepA : 0); PG8_STAGE(bufoff, _p, voffAr); } else { const char* _p = (ptr) + ((half) ? hstepA : 0); PG8_STAGE(bufoff, _p, voffA); } } while (0)
; #define PG8_LDA(dst, b, h) do { _Pragma("unroll") for (int m = 0; m < 4; ++m) _Pragma("unroll") for (int k = 0; k < 2; ++k) dst[m][k] = *(const LAS bf16x8*)(lds + PG8_SA(b, h) + aoff + m * 2048 + k * 1024); } while (0)
; #define PG8_LDB(dst, b, h) do { _Pragma("unroll") for (int n = 0; n < 2; ++n) _Pragma("unroll") for (int k = 0; k < 2; ++k) dst[n][k] = *(const LAS bf16x8*)(lds + PG8_SB(b, h) + boff + n * 2048 + k * 1024); } while (0)
; #define PG8_MMA(ai, bj, At, Bt) do { __builtin_amdgcn_s_setprio(1); _Pragma("unroll") for (int m = 0; m < 4; ++m) _Pragma("unroll") for (int n = 0; n < 2; ++n) _Pragma("unroll") for (int k = 0; k < 2; ++k) \
;         acc[ai][bj][m][n] = __builtin_amdgcn_mfma_f32_16x16x32_bf16(Bt[n][k], At[m][k], acc[ai][bj][m][n], 0, 0, 0); __builtin_amdgcn_s_setprio(0); } while (0)
; #define PG8_WAIT_V(n) asm volatile("s_waitcnt vmcnt(" #n ")" ::: "memory")
; #define PG8_WAIT_L(n) asm volatile("s_waitcnt lgkmcnt(" #n ")" ::: "memory")
; #define PG8_BAR __builtin_amdgcn_s_barrier()
; #define PG8_SCHED __builtin_amdgcn_sched_barrier(0)
;     ...
;             PG8_WAIT_V(6); PG8_BAR; PG8_MMA(1, 1, At, B1); PG8_BAR;
;             PG8_LDB(B0, 1, 0); PG8_SCHED; PG8_LDA(At, 1, 0); PG8_STAGE_A(PG8_SA(0, 1), a2, 1, r2);
;             PG8_WAIT_L(8); PG8_BAR; PG8_WAIT_L(0); PG8_MMA(0, 0, At, B0); PG8_BAR; PG8_SCHED;
;             PG8_LDB(B1, 1, 1); PG8_STAGE(PG8_SB(1, 0), b3, voffB);
;             PG8_BAR; PG8_WAIT_L(0); PG8_MMA(0, 1, At, B1); PG8_BAR;
;             PG8_LDA(At, 1, 1); PG8_STAGE_A(PG8_SA(1, 0), a3, 0, r3);
;             PG8_BAR; PG8_WAIT_L(0); PG8_MMA(1, 0, At, B0); PG8_BAR; PG8_SCHED;
	s_add_u32 s68, s14, 0x80000
	s_addc_u32 s69, s15, 0
	s_add_i32 s10, s10, s5
	v_lshl_add_u64 v[150:151], s[68:69], 0, v[132:133]
	s_mov_b32 m0, s10
	s_nop 0
	global_load_lds_dwordx4 v[150:151], off
	v_lshl_add_u64 v[150:151], s[68:69], 0, v[128:129]
	s_add_i32 m0, s10, 0x2000
	s_nop 0
	global_load_lds_dwordx4 v[150:151], off
	v_add_u32_e32 v172, 0x18000, v145
	ds_read_b128 v[150:153], v172
	ds_read_b128 v[154:157], v172 offset:1024
	ds_read_b128 v[168:171], v172 offset:2048
	ds_read_b128 v[172:175], v172 offset:3072
	s_waitcnt vmcnt(10)
	s_barrier
	v_mfma_f32_16x16x32_bf16 v[48:51], v[228:231], v[176:179], v[48:51]
	v_mfma_f32_16x16x32_bf16 v[40:43], v[236:239], v[176:179], v[40:43]
	v_mfma_f32_16x16x32_bf16 v[32:35], v[228:231], v[204:207], v[32:35]
	v_mfma_f32_16x16x32_bf16 v[24:27], v[236:239], v[204:207], v[24:27]
	v_mfma_f32_16x16x32_bf16 v[16:19], v[228:231], v[212:215], v[16:19]
	v_mfma_f32_16x16x32_bf16 v[8:11], v[236:239], v[212:215], v[8:11]
	v_mfma_f32_16x16x32_bf16 v[4:7], v[228:231], v[220:223], v[4:7]
	v_mfma_f32_16x16x32_bf16 v[0:3], v[236:239], v[220:223], v[0:3]
	v_mfma_f32_16x16x32_bf16 v[48:51], v[232:235], v[180:183], v[48:51]
	v_mfma_f32_16x16x32_bf16 v[40:43], v[240:243], v[180:183], v[40:43]
	v_mfma_f32_16x16x32_bf16 v[32:35], v[232:235], v[208:211], v[32:35]
	v_mfma_f32_16x16x32_bf16 v[24:27], v[240:243], v[208:211], v[24:27]
	v_mfma_f32_16x16x32_bf16 v[16:19], v[232:235], v[216:219], v[16:19]
	v_mfma_f32_16x16x32_bf16 v[8:11], v[240:243], v[216:219], v[8:11]
	v_mfma_f32_16x16x32_bf16 v[4:7], v[232:235], v[224:227], v[4:7]
	v_mfma_f32_16x16x32_bf16 v[0:3], v[240:243], v[224:227], v[0:3]
	s_add_i32 s10, 0, 0x18000
	s_barrier
	s_add_u32 s20, s20, 0x80000
	s_addc_u32 s21, s21, 0
	s_mov_b32 m0, s47
	v_lshl_add_u64 v[190:191], s[20:21], 0, v[134:135]
	ds_read_b128 v[176:179], v149 offset:32768
	ds_read_b128 v[180:183], v149 offset:33792
	ds_read_b128 v[204:207], v149 offset:34816
	ds_read_b128 v[208:211], v149 offset:35840
	ds_read_b128 v[212:215], v149 offset:36864
	ds_read_b128 v[216:219], v149 offset:37888
	ds_read_b128 v[220:223], v149 offset:38912
	ds_read_b128 v[224:227], v149 offset:39936
	global_load_lds_dwordx4 v[190:191], off
	v_lshl_add_u64 v[190:191], s[20:21], 0, v[130:131]
	s_mov_b32 m0, s50
	s_nop 0
	global_load_lds_dwordx4 v[190:191], off
	s_waitcnt lgkmcnt(8)
	s_waitcnt vmcnt(10)
	s_barrier
	s_waitcnt lgkmcnt(0)
	v_mfma_f32_16x16x32_bf16 v[124:127], v[150:153], v[176:179], v[124:127]
	v_mfma_f32_16x16x32_bf16 v[120:123], v[168:171], v[176:179], v[120:123]
	v_mfma_f32_16x16x32_bf16 v[116:119], v[150:153], v[204:207], v[116:119]
	v_mfma_f32_16x16x32_bf16 v[108:111], v[168:171], v[204:207], v[108:111]
	v_mfma_f32_16x16x32_bf16 v[100:103], v[150:153], v[212:215], v[100:103]
	v_mfma_f32_16x16x32_bf16 v[92:95], v[168:171], v[212:215], v[92:95]
	v_mfma_f32_16x16x32_bf16 v[84:87], v[150:153], v[220:223], v[84:87]
	v_mfma_f32_16x16x32_bf16 v[76:79], v[168:171], v[220:223], v[76:79]
	v_mfma_f32_16x16x32_bf16 v[124:127], v[154:157], v[180:183], v[124:127]
	v_mfma_f32_16x16x32_bf16 v[120:123], v[172:175], v[180:183], v[120:123]
	v_mfma_f32_16x16x32_bf16 v[116:119], v[154:157], v[208:211], v[116:119]
	v_mfma_f32_16x16x32_bf16 v[108:111], v[172:175], v[208:211], v[108:111]
	v_mfma_f32_16x16x32_bf16 v[100:103], v[154:157], v[216:219], v[100:103]
	v_mfma_f32_16x16x32_bf16 v[92:95], v[172:175], v[216:219], v[92:95]
	v_mfma_f32_16x16x32_bf16 v[84:87], v[154:157], v[224:227], v[84:87]
	v_mfma_f32_16x16x32_bf16 v[76:79], v[172:175], v[224:227], v[76:79]
	s_barrier
	s_add_i32 s11, 0, 0x1c000
	s_add_i32 s10, s10, s5
	v_add_u32_e32 v190, s11, v145
	v_lshl_add_u64 v[158:159], v[158:159], 0, s[28:29]
	s_mov_b32 m0, s10
	ds_read_b128 v[228:231], v190
	ds_read_b128 v[232:235], v190 offset:1024
	ds_read_b128 v[236:239], v190 offset:2048
	ds_read_b128 v[240:243], v190 offset:3072
	global_load_lds_dwordx4 v[158:159], off
	v_lshl_add_u64 v[158:159], v[184:185], 0, s[28:29]
	s_add_i32 m0, s10, 0x2000
	s_nop 0
	global_load_lds_dwordx4 v[158:159], off
	s_waitcnt vmcnt(10)
	s_barrier
	s_waitcnt lgkmcnt(0)
	v_mfma_f32_16x16x32_bf16 v[112:115], v[228:231], v[176:179], v[112:115]
	v_mfma_f32_16x16x32_bf16 v[104:107], v[236:239], v[176:179], v[104:107]
	v_mfma_f32_16x16x32_bf16 v[96:99], v[228:231], v[204:207], v[96:99]
	v_mfma_f32_16x16x32_bf16 v[88:91], v[236:239], v[204:207], v[88:91]
	v_mfma_f32_16x16x32_bf16 v[80:83], v[228:231], v[212:215], v[80:83]
	v_mfma_f32_16x16x32_bf16 v[72:75], v[236:239], v[212:215], v[72:75]
	v_mfma_f32_16x16x32_bf16 v[68:71], v[228:231], v[220:223], v[68:71]
	v_mfma_f32_16x16x32_bf16 v[64:67], v[236:239], v[220:223], v[64:67]
	v_mfma_f32_16x16x32_bf16 v[112:115], v[232:235], v[180:183], v[112:115]
	v_mfma_f32_16x16x32_bf16 v[104:107], v[240:243], v[180:183], v[104:107]
	v_mfma_f32_16x16x32_bf16 v[96:99], v[232:235], v[208:211], v[96:99]
	v_mfma_f32_16x16x32_bf16 v[88:91], v[240:243], v[208:211], v[88:91]
	v_mfma_f32_16x16x32_bf16 v[80:83], v[232:235], v[216:219], v[80:83]
	v_mfma_f32_16x16x32_bf16 v[72:75], v[240:243], v[216:219], v[72:75]
	v_mfma_f32_16x16x32_bf16 v[68:71], v[232:235], v[224:227], v[68:71]
	v_mfma_f32_16x16x32_bf16 v[64:67], v[240:243], v[224:227], v[64:67]
	s_mov_b32 m0, s48
	v_lshl_add_u64 v[158:159], s[16:17], 0, v[134:135]
	s_barrier
	ds_read_b128 v[176:179], v149 offset:49152
	ds_read_b128 v[180:183], v149 offset:50176
	ds_read_b128 v[204:207], v149 offset:51200
	ds_read_b128 v[208:211], v149 offset:52224
	ds_read_b128 v[212:215], v149 offset:53248
	ds_read_b128 v[216:219], v149 offset:54272
	ds_read_b128 v[220:223], v149 offset:55296
	ds_read_b128 v[224:227], v149 offset:56320
	global_load_lds_dwordx4 v[158:159], off
	v_lshl_add_u64 v[158:159], s[16:17], 0, v[130:131]
	s_mov_b32 m0, s49
	s_nop 0
	global_load_lds_dwordx4 v[158:159], off
	s_waitcnt vmcnt(10)
	s_barrier
; #define PG8_STAGE(bufoff, gbase, voff) do { _Pragma("unroll") for (int _i = 0; _i < 2; ++_i) \
;         __builtin_amdgcn_global_load_lds((const unsigned*)((const char*)(gbase) + (voff)[_i]), (LAS unsigned*)(lds + (bufoff) + ldsw + _i * 8192), 16, 0, 0); } while (0)
; #define PG8_MMA(ai, bj, At, Bt) do { __builtin_amdgcn_s_setprio(1); _Pragma("unroll") for (int m = 0; m < 4; ++m) _Pragma("unroll") for (int n = 0; n < 2; ++n) _Pragma("unroll") for (int k = 0; k < 2; ++k) \
;         acc[ai][bj][m][n] = __builtin_amdgcn_mfma_f32_16x16x32_bf16(Bt[n][k], At[m][k], acc[ai][bj][m][n], 0, 0, 0); __builtin_amdgcn_s_setprio(0); } while (0)
; #define PG8_WAIT_V(n) asm volatile("s_waitcnt vmcnt(" #n ")" ::: "memory")
; #define PG8_WAIT_L(n) asm volatile("s_waitcnt lgkmcnt(" #n ")" ::: "memory")
; #define PG8_BAR __builtin_amdgcn_s_barrier()
; #define PG8_SCHED __builtin_amdgcn_sched_barrier(0)
;     ...
;             PG8_BAR; PG8_WAIT_L(0); PG8_MMA(1, 0, At, B0); PG8_BAR; PG8_SCHED;
;             PG8_STAGE(PG8_SB(1, 1), b3 + hb2, voffB);
;             PG8_WAIT_V(6); PG8_BAR; PG8_MMA(1, 1, At, B1); PG8_BAR;
	s_waitcnt lgkmcnt(0)
	v_mfma_f32_16x16x32_bf16 v[60:63], v[150:153], v[176:179], v[60:63]
	v_mfma_f32_16x16x32_bf16 v[56:59], v[168:171], v[176:179], v[56:59]
	v_mfma_f32_16x16x32_bf16 v[52:55], v[150:153], v[204:207], v[52:55]
	v_mfma_f32_16x16x32_bf16 v[44:47], v[168:171], v[204:207], v[44:47]
	v_mfma_f32_16x16x32_bf16 v[36:39], v[150:153], v[212:215], v[36:39]
	v_mfma_f32_16x16x32_bf16 v[28:31], v[168:171], v[212:215], v[28:31]
	v_mfma_f32_16x16x32_bf16 v[20:23], v[150:153], v[220:223], v[20:23]
	v_mfma_f32_16x16x32_bf16 v[12:15], v[168:171], v[220:223], v[12:15]
	v_mfma_f32_16x16x32_bf16 v[60:63], v[154:157], v[180:183], v[60:63]
	v_mfma_f32_16x16x32_bf16 v[56:59], v[172:175], v[180:183], v[56:59]
	v_mfma_f32_16x16x32_bf16 v[52:55], v[154:157], v[208:211], v[52:55]
	v_mfma_f32_16x16x32_bf16 v[44:47], v[172:175], v[208:211], v[44:47]
	v_mfma_f32_16x16x32_bf16 v[36:39], v[154:157], v[216:219], v[36:39]
	v_mfma_f32_16x16x32_bf16 v[28:31], v[172:175], v[216:219], v[28:31]
	v_mfma_f32_16x16x32_bf16 v[20:23], v[154:157], v[224:227], v[20:23]
	v_mfma_f32_16x16x32_bf16 v[12:15], v[172:175], v[224:227], v[12:15]
	s_barrier
	s_add_u32 s14, s14, 0x80080
	s_addc_u32 s15, s15, 0
	s_add_i32 s10, s11, s5
	v_lshl_add_u64 v[150:151], s[14:15], 0, v[132:133]
	s_mov_b32 m0, s10
	s_nop 0
	global_load_lds_dwordx4 v[150:151], off
	v_lshl_add_u64 v[150:151], s[14:15], 0, v[128:129]
	s_add_i32 m0, s10, 0x2000
	s_nop 0
	global_load_lds_dwordx4 v[150:151], off
	v_add_u32_e32 v158, 0x10000, v145
	ds_read_b128 v[150:153], v158
	ds_read_b128 v[154:157], v158 offset:1024
	ds_read_b128 v[168:171], v158 offset:2048
	ds_read_b128 v[172:175], v158 offset:3072
	s_waitcnt vmcnt(10)
	s_barrier
	v_mfma_f32_16x16x32_bf16 v[48:51], v[228:231], v[176:179], v[48:51]
	v_mfma_f32_16x16x32_bf16 v[40:43], v[236:239], v[176:179], v[40:43]
	v_mfma_f32_16x16x32_bf16 v[32:35], v[228:231], v[204:207], v[32:35]
	v_mfma_f32_16x16x32_bf16 v[24:27], v[236:239], v[204:207], v[24:27]
	v_mfma_f32_16x16x32_bf16 v[16:19], v[228:231], v[212:215], v[16:19]
	v_mfma_f32_16x16x32_bf16 v[8:11], v[236:239], v[212:215], v[8:11]
	v_mfma_f32_16x16x32_bf16 v[4:7], v[228:231], v[220:223], v[4:7]
	v_mfma_f32_16x16x32_bf16 v[0:3], v[236:239], v[220:223], v[0:3]
	v_mfma_f32_16x16x32_bf16 v[48:51], v[232:235], v[180:183], v[48:51]
	v_mfma_f32_16x16x32_bf16 v[40:43], v[240:243], v[180:183], v[40:43]
	v_mfma_f32_16x16x32_bf16 v[32:35], v[232:235], v[208:211], v[32:35]
	v_mfma_f32_16x16x32_bf16 v[24:27], v[240:243], v[208:211], v[24:27]
	v_mfma_f32_16x16x32_bf16 v[16:19], v[232:235], v[216:219], v[16:19]
	v_mfma_f32_16x16x32_bf16 v[8:11], v[240:243], v[216:219], v[8:11]
	v_mfma_f32_16x16x32_bf16 v[4:7], v[232:235], v[224:227], v[4:7]
	v_mfma_f32_16x16x32_bf16 v[0:3], v[240:243], v[224:227], v[0:3]
	s_add_i32 s66, s66, 2
	s_add_u32 s0, s0, 0x100
	s_addc_u32 s1, s1, 0
	s_cmp_gt_u32 s66, 29
	s_cbranch_scc0 .Lrot_567_bar
	s_barrier
; __device__ __forceinline__ unsigned cvt_pk_bf16(float lo, float hi) { unsigned r; asm volatile("v_cvt_pk_bf16_f32 %0, %1, %2" : "=v"(r) : "v"(lo), "v"(hi)); return r; }
; #define PG8_WAIT_V(n) asm volatile("s_waitcnt vmcnt(" #n ")" ::: "memory")
; #define PG8_BAR __builtin_amdgcn_s_barrier()
;     ...
;         if (!has_next) break;
; #pragma unroll
;         for (int a = 0; a < 2; ++a)
; #pragma unroll
;             for (int b = 0; b < 2; ++b)
; #pragma unroll
;                 for (int m = 0; m < 4; ++m)
; #pragma unroll
;                     for (int n = 0; n < 2; ++n) acc[a][b][m][n] = (f32x4){0.f, 0.f, 0.f, 0.f};
;         cur = nxt; cA = nA; cB = nB; cAr = nAr; cHb = nHb; ++ui;
;     }
;     PG8_WAIT_V(0);
;     if (wr == 0) PG8_BAR;
;     PG8_BAR;
;     __device__ __forceinline__ void generic(const f32x4 (&acc)[2][2][4][2], const Unit& u, int wr, int wc, int fr, int fq) const {
;     ...
;                     } else if (MODE == 0) {
;                         u32x4 w; w.x = cvt_pk_bf16(v0[0], v0[1]); w.y = cvt_pk_bf16(v0[2], v0[3]); w.z = cvt_pk_bf16(v1[0], v1[1]); w.w = cvt_pk_bf16(v1[2], v1[3]);
;                         *(u32x4*)(O + (size_t)(u.pm * BM + rt) * ldc + u.pn * BM + ct) = w;
	s_waitcnt lgkmcnt(0)
	s_lshl_b32 s9, s9, 8
	v_cvt_pk_bf16_f32 v124, v124, v125
	v_cvt_pk_bf16_f32 v125, v126, v127
	v_cvt_pk_bf16_f32 v126, v120, v121
	v_add_u32_e32 v120, s9, v144
	v_ashrrev_i32_e32 v121, 31, v120
	s_lshl_b32 s0, s8, 8
	v_cvt_pk_bf16_f32 v127, v122, v123
	v_lshlrev_b64 v[122:123], 12, v[120:121]
	s_ashr_i32 s1, s0, 31
	v_lshl_add_u64 v[122:123], s[2:3], 0, v[122:123]
	s_lshl_b64 s[0:1], s[0:1], 1
	v_lshl_add_u64 v[122:123], v[122:123], 0, s[0:1]
	v_lshl_add_u64 v[122:123], v[122:123], 0, v[160:161]
	global_store_dwordx4 v[122:123], v[124:127], off
	v_cvt_pk_bf16_f32 v112, v112, v113
	v_cvt_pk_bf16_f32 v113, v114, v115
	v_cvt_pk_bf16_f32 v114, v104, v105
	v_cvt_pk_bf16_f32 v115, v106, v107
	global_store_dwordx4 v[122:123], v[112:115], off offset:256
	v_cvt_pk_bf16_f32 v104, v116, v117
	v_cvt_pk_bf16_f32 v105, v118, v119
	v_cvt_pk_bf16_f32 v106, v108, v109
	v_add_u32_e32 v108, s9, v146
	v_ashrrev_i32_e32 v109, 31, v108
	v_lshlrev_b64 v[108:109], 12, v[108:109]
	v_lshl_add_u64 v[108:109], s[2:3], 0, v[108:109]
	v_lshl_add_u64 v[108:109], v[108:109], 0, s[0:1]
	v_lshl_add_u64 v[108:109], v[108:109], 0, v[160:161]
	v_cvt_pk_bf16_f32 v107, v110, v111
	global_store_dwordx4 v[108:109], v[104:107], off
	v_cvt_pk_bf16_f32 v96, v96, v97
	v_cvt_pk_bf16_f32 v97, v98, v99
	v_cvt_pk_bf16_f32 v98, v88, v89
	v_cvt_pk_bf16_f32 v99, v90, v91
	global_store_dwordx4 v[108:109], v[96:99], off offset:256
	v_cvt_pk_bf16_f32 v88, v100, v101
	v_cvt_pk_bf16_f32 v89, v102, v103
	v_cvt_pk_bf16_f32 v90, v92, v93
	v_add_u32_e32 v92, s9, v147
	v_ashrrev_i32_e32 v93, 31, v92
	v_lshlrev_b64 v[92:93], 12, v[92:93]
	v_lshl_add_u64 v[92:93], s[2:3], 0, v[92:93]
	v_lshl_add_u64 v[92:93], v[92:93], 0, s[0:1]
	v_lshl_add_u64 v[92:93], v[92:93], 0, v[160:161]
	v_cvt_pk_bf16_f32 v91, v94, v95
	global_store_dwordx4 v[92:93], v[88:91], off
	v_cvt_pk_bf16_f32 v80, v80, v81
	v_cvt_pk_bf16_f32 v81, v82, v83
	v_cvt_pk_bf16_f32 v82, v72, v73
	v_cvt_pk_bf16_f32 v83, v74, v75
	global_store_dwordx4 v[92:93], v[80:83], off offset:256
	v_cvt_pk_bf16_f32 v72, v84, v85
	v_cvt_pk_bf16_f32 v73, v86, v87
	v_cvt_pk_bf16_f32 v74, v76, v77
	v_add_u32_e32 v76, s9, v148
	v_ashrrev_i32_e32 v77, 31, v76
	v_lshlrev_b64 v[76:77], 12, v[76:77]
	v_lshl_add_u64 v[76:77], s[2:3], 0, v[76:77]
	v_lshl_add_u64 v[76:77], v[76:77], 0, s[0:1]
	v_lshl_add_u64 v[76:77], v[76:77], 0, v[160:161]
	v_cvt_pk_bf16_f32 v75, v78, v79
	global_store_dwordx4 v[76:77], v[72:75], off
	v_cvt_pk_bf16_f32 v68, v68, v69
	v_cvt_pk_bf16_f32 v69, v70, v71
	v_cvt_pk_bf16_f32 v70, v64, v65
	v_cvt_pk_bf16_f32 v71, v66, v67
	global_store_dwordx4 v[76:77], v[68:71], off offset:256
	v_cvt_pk_bf16_f32 v60, v60, v61
	v_cvt_pk_bf16_f32 v61, v62, v63
	v_cvt_pk_bf16_f32 v62, v56, v57
	v_add_u32_e32 v56, 0x80, v120
	v_ashrrev_i32_e32 v57, 31, v56
	v_lshlrev_b64 v[56:57], 12, v[56:57]
	v_lshl_add_u64 v[56:57], s[2:3], 0, v[56:57]
	v_lshl_add_u64 v[56:57], v[56:57], 0, s[0:1]
	v_lshl_add_u64 v[56:57], v[56:57], 0, v[160:161]
	v_cvt_pk_bf16_f32 v63, v58, v59
	global_store_dwordx4 v[56:57], v[60:63], off
	v_cvt_pk_bf16_f32 v48, v48, v49
	v_cvt_pk_bf16_f32 v49, v50, v51
	v_cvt_pk_bf16_f32 v50, v40, v41
	v_cvt_pk_bf16_f32 v51, v42, v43
	global_store_dwordx4 v[56:57], v[48:51], off offset:256
	v_cvt_pk_bf16_f32 v40, v52, v53
	v_cvt_pk_bf16_f32 v41, v54, v55
	v_cvt_pk_bf16_f32 v42, v44, v45
	v_add_u32_e32 v44, 0x90, v120
	v_ashrrev_i32_e32 v45, 31, v44
	v_lshlrev_b64 v[44:45], 12, v[44:45]
	v_lshl_add_u64 v[44:45], s[2:3], 0, v[44:45]
	v_lshl_add_u64 v[44:45], v[44:45], 0, s[0:1]
	v_lshl_add_u64 v[44:45], v[44:45], 0, v[160:161]
	v_cvt_pk_bf16_f32 v43, v46, v47
	global_store_dwordx4 v[44:45], v[40:43], off
	v_cvt_pk_bf16_f32 v32, v32, v33
	v_cvt_pk_bf16_f32 v33, v34, v35
	v_cvt_pk_bf16_f32 v34, v24, v25
	v_cvt_pk_bf16_f32 v35, v26, v27
	global_store_dwordx4 v[44:45], v[32:35], off offset:256
	v_cvt_pk_bf16_f32 v24, v36, v37
	v_cvt_pk_bf16_f32 v25, v38, v39
	v_cvt_pk_bf16_f32 v26, v28, v29
	v_add_u32_e32 v28, 0xa0, v120
	v_ashrrev_i32_e32 v29, 31, v28
	v_lshlrev_b64 v[28:29], 12, v[28:29]
	v_lshl_add_u64 v[28:29], s[2:3], 0, v[28:29]
	v_lshl_add_u64 v[28:29], v[28:29], 0, s[0:1]
	v_lshl_add_u64 v[28:29], v[28:29], 0, v[160:161]
	v_cvt_pk_bf16_f32 v27, v30, v31
	global_store_dwordx4 v[28:29], v[24:27], off
	v_cvt_pk_bf16_f32 v16, v16, v17
	v_cvt_pk_bf16_f32 v17, v18, v19
	v_cvt_pk_bf16_f32 v18, v8, v9
	v_cvt_pk_bf16_f32 v19, v10, v11
	global_store_dwordx4 v[28:29], v[16:19], off offset:256
	v_cvt_pk_bf16_f32 v8, v20, v21
	v_cvt_pk_bf16_f32 v9, v22, v23
	v_cvt_pk_bf16_f32 v10, v12, v13
	v_add_u32_e32 v12, 0xb0, v120
	v_ashrrev_i32_e32 v13, 31, v12
	v_lshlrev_b64 v[12:13], 12, v[12:13]
	v_lshl_add_u64 v[12:13], s[2:3], 0, v[12:13]
	v_lshl_add_u64 v[12:13], v[12:13], 0, s[0:1]
	v_lshl_add_u64 v[12:13], v[12:13], 0, v[160:161]
	s_and_b64 vcc, exec, s[42:43]
	s_mov_b32 s8, s24
	s_mov_b32 s9, s26
	s_mov_b64 s[0:1], s[44:45]
	s_mov_b64 s[38:39], s[36:37]
	v_cvt_pk_bf16_f32 v11, v14, v15
	global_store_dwordx4 v[12:13], v[8:11], off
	v_cvt_pk_bf16_f32 v4, v4, v5
	v_cvt_pk_bf16_f32 v5, v6, v7
	v_cvt_pk_bf16_f32 v6, v0, v1
	v_cvt_pk_bf16_f32 v7, v2, v3
	global_store_dwordx4 v[12:13], v[4:7], off offset:256
	s_cbranch_vccz .LBB0_564
	s_waitcnt vmcnt(0)
	s_cmpk_gt_u32 s4, 0xff
	s_cbranch_scc1 .LBB0_571
	s_barrier

; #define PG8_STAGE_A(bufoff, ptr, half, rev) do { if (REVA && (rev)) { const char* _p = (ptr) - ((half) ? hstepA : 0); PG8_STAGE(bufoff, _p, voffAr); } else { const char* _p = (ptr) + ((half) ? hstepA : 0); PG8_STAGE(bufoff, _p, voffA); } } while (0)
; #define PG8_LDA(dst, b, h) do { _Pragma("unroll") for (int m = 0; m < 4; ++m) _Pragma("unroll") for (int k = 0; k < 2; ++k) dst[m][k] = *(const LAS bf16x8*)(lds + PG8_SA(b, h) + aoff + m * 2048 + k * 1024); } while (0)
; #define PG8_LDB(dst, b, h) do { _Pragma("unroll") for (int n = 0; n < 2; ++n) _Pragma("unroll") for (int k = 0; k < 2; ++k) dst[n][k] = *(const LAS bf16x8*)(lds + PG8_SB(b, h) + boff + n * 2048 + k * 1024); } while (0)
; #define PG8_SCHED __builtin_amdgcn_sched_barrier(0)
;     ...
;         const bool has_next = next_unit(ui + 1, nM, nN, MP, nxt, rot);
;         const char* nA = has_next ? nxt.a : cA; const char* nB = has_next ? nxt.b : cB; const char* nAr = has_next ? nxt.ar : cAr; const size_t nHb = has_next ? nxt.hb : cHb;
;         for (int t = 0; t < nt; t += 2) {
;             const bool last = (t == nt - 2);
;             const char* a1 = PG8_APTR(cA, cAr, t + 1); const bool r1 = REVA && ((t + 1) & 4);
;             const char* a2 = last ? nA : PG8_APTR(cA, cAr, t + 2); const bool r2 = REVA && !last && ((t + 2) & 4);
;             const char* a3 = last ? nA + kstep : PG8_APTR(cA, cAr, t + 3); const bool r3 = REVA && !last && ((t + 3) & 4);
;             const char* b2 = last ? nB : cB + (size_t)(t + 2) * kstep; const char* b3 = b2 + kstep; const size_t hb2 = last ? nHb : cHb;
;             PG8_LDB(B0, 0, 0); PG8_SCHED; PG8_LDA(At, 0, 0); PG8_STAGE_A(PG8_SA(1, 1), a1, 1, r1);
;     ...
; #pragma unroll
;         for (int a = 0; a < 2; ++a)
; #pragma unroll
;             for (int b = 0; b < 2; ++b)
; #pragma unroll
;                 for (int m = 0; m < 4; ++m)
; #pragma unroll
;                     for (int n = 0; n < 2; ++n) acc[a][b][m][n] = (f32x4){0.f, 0.f, 0.f, 0.f};
;         cur = nxt; cA = nA; cB = nB; cAr = nAr; cHb = nHb; ++ui;
.LBB0_902:
	s_add_u32 s8, s2, 0x80
	s_addc_u32 s9, s3, 0
	s_add_u32 s22, s0, 0x100
	s_addc_u32 s27, s1, 0
	s_add_u32 s0, s38, 0x80080
	s_addc_u32 s1, s39, 0
	v_mov_b32_e32 v0, 0
	v_lshl_add_u64 v[140:141], s[0:1], 0, v[136:137]
	v_lshl_add_u64 v[142:143], s[0:1], 0, v[138:139]
	s_mov_b32 s44, -2
	s_mov_b64 s[0:1], 0
	v_mov_b32_e32 v1, v0
	v_pk_mov_b32 v[2:3], v[0:1], v[0:1]
	v_pk_mov_b32 v[4:5], v[0:1], v[0:1]
	v_pk_mov_b32 v[6:7], v[0:1], v[0:1]
	v_pk_mov_b32 v[8:9], v[0:1], v[0:1]
	v_pk_mov_b32 v[10:11], v[0:1], v[0:1]
	v_pk_mov_b32 v[12:13], v[0:1], v[0:1]
	v_pk_mov_b32 v[14:15], v[0:1], v[0:1]
	v_pk_mov_b32 v[16:17], v[0:1], v[0:1]
	v_pk_mov_b32 v[18:19], v[0:1], v[0:1]
	v_pk_mov_b32 v[20:21], v[0:1], v[0:1]
	v_pk_mov_b32 v[22:23], v[0:1], v[0:1]
	v_pk_mov_b32 v[24:25], v[0:1], v[0:1]
	v_pk_mov_b32 v[26:27], v[0:1], v[0:1]
	v_pk_mov_b32 v[28:29], v[0:1], v[0:1]
	v_pk_mov_b32 v[30:31], v[0:1], v[0:1]
	v_pk_mov_b32 v[32:33], v[0:1], v[0:1]
	v_pk_mov_b32 v[34:35], v[0:1], v[0:1]
	v_pk_mov_b32 v[36:37], v[0:1], v[0:1]
	v_pk_mov_b32 v[38:39], v[0:1], v[0:1]
	v_pk_mov_b32 v[40:41], v[0:1], v[0:1]
	v_pk_mov_b32 v[42:43], v[0:1], v[0:1]
	v_pk_mov_b32 v[44:45], v[0:1], v[0:1]
	v_pk_mov_b32 v[46:47], v[0:1], v[0:1]
	v_pk_mov_b32 v[48:49], v[0:1], v[0:1]
	v_pk_mov_b32 v[50:51], v[0:1], v[0:1]
	v_pk_mov_b32 v[52:53], v[0:1], v[0:1]
	v_pk_mov_b32 v[54:55], v[0:1], v[0:1]
	v_pk_mov_b32 v[56:57], v[0:1], v[0:1]
	v_pk_mov_b32 v[58:59], v[0:1], v[0:1]
	v_pk_mov_b32 v[60:61], v[0:1], v[0:1]
	v_pk_mov_b32 v[62:63], v[0:1], v[0:1]
	v_pk_mov_b32 v[64:65], v[0:1], v[0:1]
	v_pk_mov_b32 v[66:67], v[0:1], v[0:1]
	v_pk_mov_b32 v[68:69], v[0:1], v[0:1]
	v_pk_mov_b32 v[70:71], v[0:1], v[0:1]
	v_pk_mov_b32 v[72:73], v[0:1], v[0:1]
	v_pk_mov_b32 v[74:75], v[0:1], v[0:1]
	v_pk_mov_b32 v[76:77], v[0:1], v[0:1]
	v_pk_mov_b32 v[78:79], v[0:1], v[0:1]
	v_pk_mov_b32 v[80:81], v[0:1], v[0:1]
	v_pk_mov_b32 v[82:83], v[0:1], v[0:1]
	v_pk_mov_b32 v[84:85], v[0:1], v[0:1]
	v_pk_mov_b32 v[86:87], v[0:1], v[0:1]
	v_pk_mov_b32 v[88:89], v[0:1], v[0:1]
	v_pk_mov_b32 v[90:91], v[0:1], v[0:1]
	v_pk_mov_b32 v[92:93], v[0:1], v[0:1]
	v_pk_mov_b32 v[94:95], v[0:1], v[0:1]
	v_pk_mov_b32 v[96:97], v[0:1], v[0:1]
	v_pk_mov_b32 v[98:99], v[0:1], v[0:1]
	v_pk_mov_b32 v[100:101], v[0:1], v[0:1]
	v_pk_mov_b32 v[102:103], v[0:1], v[0:1]
	v_pk_mov_b32 v[104:105], v[0:1], v[0:1]
	v_pk_mov_b32 v[106:107], v[0:1], v[0:1]
	v_pk_mov_b32 v[108:109], v[0:1], v[0:1]
	v_pk_mov_b32 v[110:111], v[0:1], v[0:1]
	v_pk_mov_b32 v[112:113], v[0:1], v[0:1]
	v_pk_mov_b32 v[114:115], v[0:1], v[0:1]
	v_pk_mov_b32 v[116:117], v[0:1], v[0:1]
	v_pk_mov_b32 v[118:119], v[0:1], v[0:1]
	v_pk_mov_b32 v[120:121], v[0:1], v[0:1]
	v_pk_mov_b32 v[122:123], v[0:1], v[0:1]
	v_pk_mov_b32 v[124:125], v[0:1], v[0:1]
	v_pk_mov_b32 v[126:127], v[0:1], v[0:1]
	v_add_u32_e32 v158, 0x10000, v145
	ds_read_b128 v[154:157], v158
	ds_read_b128 v[168:171], v158 offset:1024
	ds_read_b128 v[172:175], v158 offset:2048
	ds_read_b128 v[176:179], v158 offset:3072
	s_branch .LBB0_903

; #define PG8_STAGE(bufoff, gbase, voff) do { _Pragma("unroll") for (int _i = 0; _i < 2; ++_i) \
;         __builtin_amdgcn_global_load_lds((const unsigned*)((const char*)(gbase) + (voff)[_i]), (LAS unsigned*)(lds + (bufoff) + ldsw + _i * 8192), 16, 0, 0); } while (0)
; #define PG8_STAGE_A(bufoff, ptr, half, rev) do { if (REVA && (rev)) { const char* _p = (ptr) - ((half) ? hstepA : 0); PG8_STAGE(bufoff, _p, voffAr); } else { const char* _p = (ptr) + ((half) ? hstepA : 0); PG8_STAGE(bufoff, _p, voffA); } } while (0)
; #define PG8_LDA(dst, b, h) do { _Pragma("unroll") for (int m = 0; m < 4; ++m) _Pragma("unroll") for (int k = 0; k < 2; ++k) dst[m][k] = *(const LAS bf16x8*)(lds + PG8_SA(b, h) + aoff + m * 2048 + k * 1024); } while (0)
; #define PG8_LDB(dst, b, h) do { _Pragma("unroll") for (int n = 0; n < 2; ++n) _Pragma("unroll") for (int k = 0; k < 2; ++k) dst[n][k] = *(const LAS bf16x8*)(lds + PG8_SB(b, h) + boff + n * 2048 + k * 1024); } while (0)
; #define PG8_WAIT_V(n) asm volatile("s_waitcnt vmcnt(" #n ")" ::: "memory")
; #define PG8_WAIT_L(n) asm volatile("s_waitcnt lgkmcnt(" #n ")" ::: "memory")
; #define PG8_BAR __builtin_amdgcn_s_barrier()
;     ...
;         for (int t = 0; t < nt; t += 2) {
;             const bool last = (t == nt - 2);
;             const char* a1 = PG8_APTR(cA, cAr, t + 1); const bool r1 = REVA && ((t + 1) & 4);
;             const char* a2 = last ? nA : PG8_APTR(cA, cAr, t + 2); const bool r2 = REVA && !last && ((t + 2) & 4);
;             const char* a3 = last ? nA + kstep : PG8_APTR(cA, cAr, t + 3); const bool r3 = REVA && !last && ((t + 3) & 4);
;             const char* b2 = last ? nB : cB + (size_t)(t + 2) * kstep; const char* b3 = b2 + kstep; const size_t hb2 = last ? nHb : cHb;
;             PG8_LDB(B0, 0, 0); PG8_SCHED; PG8_LDA(At, 0, 0); PG8_STAGE_A(PG8_SA(1, 1), a1, 1, r1);
;             PG8_WAIT_L(8); PG8_BAR; PG8_WAIT_L(0); PG8_MMA(0, 0, At, B0); PG8_BAR; PG8_SCHED;
;             PG8_LDB(B1, 0, 1); PG8_STAGE(PG8_SB(0, 0), b2, voffB);
;             PG8_BAR; PG8_WAIT_L(0); PG8_MMA(0, 1, At, B1); PG8_BAR;
;             PG8_LDA(At, 0, 1); PG8_STAGE_A(PG8_SA(0, 0), a2, 0, r2);
;             PG8_BAR; PG8_WAIT_L(0); PG8_MMA(1, 0, At, B0); PG8_BAR; PG8_SCHED;
;             PG8_STAGE(PG8_SB(0, 1), b2 + hb2, voffB);
;             PG8_WAIT_V(6); PG8_BAR; PG8_MMA(1, 1, At, B1); PG8_BAR;
.LBB0_903:
	s_add_u32 s10, s38, s0
	s_addc_u32 s11, s39, s1
	s_add_u32 s20, s10, 0x100
	s_addc_u32 s21, s11, 0
	s_add_u32 s10, s10, 0x180
	s_addc_u32 s11, s11, 0
	s_add_u32 s14, s22, s0
	s_addc_u32 s15, s27, s1
	s_add_i32 s45, 0, 0x10000
	s_cmpk_eq_i32 s0, 0xf00
	s_cselect_b32 s15, s37, s15
	s_cselect_b32 s14, s36, s14
	s_cselect_b32 s17, s9, s11
	s_cselect_b32 s16, s8, s10
	s_cselect_b32 s21, s3, s21
	s_cselect_b32 s20, s2, s20
	v_lshl_add_u64 v[158:159], v[140:141], 0, s[0:1]
	s_add_i32 m0, s48, 0xc000
	ds_read_b128 v[180:183], v153
	ds_read_b128 v[204:207], v153 offset:1024
	ds_read_b128 v[208:211], v153 offset:2048
	ds_read_b128 v[212:215], v153 offset:3072
	ds_read_b128 v[216:219], v153 offset:4096
	ds_read_b128 v[220:223], v153 offset:5120
	ds_read_b128 v[224:227], v153 offset:6144
	ds_read_b128 v[228:231], v153 offset:7168
	global_load_lds_dwordx4 v[158:159], off
	v_lshl_add_u64 v[158:159], v[142:143], 0, s[0:1]
	s_add_i32 m0, s48, 0xe000
	s_nop 0
	global_load_lds_dwordx4 v[158:159], off
	s_waitcnt lgkmcnt(8)
	s_waitcnt vmcnt(10)
	s_barrier
	s_waitcnt lgkmcnt(0)
	v_mfma_f32_16x16x32_bf16 v[124:127], v[154:157], v[180:183], v[124:127]
	v_mfma_f32_16x16x32_bf16 v[120:123], v[172:175], v[180:183], v[120:123]
	v_mfma_f32_16x16x32_bf16 v[108:111], v[154:157], v[208:211], v[108:111]
	v_mfma_f32_16x16x32_bf16 v[104:107], v[172:175], v[208:211], v[104:107]
	v_mfma_f32_16x16x32_bf16 v[92:95], v[154:157], v[216:219], v[92:95]
	v_mfma_f32_16x16x32_bf16 v[88:91], v[172:175], v[216:219], v[88:91]
	v_mfma_f32_16x16x32_bf16 v[76:79], v[154:157], v[224:227], v[76:79]
	v_mfma_f32_16x16x32_bf16 v[72:75], v[172:175], v[224:227], v[72:75]
	v_mfma_f32_16x16x32_bf16 v[124:127], v[168:171], v[204:207], v[124:127]
	v_mfma_f32_16x16x32_bf16 v[120:123], v[176:179], v[204:207], v[120:123]
	v_mfma_f32_16x16x32_bf16 v[108:111], v[168:171], v[212:215], v[108:111]
	v_mfma_f32_16x16x32_bf16 v[104:107], v[176:179], v[212:215], v[104:107]
	v_mfma_f32_16x16x32_bf16 v[92:95], v[168:171], v[220:223], v[92:95]
	v_mfma_f32_16x16x32_bf16 v[88:91], v[176:179], v[220:223], v[88:91]
	v_mfma_f32_16x16x32_bf16 v[76:79], v[168:171], v[228:231], v[76:79]
	v_mfma_f32_16x16x32_bf16 v[72:75], v[176:179], v[228:231], v[72:75]
	s_barrier
	s_add_i32 s10, 0, 0x14000
	v_add_u32_e32 v158, s10, v145
	s_add_i32 s11, s45, s47
	ds_read_b128 v[232:235], v158
	ds_read_b128 v[236:239], v158 offset:1024
	ds_read_b128 v[240:243], v158 offset:2048
	ds_read_b128 v[244:247], v158 offset:3072
	v_lshl_add_u64 v[158:159], s[14:15], 0, v[130:131]
	s_mov_b32 m0, s11
	v_lshl_add_u64 v[184:185], s[14:15], 0, v[134:135]
	global_load_lds_dwordx4 v[158:159], off
	s_add_i32 m0, s11, 0x2000
	s_nop 0
	global_load_lds_dwordx4 v[184:185], off
	s_waitcnt vmcnt(10)
	s_barrier
	s_waitcnt lgkmcnt(0)
	v_mfma_f32_16x16x32_bf16 v[116:119], v[232:235], v[180:183], v[116:119]
	v_mfma_f32_16x16x32_bf16 v[112:115], v[240:243], v[180:183], v[112:115]
	v_mfma_f32_16x16x32_bf16 v[100:103], v[232:235], v[208:211], v[100:103]
	v_mfma_f32_16x16x32_bf16 v[96:99], v[240:243], v[208:211], v[96:99]
	v_mfma_f32_16x16x32_bf16 v[84:87], v[232:235], v[216:219], v[84:87]
	v_mfma_f32_16x16x32_bf16 v[80:83], v[240:243], v[216:219], v[80:83]
	v_mfma_f32_16x16x32_bf16 v[68:71], v[232:235], v[224:227], v[68:71]
	v_mfma_f32_16x16x32_bf16 v[64:67], v[240:243], v[224:227], v[64:67]
	v_mfma_f32_16x16x32_bf16 v[116:119], v[236:239], v[204:207], v[116:119]
	v_mfma_f32_16x16x32_bf16 v[112:115], v[244:247], v[204:207], v[112:115]
	v_mfma_f32_16x16x32_bf16 v[100:103], v[236:239], v[212:215], v[100:103]
	v_mfma_f32_16x16x32_bf16 v[96:99], v[244:247], v[212:215], v[96:99]
	v_mfma_f32_16x16x32_bf16 v[84:87], v[236:239], v[220:223], v[84:87]
	v_mfma_f32_16x16x32_bf16 v[80:83], v[244:247], v[220:223], v[80:83]
	v_mfma_f32_16x16x32_bf16 v[68:71], v[236:239], v[228:231], v[68:71]
	v_mfma_f32_16x16x32_bf16 v[64:67], v[244:247], v[228:231], v[64:67]
	s_mov_b32 m0, s48
	v_lshl_add_u64 v[190:191], s[20:21], 0, v[128:129]
	s_barrier
	ds_read_b128 v[180:183], v153 offset:16384
	ds_read_b128 v[204:207], v153 offset:17408
	ds_read_b128 v[208:211], v153 offset:18432
	ds_read_b128 v[212:215], v153 offset:19456
	ds_read_b128 v[216:219], v153 offset:20480
	ds_read_b128 v[220:223], v153 offset:21504
	ds_read_b128 v[224:227], v153 offset:22528
	ds_read_b128 v[228:231], v153 offset:23552
	global_load_lds_dwordx4 v[190:191], off
	v_lshl_add_u64 v[190:191], s[20:21], 0, v[132:133]
	s_mov_b32 m0, s49
	s_nop 0
	global_load_lds_dwordx4 v[190:191], off
	s_waitcnt vmcnt(10)
	s_barrier
	s_waitcnt lgkmcnt(0)
	v_mfma_f32_16x16x32_bf16 v[60:63], v[154:157], v[180:183], v[60:63]
	v_mfma_f32_16x16x32_bf16 v[56:59], v[172:175], v[180:183], v[56:59]
	v_mfma_f32_16x16x32_bf16 v[44:47], v[154:157], v[208:211], v[44:47]
	v_mfma_f32_16x16x32_bf16 v[40:43], v[172:175], v[208:211], v[40:43]
	v_mfma_f32_16x16x32_bf16 v[28:31], v[154:157], v[216:219], v[28:31]
	v_mfma_f32_16x16x32_bf16 v[24:27], v[172:175], v[216:219], v[24:27]
	v_mfma_f32_16x16x32_bf16 v[12:15], v[154:157], v[224:227], v[12:15]
	v_mfma_f32_16x16x32_bf16 v[8:11], v[172:175], v[224:227], v[8:11]
	v_mfma_f32_16x16x32_bf16 v[60:63], v[168:171], v[204:207], v[60:63]
	v_mfma_f32_16x16x32_bf16 v[56:59], v[176:179], v[204:207], v[56:59]
	v_mfma_f32_16x16x32_bf16 v[44:47], v[168:171], v[212:215], v[44:47]
	v_mfma_f32_16x16x32_bf16 v[40:43], v[176:179], v[212:215], v[40:43]
	v_mfma_f32_16x16x32_bf16 v[28:31], v[168:171], v[220:223], v[28:31]
	v_mfma_f32_16x16x32_bf16 v[24:27], v[176:179], v[220:223], v[24:27]
	v_mfma_f32_16x16x32_bf16 v[12:15], v[168:171], v[228:231], v[12:15]
	v_mfma_f32_16x16x32_bf16 v[8:11], v[176:179], v[228:231], v[8:11]
	s_barrier
; #define PG8_STAGE(bufoff, gbase, voff) do { _Pragma("unroll") for (int _i = 0; _i < 2; ++_i) \
;         __builtin_amdgcn_global_load_lds((const unsigned*)((const char*)(gbase) + (voff)[_i]), (LAS unsigned*)(lds + (bufoff) + ldsw + _i * 8192), 16, 0, 0); } while (0)
; #define PG8_STAGE_A(bufoff, ptr, half, rev) do { if (REVA && (rev)) { const char* _p = (ptr) - ((half) ? hstepA : 0); PG8_STAGE(bufoff, _p, voffAr); } else { const char* _p = (ptr) + ((half) ? hstepA : 0); PG8_STAGE(bufoff, _p, voffA); } } while (0)
; #define PG8_LDA(dst, b, h) do { _Pragma("unroll") for (int m = 0; m < 4; ++m) _Pragma("unroll") for (int k = 0; k < 2; ++k) dst[m][k] = *(const LAS bf16x8*)(lds + PG8_SA(b, h) + aoff + m * 2048 + k * 1024); } while (0)
; #define PG8_LDB(dst, b, h) do { _Pragma("unroll") for (int n = 0; n < 2; ++n) _Pragma("unroll") for (int k = 0; k < 2; ++k) dst[n][k] = *(const LAS bf16x8*)(lds + PG8_SB(b, h) + boff + n * 2048 + k * 1024); } while (0)
; #define PG8_MMA(ai, bj, At, Bt) do { __builtin_amdgcn_s_setprio(1); _Pragma("unroll") for (int m = 0; m < 4; ++m) _Pragma("unroll") for (int n = 0; n < 2; ++n) _Pragma("unroll") for (int k = 0; k < 2; ++k) \
;         acc[ai][bj][m][n] = __builtin_amdgcn_mfma_f32_16x16x32_bf16(Bt[n][k], At[m][k], acc[ai][bj][m][n], 0, 0, 0); __builtin_amdgcn_s_setprio(0); } while (0)
; #define PG8_WAIT_V(n) asm volatile("s_waitcnt vmcnt(" #n ")" ::: "memory")
; #define PG8_WAIT_L(n) asm volatile("s_waitcnt lgkmcnt(" #n ")" ::: "memory")
; #define PG8_BAR __builtin_amdgcn_s_barrier()
; #define PG8_SCHED __builtin_amdgcn_sched_barrier(0)
;     ...
;             PG8_WAIT_V(6); PG8_BAR; PG8_MMA(1, 1, At, B1); PG8_BAR;
;             PG8_LDB(B0, 1, 0); PG8_SCHED; PG8_LDA(At, 1, 0); PG8_STAGE_A(PG8_SA(0, 1), a2, 1, r2);
;             PG8_WAIT_L(8); PG8_BAR; PG8_WAIT_L(0); PG8_MMA(0, 0, At, B0); PG8_BAR; PG8_SCHED;
;             PG8_LDB(B1, 1, 1); PG8_STAGE(PG8_SB(1, 0), b3, voffB);
;             PG8_BAR; PG8_WAIT_L(0); PG8_MMA(0, 1, At, B1); PG8_BAR;
;             PG8_LDA(At, 1, 1); PG8_STAGE_A(PG8_SA(1, 0), a3, 0, r3);
;             PG8_BAR; PG8_WAIT_L(0); PG8_MMA(1, 0, At, B0); PG8_BAR; PG8_SCHED;
	s_add_u32 s70, s14, 0x880000
	s_addc_u32 s71, s15, 0
	s_add_i32 s10, s10, s47
	v_lshl_add_u64 v[154:155], s[70:71], 0, v[130:131]
	s_mov_b32 m0, s10
	s_nop 0
	global_load_lds_dwordx4 v[154:155], off
	v_lshl_add_u64 v[154:155], s[70:71], 0, v[134:135]
	s_add_i32 m0, s10, 0x2000
	s_nop 0
	global_load_lds_dwordx4 v[154:155], off
	v_add_u32_e32 v176, 0x18000, v145
	ds_read_b128 v[154:157], v176
	ds_read_b128 v[168:171], v176 offset:1024
	ds_read_b128 v[172:175], v176 offset:2048
	ds_read_b128 v[176:179], v176 offset:3072
	s_waitcnt vmcnt(10)
	s_barrier
	v_mfma_f32_16x16x32_bf16 v[52:55], v[232:235], v[180:183], v[52:55]
	v_mfma_f32_16x16x32_bf16 v[48:51], v[240:243], v[180:183], v[48:51]
	v_mfma_f32_16x16x32_bf16 v[36:39], v[232:235], v[208:211], v[36:39]
	v_mfma_f32_16x16x32_bf16 v[32:35], v[240:243], v[208:211], v[32:35]
	v_mfma_f32_16x16x32_bf16 v[20:23], v[232:235], v[216:219], v[20:23]
	v_mfma_f32_16x16x32_bf16 v[16:19], v[240:243], v[216:219], v[16:19]
	v_mfma_f32_16x16x32_bf16 v[4:7], v[232:235], v[224:227], v[4:7]
	v_mfma_f32_16x16x32_bf16 v[0:3], v[240:243], v[224:227], v[0:3]
	v_mfma_f32_16x16x32_bf16 v[52:55], v[236:239], v[204:207], v[52:55]
	v_mfma_f32_16x16x32_bf16 v[48:51], v[244:247], v[204:207], v[48:51]
	v_mfma_f32_16x16x32_bf16 v[36:39], v[236:239], v[212:215], v[36:39]
	v_mfma_f32_16x16x32_bf16 v[32:35], v[244:247], v[212:215], v[32:35]
	v_mfma_f32_16x16x32_bf16 v[20:23], v[236:239], v[220:223], v[20:23]
	v_mfma_f32_16x16x32_bf16 v[16:19], v[244:247], v[220:223], v[16:19]
	v_mfma_f32_16x16x32_bf16 v[4:7], v[236:239], v[228:231], v[4:7]
	v_mfma_f32_16x16x32_bf16 v[0:3], v[244:247], v[228:231], v[0:3]
	s_add_i32 s10, 0, 0x18000
	s_barrier
	s_add_u32 s20, s20, 0x80000
	s_addc_u32 s21, s21, 0
	s_mov_b32 m0, s50
	v_lshl_add_u64 v[190:191], s[20:21], 0, v[128:129]
	ds_read_b128 v[180:183], v153 offset:32768
	ds_read_b128 v[204:207], v153 offset:33792
	ds_read_b128 v[208:211], v153 offset:34816
	ds_read_b128 v[212:215], v153 offset:35840
	ds_read_b128 v[216:219], v153 offset:36864
	ds_read_b128 v[220:223], v153 offset:37888
	ds_read_b128 v[224:227], v153 offset:38912
	ds_read_b128 v[228:231], v153 offset:39936
	global_load_lds_dwordx4 v[190:191], off
	v_lshl_add_u64 v[190:191], s[20:21], 0, v[132:133]
	s_mov_b32 m0, s51
	s_nop 0
	global_load_lds_dwordx4 v[190:191], off
	s_waitcnt lgkmcnt(8)
	s_waitcnt vmcnt(10)
	s_barrier
	s_waitcnt lgkmcnt(0)
	v_mfma_f32_16x16x32_bf16 v[124:127], v[154:157], v[180:183], v[124:127]
	v_mfma_f32_16x16x32_bf16 v[120:123], v[172:175], v[180:183], v[120:123]
	v_mfma_f32_16x16x32_bf16 v[108:111], v[154:157], v[208:211], v[108:111]
	v_mfma_f32_16x16x32_bf16 v[104:107], v[172:175], v[208:211], v[104:107]
	v_mfma_f32_16x16x32_bf16 v[92:95], v[154:157], v[216:219], v[92:95]
	v_mfma_f32_16x16x32_bf16 v[88:91], v[172:175], v[216:219], v[88:91]
	v_mfma_f32_16x16x32_bf16 v[76:79], v[154:157], v[224:227], v[76:79]
	v_mfma_f32_16x16x32_bf16 v[72:75], v[172:175], v[224:227], v[72:75]
	v_mfma_f32_16x16x32_bf16 v[124:127], v[168:171], v[204:207], v[124:127]
	v_mfma_f32_16x16x32_bf16 v[120:123], v[176:179], v[204:207], v[120:123]
	v_mfma_f32_16x16x32_bf16 v[108:111], v[168:171], v[212:215], v[108:111]
	v_mfma_f32_16x16x32_bf16 v[104:107], v[176:179], v[212:215], v[104:107]
	v_mfma_f32_16x16x32_bf16 v[92:95], v[168:171], v[220:223], v[92:95]
	v_mfma_f32_16x16x32_bf16 v[88:91], v[176:179], v[220:223], v[88:91]
	v_mfma_f32_16x16x32_bf16 v[76:79], v[168:171], v[228:231], v[76:79]
	v_mfma_f32_16x16x32_bf16 v[72:75], v[176:179], v[228:231], v[72:75]
	s_barrier
	s_add_i32 s11, 0, 0x1c000
	s_add_i32 s10, s10, s47
	v_add_u32_e32 v190, s11, v145
	v_lshl_add_u64 v[158:159], v[158:159], 0, s[28:29]
	s_mov_b32 m0, s10
	ds_read_b128 v[232:235], v190
	ds_read_b128 v[236:239], v190 offset:1024
	ds_read_b128 v[240:243], v190 offset:2048
	ds_read_b128 v[244:247], v190 offset:3072
	global_load_lds_dwordx4 v[158:159], off
	v_lshl_add_u64 v[158:159], v[184:185], 0, s[28:29]
	s_add_i32 m0, s10, 0x2000
	s_nop 0
	global_load_lds_dwordx4 v[158:159], off
	s_waitcnt vmcnt(10)
	s_barrier
	s_waitcnt lgkmcnt(0)
	v_mfma_f32_16x16x32_bf16 v[116:119], v[232:235], v[180:183], v[116:119]
	v_mfma_f32_16x16x32_bf16 v[112:115], v[240:243], v[180:183], v[112:115]
	v_mfma_f32_16x16x32_bf16 v[100:103], v[232:235], v[208:211], v[100:103]
	v_mfma_f32_16x16x32_bf16 v[96:99], v[240:243], v[208:211], v[96:99]
	v_mfma_f32_16x16x32_bf16 v[84:87], v[232:235], v[216:219], v[84:87]
	v_mfma_f32_16x16x32_bf16 v[80:83], v[240:243], v[216:219], v[80:83]
	v_mfma_f32_16x16x32_bf16 v[68:71], v[232:235], v[224:227], v[68:71]
	v_mfma_f32_16x16x32_bf16 v[64:67], v[240:243], v[224:227], v[64:67]
	v_mfma_f32_16x16x32_bf16 v[116:119], v[236:239], v[204:207], v[116:119]
	v_mfma_f32_16x16x32_bf16 v[112:115], v[244:247], v[204:207], v[112:115]
	v_mfma_f32_16x16x32_bf16 v[100:103], v[236:239], v[212:215], v[100:103]
	v_mfma_f32_16x16x32_bf16 v[96:99], v[244:247], v[212:215], v[96:99]
	v_mfma_f32_16x16x32_bf16 v[84:87], v[236:239], v[220:223], v[84:87]
	v_mfma_f32_16x16x32_bf16 v[80:83], v[244:247], v[220:223], v[80:83]
	v_mfma_f32_16x16x32_bf16 v[68:71], v[236:239], v[228:231], v[68:71]
	v_mfma_f32_16x16x32_bf16 v[64:67], v[244:247], v[228:231], v[64:67]
	s_mov_b32 m0, s66
	v_lshl_add_u64 v[158:159], s[16:17], 0, v[128:129]
	s_barrier
; __device__ __forceinline__ unsigned cvt_pk_bf16(float lo, float hi) { unsigned r; asm volatile("v_cvt_pk_bf16_f32 %0, %1, %2" : "=v"(r) : "v"(lo), "v"(hi)); return r; }
; #define PG8_STAGE(bufoff, gbase, voff) do { _Pragma("unroll") for (int _i = 0; _i < 2; ++_i) \
;         __builtin_amdgcn_global_load_lds((const unsigned*)((const char*)(gbase) + (voff)[_i]), (LAS unsigned*)(lds + (bufoff) + ldsw + _i * 8192), 16, 0, 0); } while (0)
; #define PG8_MMA(ai, bj, At, Bt) do { __builtin_amdgcn_s_setprio(1); _Pragma("unroll") for (int m = 0; m < 4; ++m) _Pragma("unroll") for (int n = 0; n < 2; ++n) _Pragma("unroll") for (int k = 0; k < 2; ++k) \
;         acc[ai][bj][m][n] = __builtin_amdgcn_mfma_f32_16x16x32_bf16(Bt[n][k], At[m][k], acc[ai][bj][m][n], 0, 0, 0); __builtin_amdgcn_s_setprio(0); } while (0)
; #define PG8_WAIT_V(n) asm volatile("s_waitcnt vmcnt(" #n ")" ::: "memory")
; #define PG8_WAIT_L(n) asm volatile("s_waitcnt lgkmcnt(" #n ")" ::: "memory")
; #define PG8_BAR __builtin_amdgcn_s_barrier()
; #define PG8_SCHED __builtin_amdgcn_sched_barrier(0)
;     ...
;             PG8_BAR; PG8_WAIT_L(0); PG8_MMA(1, 0, At, B0); PG8_BAR; PG8_SCHED;
;             PG8_STAGE(PG8_SB(1, 1), b3 + hb2, voffB);
;             PG8_WAIT_V(6); PG8_BAR; PG8_MMA(1, 1, At, B1); PG8_BAR;
;     __device__ __forceinline__ void generic(const f32x4 (&acc)[2][2][4][2], const Unit& u, int wr, int wc, int fr, int fq) const {
;     ...
;                     } else if (MODE == 1) {
;                         const int b = u.pn >> 3, g = u.pn & 7, k = (Lb == 4096) ? (2 * ((u.pm & 7) * BM + rt) + (u.pm >> 3)) : (u.pm * BM + rt), rb = rowbase0 + b * (Lb + 1);
;                         u32x4 w; w.x = cvt_pk_bf16(v0[0], v0[1]); w.y = cvt_pk_bf16(v0[2], v0[3]); w.z = cvt_pk_bf16(v1[0], v1[1]); w.w = cvt_pk_bf16(v1[2], v1[3]);
;                         *(u32x4*)(O + (size_t)(rb + k) * 2048 + g * 256 + ct) = w;
;                         if (k == 0) *(u32x4*)(O + (size_t)(rb + Lb) * 2048 + g * 256 + ct) = w;
	ds_read_b128 v[180:183], v153 offset:49152
	ds_read_b128 v[204:207], v153 offset:50176
	ds_read_b128 v[208:211], v153 offset:51200
	ds_read_b128 v[212:215], v153 offset:52224
	ds_read_b128 v[216:219], v153 offset:53248
	ds_read_b128 v[220:223], v153 offset:54272
	ds_read_b128 v[224:227], v153 offset:55296
	ds_read_b128 v[228:231], v153 offset:56320
	global_load_lds_dwordx4 v[158:159], off
	v_lshl_add_u64 v[158:159], s[16:17], 0, v[132:133]
	s_mov_b32 m0, s67
	s_nop 0
	global_load_lds_dwordx4 v[158:159], off
	s_waitcnt vmcnt(10)
	s_barrier
	s_waitcnt lgkmcnt(0)
	v_mfma_f32_16x16x32_bf16 v[60:63], v[154:157], v[180:183], v[60:63]
	v_mfma_f32_16x16x32_bf16 v[56:59], v[172:175], v[180:183], v[56:59]
	v_mfma_f32_16x16x32_bf16 v[44:47], v[154:157], v[208:211], v[44:47]
	v_mfma_f32_16x16x32_bf16 v[40:43], v[172:175], v[208:211], v[40:43]
	v_mfma_f32_16x16x32_bf16 v[28:31], v[154:157], v[216:219], v[28:31]
	v_mfma_f32_16x16x32_bf16 v[24:27], v[172:175], v[216:219], v[24:27]
	v_mfma_f32_16x16x32_bf16 v[12:15], v[154:157], v[224:227], v[12:15]
	v_mfma_f32_16x16x32_bf16 v[8:11], v[172:175], v[224:227], v[8:11]
	v_mfma_f32_16x16x32_bf16 v[60:63], v[168:171], v[204:207], v[60:63]
	v_mfma_f32_16x16x32_bf16 v[56:59], v[176:179], v[204:207], v[56:59]
	v_mfma_f32_16x16x32_bf16 v[44:47], v[168:171], v[212:215], v[44:47]
	v_mfma_f32_16x16x32_bf16 v[40:43], v[176:179], v[212:215], v[40:43]
	v_mfma_f32_16x16x32_bf16 v[28:31], v[168:171], v[220:223], v[28:31]
	v_mfma_f32_16x16x32_bf16 v[24:27], v[176:179], v[220:223], v[24:27]
	v_mfma_f32_16x16x32_bf16 v[12:15], v[168:171], v[228:231], v[12:15]
	v_mfma_f32_16x16x32_bf16 v[8:11], v[176:179], v[228:231], v[8:11]
	s_barrier
	s_add_u32 s14, s14, 0x880080
	s_addc_u32 s15, s15, 0
	s_add_i32 s10, s11, s47
	v_lshl_add_u64 v[154:155], s[14:15], 0, v[130:131]
	s_mov_b32 m0, s10
	s_nop 0
	global_load_lds_dwordx4 v[154:155], off
	v_lshl_add_u64 v[154:155], s[14:15], 0, v[134:135]
	s_add_i32 m0, s10, 0x2000
	s_nop 0
	global_load_lds_dwordx4 v[154:155], off
	v_add_u32_e32 v158, 0x10000, v145
	ds_read_b128 v[154:157], v158
	ds_read_b128 v[168:171], v158 offset:1024
	ds_read_b128 v[172:175], v158 offset:2048
	ds_read_b128 v[176:179], v158 offset:3072
	s_waitcnt vmcnt(10)
	s_barrier
	v_mfma_f32_16x16x32_bf16 v[52:55], v[232:235], v[180:183], v[52:55]
	v_mfma_f32_16x16x32_bf16 v[48:51], v[240:243], v[180:183], v[48:51]
	v_mfma_f32_16x16x32_bf16 v[36:39], v[232:235], v[208:211], v[36:39]
	v_mfma_f32_16x16x32_bf16 v[32:35], v[240:243], v[208:211], v[32:35]
	v_mfma_f32_16x16x32_bf16 v[20:23], v[232:235], v[216:219], v[20:23]
	v_mfma_f32_16x16x32_bf16 v[16:19], v[240:243], v[216:219], v[16:19]
	v_mfma_f32_16x16x32_bf16 v[4:7], v[232:235], v[224:227], v[4:7]
	v_mfma_f32_16x16x32_bf16 v[0:3], v[240:243], v[224:227], v[0:3]
	v_mfma_f32_16x16x32_bf16 v[52:55], v[236:239], v[204:207], v[52:55]
	v_mfma_f32_16x16x32_bf16 v[48:51], v[244:247], v[204:207], v[48:51]
	v_mfma_f32_16x16x32_bf16 v[36:39], v[236:239], v[212:215], v[36:39]
	v_mfma_f32_16x16x32_bf16 v[32:35], v[244:247], v[212:215], v[32:35]
	v_mfma_f32_16x16x32_bf16 v[20:23], v[236:239], v[220:223], v[20:23]
	v_mfma_f32_16x16x32_bf16 v[16:19], v[244:247], v[220:223], v[16:19]
	v_mfma_f32_16x16x32_bf16 v[4:7], v[236:239], v[228:231], v[4:7]
	v_mfma_f32_16x16x32_bf16 v[0:3], v[244:247], v[228:231], v[0:3]
	s_add_i32 s44, s44, 2
	s_add_u32 s0, s0, 0x100
	s_addc_u32 s1, s1, 0
	s_cmp_gt_u32 s44, 29
	s_cbranch_scc0 .Lrot_903_bar
	s_barrier
	s_waitcnt lgkmcnt(0)
	s_lshl_b32 s1, s7, 8
	s_and_b32 s8, s1, 0x700
	s_ashr_i32 s0, s6, 3
	v_add_u32_e32 v140, s8, v144
	s_ashr_i32 s7, s7, 3
	v_lshl_add_u32 v140, v140, 1, s7
	s_mulk_i32 s0, 0x1001
	v_cvt_pk_bf16_f32 v124, v124, v125
	v_cvt_pk_bf16_f32 v125, v126, v127
	v_cvt_pk_bf16_f32 v126, v120, v121
	v_add_u32_e32 v120, s0, v140
	v_ashrrev_i32_e32 v121, 31, v120
	s_lshl_b32 s1, s6, 8
	v_lshlrev_b64 v[120:121], 12, v[120:121]
	s_and_b32 s1, s1, 0x700
	v_lshl_add_u64 v[120:121], s[24:25], 0, v[120:121]
	s_lshl_b32 s22, s1, 1
	v_lshl_add_u64 v[120:121], v[120:121], 0, s[22:23]
	v_lshl_add_u64 v[120:121], v[120:121], 0, v[160:161]
	v_cmp_eq_u32_e64 s[44:45], 0, v140
	v_cvt_pk_bf16_f32 v127, v122, v123
	global_store_dwordx4 v[120:121], v[124:127], off
	s_and_saveexec_b64 s[14:15], s[44:45]
	s_cbranch_execz .LBB0_906
	s_ashr_i32 s1, s0, 31
	s_lshl_b64 s[16:17], s[0:1], 12
	s_add_u32 s1, s24, s16
	s_addc_u32 s6, s25, s17
	s_add_u32 s16, s1, s22
	s_addc_u32 s17, s6, 0
	v_lshl_add_u64 v[122:123], s[16:17], 0, v[160:161]
	v_add_co_u32_e32 v122, vcc, 0x1000000, v122
	s_nop 1
	v_addc_co_u32_e32 v123, vcc, 0, v123, vcc
	global_store_dwordx4 v[122:123], v[124:127], off

; #define PG8_STAGE_A(bufoff, ptr, half, rev) do { if (REVA && (rev)) { const char* _p = (ptr) - ((half) ? hstepA : 0); PG8_STAGE(bufoff, _p, voffAr); } else { const char* _p = (ptr) + ((half) ? hstepA : 0); PG8_STAGE(bufoff, _p, voffA); } } while (0)
; #define PG8_LDA(dst, b, h) do { _Pragma("unroll") for (int m = 0; m < 4; ++m) _Pragma("unroll") for (int k = 0; k < 2; ++k) dst[m][k] = *(const LAS bf16x8*)(lds + PG8_SA(b, h) + aoff + m * 2048 + k * 1024); } while (0)
; #define PG8_LDB(dst, b, h) do { _Pragma("unroll") for (int n = 0; n < 2; ++n) _Pragma("unroll") for (int k = 0; k < 2; ++k) dst[n][k] = *(const LAS bf16x8*)(lds + PG8_SB(b, h) + boff + n * 2048 + k * 1024); } while (0)
; #define PG8_SCHED __builtin_amdgcn_sched_barrier(0)
;     ...
;         const bool has_next = next_unit(ui + 1, nM, nN, MP, nxt, rot);
;         const char* nA = has_next ? nxt.a : cA; const char* nB = has_next ? nxt.b : cB; const char* nAr = has_next ? nxt.ar : cAr; const size_t nHb = has_next ? nxt.hb : cHb;
;         for (int t = 0; t < nt; t += 2) {
;             const bool last = (t == nt - 2);
;             const char* a1 = PG8_APTR(cA, cAr, t + 1); const bool r1 = REVA && ((t + 1) & 4);
;             const char* a2 = last ? nA : PG8_APTR(cA, cAr, t + 2); const bool r2 = REVA && !last && ((t + 2) & 4);
;             const char* a3 = last ? nA + kstep : PG8_APTR(cA, cAr, t + 3); const bool r3 = REVA && !last && ((t + 3) & 4);
;             const char* b2 = last ? nB : cB + (size_t)(t + 2) * kstep; const char* b3 = b2 + kstep; const size_t hb2 = last ? nHb : cHb;
;             PG8_LDB(B0, 0, 0); PG8_SCHED; PG8_LDA(At, 0, 0); PG8_STAGE_A(PG8_SA(1, 1), a1, 1, r1);
;     ...
; #pragma unroll
;         for (int a = 0; a < 2; ++a)
; #pragma unroll
;             for (int b = 0; b < 2; ++b)
; #pragma unroll
;                 for (int m = 0; m < 4; ++m)
; #pragma unroll
;                     for (int n = 0; n < 2; ++n) acc[a][b][m][n] = (f32x4){0.f, 0.f, 0.f, 0.f};
;         cur = nxt; cA = nA; cB = nB; cAr = nAr; cHb = nHb; ++ui;
.LBB0_1131:
	s_add_u32 s6, s78, 0x80
	s_addc_u32 s7, s79, 0
	s_add_u32 s8, s0, 0x80080
	s_addc_u32 s9, s1, 0
	v_lshl_add_u64 v[96:97], s[8:9], 0, v[176:177]
	v_lshl_add_u64 v[98:99], s[8:9], 0, v[178:179]
	s_add_u32 s8, s2, 0x100
	v_mov_b32_e32 v0, 0
	s_addc_u32 s9, s3, 0
	s_mov_b32 s26, -2
	s_mov_b64 s[2:3], 0
	v_mov_b32_e32 v1, v0
	v_pk_mov_b32 v[2:3], v[0:1], v[0:1]
	v_pk_mov_b32 v[4:5], v[0:1], v[0:1]
	v_pk_mov_b32 v[6:7], v[0:1], v[0:1]
	v_pk_mov_b32 v[8:9], v[0:1], v[0:1]
	v_pk_mov_b32 v[10:11], v[0:1], v[0:1]
	v_pk_mov_b32 v[12:13], v[0:1], v[0:1]
	v_pk_mov_b32 v[14:15], v[0:1], v[0:1]
	v_pk_mov_b32 v[16:17], v[0:1], v[0:1]
	v_pk_mov_b32 v[18:19], v[0:1], v[0:1]
	v_pk_mov_b32 v[20:21], v[0:1], v[0:1]
	v_pk_mov_b32 v[22:23], v[0:1], v[0:1]
	v_pk_mov_b32 v[24:25], v[0:1], v[0:1]
	v_pk_mov_b32 v[26:27], v[0:1], v[0:1]
	v_pk_mov_b32 v[28:29], v[0:1], v[0:1]
	v_pk_mov_b32 v[30:31], v[0:1], v[0:1]
	v_pk_mov_b32 v[32:33], v[0:1], v[0:1]
	v_pk_mov_b32 v[34:35], v[0:1], v[0:1]
	v_pk_mov_b32 v[36:37], v[0:1], v[0:1]
	v_pk_mov_b32 v[38:39], v[0:1], v[0:1]
	v_pk_mov_b32 v[40:41], v[0:1], v[0:1]
	v_pk_mov_b32 v[42:43], v[0:1], v[0:1]
	v_pk_mov_b32 v[44:45], v[0:1], v[0:1]
	v_pk_mov_b32 v[46:47], v[0:1], v[0:1]
	v_pk_mov_b32 v[48:49], v[0:1], v[0:1]
	v_pk_mov_b32 v[50:51], v[0:1], v[0:1]
	v_pk_mov_b32 v[52:53], v[0:1], v[0:1]
	v_pk_mov_b32 v[54:55], v[0:1], v[0:1]
	v_pk_mov_b32 v[56:57], v[0:1], v[0:1]
	v_pk_mov_b32 v[58:59], v[0:1], v[0:1]
	v_pk_mov_b32 v[60:61], v[0:1], v[0:1]
	v_pk_mov_b32 v[62:63], v[0:1], v[0:1]
	v_pk_mov_b32 v[64:65], v[0:1], v[0:1]
	v_pk_mov_b32 v[66:67], v[0:1], v[0:1]
	v_pk_mov_b32 v[68:69], v[0:1], v[0:1]
	v_pk_mov_b32 v[70:71], v[0:1], v[0:1]
	v_pk_mov_b32 v[72:73], v[0:1], v[0:1]
	v_pk_mov_b32 v[74:75], v[0:1], v[0:1]
	v_pk_mov_b32 v[76:77], v[0:1], v[0:1]
	v_pk_mov_b32 v[78:79], v[0:1], v[0:1]
	v_pk_mov_b32 v[80:81], v[0:1], v[0:1]
	v_pk_mov_b32 v[82:83], v[0:1], v[0:1]
	v_pk_mov_b32 v[84:85], v[0:1], v[0:1]
	v_pk_mov_b32 v[86:87], v[0:1], v[0:1]
	v_pk_mov_b32 v[88:89], v[0:1], v[0:1]
	v_pk_mov_b32 v[90:91], v[0:1], v[0:1]
	v_pk_mov_b32 v[92:93], v[0:1], v[0:1]
	v_pk_mov_b32 v[94:95], v[0:1], v[0:1]
	v_pk_mov_b32 v[100:101], v[0:1], v[0:1]
	v_pk_mov_b32 v[102:103], v[0:1], v[0:1]
	v_pk_mov_b32 v[104:105], v[0:1], v[0:1]
	v_pk_mov_b32 v[106:107], v[0:1], v[0:1]
	v_pk_mov_b32 v[112:113], v[0:1], v[0:1]
	v_pk_mov_b32 v[114:115], v[0:1], v[0:1]
	v_pk_mov_b32 v[116:117], v[0:1], v[0:1]
	v_pk_mov_b32 v[118:119], v[0:1], v[0:1]
	v_pk_mov_b32 v[124:125], v[0:1], v[0:1]
	v_pk_mov_b32 v[126:127], v[0:1], v[0:1]
	v_pk_mov_b32 v[128:129], v[0:1], v[0:1]
	v_pk_mov_b32 v[130:131], v[0:1], v[0:1]
	v_pk_mov_b32 v[136:137], v[0:1], v[0:1]
	v_pk_mov_b32 v[138:139], v[0:1], v[0:1]
	v_pk_mov_b32 v[144:145], v[0:1], v[0:1]
	v_pk_mov_b32 v[146:147], v[0:1], v[0:1]
	s_nop 0
	v_add_u32_e32 v140, 0x10000, v205
	ds_read_b128 v[108:111], v140
	ds_read_b128 v[120:123], v140 offset:1024
	ds_read_b128 v[132:135], v140 offset:2048
	ds_read_b128 v[140:143], v140 offset:3072
	s_branch .LBB0_1132

; #define PG8_STAGE(bufoff, gbase, voff) do { _Pragma("unroll") for (int _i = 0; _i < 2; ++_i) \
;         __builtin_amdgcn_global_load_lds((const unsigned*)((const char*)(gbase) + (voff)[_i]), (LAS unsigned*)(lds + (bufoff) + ldsw + _i * 8192), 16, 0, 0); } while (0)
; #define PG8_STAGE_A(bufoff, ptr, half, rev) do { if (REVA && (rev)) { const char* _p = (ptr) - ((half) ? hstepA : 0); PG8_STAGE(bufoff, _p, voffAr); } else { const char* _p = (ptr) + ((half) ? hstepA : 0); PG8_STAGE(bufoff, _p, voffA); } } while (0)
; #define PG8_LDA(dst, b, h) do { _Pragma("unroll") for (int m = 0; m < 4; ++m) _Pragma("unroll") for (int k = 0; k < 2; ++k) dst[m][k] = *(const LAS bf16x8*)(lds + PG8_SA(b, h) + aoff + m * 2048 + k * 1024); } while (0)
; #define PG8_LDB(dst, b, h) do { _Pragma("unroll") for (int n = 0; n < 2; ++n) _Pragma("unroll") for (int k = 0; k < 2; ++k) dst[n][k] = *(const LAS bf16x8*)(lds + PG8_SB(b, h) + boff + n * 2048 + k * 1024); } while (0)
; #define PG8_WAIT_V(n) asm volatile("s_waitcnt vmcnt(" #n ")" ::: "memory")
; #define PG8_WAIT_L(n) asm volatile("s_waitcnt lgkmcnt(" #n ")" ::: "memory")
; #define PG8_BAR __builtin_amdgcn_s_barrier()
;     ...
;         for (int t = 0; t < nt; t += 2) {
;             const bool last = (t == nt - 2);
;             const char* a1 = PG8_APTR(cA, cAr, t + 1); const bool r1 = REVA && ((t + 1) & 4);
;             const char* a2 = last ? nA : PG8_APTR(cA, cAr, t + 2); const bool r2 = REVA && !last && ((t + 2) & 4);
;             const char* a3 = last ? nA + kstep : PG8_APTR(cA, cAr, t + 3); const bool r3 = REVA && !last && ((t + 3) & 4);
;             const char* b2 = last ? nB : cB + (size_t)(t + 2) * kstep; const char* b3 = b2 + kstep; const size_t hb2 = last ? nHb : cHb;
;             PG8_LDB(B0, 0, 0); PG8_SCHED; PG8_LDA(At, 0, 0); PG8_STAGE_A(PG8_SA(1, 1), a1, 1, r1);
;             PG8_WAIT_L(8); PG8_BAR; PG8_WAIT_L(0); PG8_MMA(0, 0, At, B0); PG8_BAR; PG8_SCHED;
;             PG8_LDB(B1, 0, 1); PG8_STAGE(PG8_SB(0, 0), b2, voffB);
;             PG8_BAR; PG8_WAIT_L(0); PG8_MMA(0, 1, At, B1); PG8_BAR;
;             PG8_LDA(At, 0, 1); PG8_STAGE_A(PG8_SA(0, 0), a2, 0, r2);
;             PG8_BAR; PG8_WAIT_L(0); PG8_MMA(1, 0, At, B0); PG8_BAR; PG8_SCHED;
;             PG8_STAGE(PG8_SB(0, 1), b2 + hb2, voffB);
;             PG8_WAIT_V(6); PG8_BAR; PG8_MMA(1, 1, At, B1); PG8_BAR;
.LBB0_1132:
	s_add_u32 s10, s0, s2
	s_addc_u32 s11, s1, s3
	s_add_u32 s16, s10, 0x100
	s_addc_u32 s17, s11, 0
	s_add_u32 s10, s10, 0x180
	s_addc_u32 s11, s11, 0
	s_add_u32 s14, s8, s2
	s_addc_u32 s15, s9, s3
	s_add_i32 s27, 0, 0x10000
	s_cmpk_eq_i32 s2, 0xf00
	s_cselect_b32 s15, s25, s15
	s_cselect_b32 s14, s24, s14
	s_cselect_b32 s21, s79, s17
	s_cselect_b32 s20, s78, s16
	s_cselect_b32 s17, s7, s11
	s_cselect_b32 s16, s6, s10
	v_lshl_add_u64 v[184:185], v[96:97], 0, s[2:3]
	s_add_i32 m0, s70, 0xc000
	ds_read_b128 v[148:151], v209
	ds_read_b128 v[152:155], v209 offset:1024
	ds_read_b128 v[156:159], v209 offset:2048
	ds_read_b128 v[180:183], v209 offset:3072
	ds_read_b128 v[210:213], v209 offset:4096
	ds_read_b128 v[214:217], v209 offset:5120
	ds_read_b128 v[218:221], v209 offset:6144
	ds_read_b128 v[222:225], v209 offset:7168
	global_load_lds_dwordx4 v[184:185], off
	v_lshl_add_u64 v[184:185], v[98:99], 0, s[2:3]
	s_add_i32 m0, s70, 0xe000
	s_nop 0
	global_load_lds_dwordx4 v[184:185], off
	s_waitcnt lgkmcnt(8)
	s_waitcnt vmcnt(10)
	s_barrier
	s_waitcnt lgkmcnt(0)
	v_mfma_f32_16x16x32_bf16 v[144:147], v[108:111], v[148:151], v[144:147]
	v_mfma_f32_16x16x32_bf16 v[136:139], v[132:135], v[148:151], v[136:139]
	v_mfma_f32_16x16x32_bf16 v[116:119], v[108:111], v[156:159], v[116:119]
	v_mfma_f32_16x16x32_bf16 v[112:115], v[132:135], v[156:159], v[112:115]
	v_mfma_f32_16x16x32_bf16 v[92:95], v[108:111], v[210:213], v[92:95]
	v_mfma_f32_16x16x32_bf16 v[88:91], v[132:135], v[210:213], v[88:91]
	v_mfma_f32_16x16x32_bf16 v[76:79], v[108:111], v[218:221], v[76:79]
	v_mfma_f32_16x16x32_bf16 v[72:75], v[132:135], v[218:221], v[72:75]
	v_mfma_f32_16x16x32_bf16 v[144:147], v[120:123], v[152:155], v[144:147]
	v_mfma_f32_16x16x32_bf16 v[136:139], v[140:143], v[152:155], v[136:139]
	v_mfma_f32_16x16x32_bf16 v[116:119], v[120:123], v[180:183], v[116:119]
	v_mfma_f32_16x16x32_bf16 v[112:115], v[140:143], v[180:183], v[112:115]
	v_mfma_f32_16x16x32_bf16 v[92:95], v[120:123], v[214:217], v[92:95]
	v_mfma_f32_16x16x32_bf16 v[88:91], v[140:143], v[214:217], v[88:91]
	v_mfma_f32_16x16x32_bf16 v[76:79], v[120:123], v[222:225], v[76:79]
	v_mfma_f32_16x16x32_bf16 v[72:75], v[140:143], v[222:225], v[72:75]
	s_barrier
	s_add_i32 s10, 0, 0x14000
	v_add_u32_e32 v184, s10, v205
	s_add_i32 s11, s27, s69
	ds_read_b128 v[226:229], v184
	ds_read_b128 v[230:233], v184 offset:1024
	ds_read_b128 v[234:237], v184 offset:2048
	ds_read_b128 v[238:241], v184 offset:3072
	v_lshl_add_u64 v[184:185], s[14:15], 0, v[172:173]
	s_mov_b32 m0, s11
	v_lshl_add_u64 v[190:191], s[14:15], 0, v[168:169]
	global_load_lds_dwordx4 v[184:185], off
	s_add_i32 m0, s11, 0x2000
	s_nop 0
	global_load_lds_dwordx4 v[190:191], off
	s_waitcnt vmcnt(10)
	s_barrier
	s_waitcnt lgkmcnt(0)
	v_mfma_f32_16x16x32_bf16 v[128:131], v[226:229], v[148:151], v[128:131]
	v_mfma_f32_16x16x32_bf16 v[124:127], v[234:237], v[148:151], v[124:127]
	v_mfma_f32_16x16x32_bf16 v[104:107], v[226:229], v[156:159], v[104:107]
	v_mfma_f32_16x16x32_bf16 v[100:103], v[234:237], v[156:159], v[100:103]
	v_mfma_f32_16x16x32_bf16 v[84:87], v[226:229], v[210:213], v[84:87]
	v_mfma_f32_16x16x32_bf16 v[80:83], v[234:237], v[210:213], v[80:83]
	v_mfma_f32_16x16x32_bf16 v[68:71], v[226:229], v[218:221], v[68:71]
	v_mfma_f32_16x16x32_bf16 v[64:67], v[234:237], v[218:221], v[64:67]
	v_mfma_f32_16x16x32_bf16 v[128:131], v[230:233], v[152:155], v[128:131]
	v_mfma_f32_16x16x32_bf16 v[124:127], v[238:241], v[152:155], v[124:127]
	v_mfma_f32_16x16x32_bf16 v[104:107], v[230:233], v[180:183], v[104:107]
	v_mfma_f32_16x16x32_bf16 v[100:103], v[238:241], v[180:183], v[100:103]
	v_mfma_f32_16x16x32_bf16 v[84:87], v[230:233], v[214:217], v[84:87]
	v_mfma_f32_16x16x32_bf16 v[80:83], v[238:241], v[214:217], v[80:83]
	v_mfma_f32_16x16x32_bf16 v[68:71], v[230:233], v[222:225], v[68:71]
	v_mfma_f32_16x16x32_bf16 v[64:67], v[238:241], v[222:225], v[64:67]
	s_mov_b32 m0, s70
	v_lshl_add_u64 v[242:243], s[20:21], 0, v[174:175]
	s_barrier
	ds_read_b128 v[148:151], v209 offset:16384
	ds_read_b128 v[152:155], v209 offset:17408
	ds_read_b128 v[156:159], v209 offset:18432
	ds_read_b128 v[180:183], v209 offset:19456
	ds_read_b128 v[210:213], v209 offset:20480
	ds_read_b128 v[214:217], v209 offset:21504
	ds_read_b128 v[218:221], v209 offset:22528
	ds_read_b128 v[222:225], v209 offset:23552
	global_load_lds_dwordx4 v[242:243], off
	v_lshl_add_u64 v[242:243], s[20:21], 0, v[170:171]
	s_mov_b32 m0, s71
	s_nop 0
	global_load_lds_dwordx4 v[242:243], off
	s_waitcnt vmcnt(10)
	s_barrier
	s_waitcnt lgkmcnt(0)
	v_mfma_f32_16x16x32_bf16 v[60:63], v[108:111], v[148:151], v[60:63]
	v_mfma_f32_16x16x32_bf16 v[56:59], v[132:135], v[148:151], v[56:59]
	v_mfma_f32_16x16x32_bf16 v[44:47], v[108:111], v[156:159], v[44:47]
	v_mfma_f32_16x16x32_bf16 v[40:43], v[132:135], v[156:159], v[40:43]
	v_mfma_f32_16x16x32_bf16 v[28:31], v[108:111], v[210:213], v[28:31]
	v_mfma_f32_16x16x32_bf16 v[24:27], v[132:135], v[210:213], v[24:27]
	v_mfma_f32_16x16x32_bf16 v[12:15], v[108:111], v[218:221], v[12:15]
	v_mfma_f32_16x16x32_bf16 v[8:11], v[132:135], v[218:221], v[8:11]
	v_mfma_f32_16x16x32_bf16 v[60:63], v[120:123], v[152:155], v[60:63]
	v_mfma_f32_16x16x32_bf16 v[56:59], v[140:143], v[152:155], v[56:59]
	v_mfma_f32_16x16x32_bf16 v[44:47], v[120:123], v[180:183], v[44:47]
	v_mfma_f32_16x16x32_bf16 v[40:43], v[140:143], v[180:183], v[40:43]
	v_mfma_f32_16x16x32_bf16 v[28:31], v[120:123], v[214:217], v[28:31]
	v_mfma_f32_16x16x32_bf16 v[24:27], v[140:143], v[214:217], v[24:27]
	v_mfma_f32_16x16x32_bf16 v[12:15], v[120:123], v[222:225], v[12:15]
	v_mfma_f32_16x16x32_bf16 v[8:11], v[140:143], v[222:225], v[8:11]
	s_barrier
; #define PG8_STAGE(bufoff, gbase, voff) do { _Pragma("unroll") for (int _i = 0; _i < 2; ++_i) \
;         __builtin_amdgcn_global_load_lds((const unsigned*)((const char*)(gbase) + (voff)[_i]), (LAS unsigned*)(lds + (bufoff) + ldsw + _i * 8192), 16, 0, 0); } while (0)
; #define PG8_STAGE_A(bufoff, ptr, half, rev) do { if (REVA && (rev)) { const char* _p = (ptr) - ((half) ? hstepA : 0); PG8_STAGE(bufoff, _p, voffAr); } else { const char* _p = (ptr) + ((half) ? hstepA : 0); PG8_STAGE(bufoff, _p, voffA); } } while (0)
; #define PG8_LDA(dst, b, h) do { _Pragma("unroll") for (int m = 0; m < 4; ++m) _Pragma("unroll") for (int k = 0; k < 2; ++k) dst[m][k] = *(const LAS bf16x8*)(lds + PG8_SA(b, h) + aoff + m * 2048 + k * 1024); } while (0)
; #define PG8_LDB(dst, b, h) do { _Pragma("unroll") for (int n = 0; n < 2; ++n) _Pragma("unroll") for (int k = 0; k < 2; ++k) dst[n][k] = *(const LAS bf16x8*)(lds + PG8_SB(b, h) + boff + n * 2048 + k * 1024); } while (0)
; #define PG8_MMA(ai, bj, At, Bt) do { __builtin_amdgcn_s_setprio(1); _Pragma("unroll") for (int m = 0; m < 4; ++m) _Pragma("unroll") for (int n = 0; n < 2; ++n) _Pragma("unroll") for (int k = 0; k < 2; ++k) \
;         acc[ai][bj][m][n] = __builtin_amdgcn_mfma_f32_16x16x32_bf16(Bt[n][k], At[m][k], acc[ai][bj][m][n], 0, 0, 0); __builtin_amdgcn_s_setprio(0); } while (0)
; #define PG8_WAIT_V(n) asm volatile("s_waitcnt vmcnt(" #n ")" ::: "memory")
; #define PG8_WAIT_L(n) asm volatile("s_waitcnt lgkmcnt(" #n ")" ::: "memory")
; #define PG8_BAR __builtin_amdgcn_s_barrier()
; #define PG8_SCHED __builtin_amdgcn_sched_barrier(0)
;     ...
;             PG8_WAIT_V(6); PG8_BAR; PG8_MMA(1, 1, At, B1); PG8_BAR;
;             PG8_LDB(B0, 1, 0); PG8_SCHED; PG8_LDA(At, 1, 0); PG8_STAGE_A(PG8_SA(0, 1), a2, 1, r2);
;             PG8_WAIT_L(8); PG8_BAR; PG8_WAIT_L(0); PG8_MMA(0, 0, At, B0); PG8_BAR; PG8_SCHED;
;             PG8_LDB(B1, 1, 1); PG8_STAGE(PG8_SB(1, 0), b3, voffB);
;             PG8_BAR; PG8_WAIT_L(0); PG8_MMA(0, 1, At, B1); PG8_BAR;
;             PG8_LDA(At, 1, 1); PG8_STAGE_A(PG8_SA(1, 0), a3, 0, r3);
;             PG8_BAR; PG8_WAIT_L(0); PG8_MMA(1, 0, At, B0); PG8_BAR; PG8_SCHED;
	s_add_u32 s36, s14, 0x80000
	s_addc_u32 s37, s15, 0
	s_add_i32 s10, s10, s69
	v_lshl_add_u64 v[108:109], s[36:37], 0, v[172:173]
	s_mov_b32 m0, s10
	s_nop 0
	global_load_lds_dwordx4 v[108:109], off
	v_lshl_add_u64 v[108:109], s[36:37], 0, v[168:169]
	s_add_i32 m0, s10, 0x2000
	s_nop 0
	global_load_lds_dwordx4 v[108:109], off
	v_add_u32_e32 v140, 0x18000, v205
	ds_read_b128 v[108:111], v140
	ds_read_b128 v[120:123], v140 offset:1024
	ds_read_b128 v[132:135], v140 offset:2048
	ds_read_b128 v[140:143], v140 offset:3072
	s_waitcnt vmcnt(10)
	s_barrier
	v_mfma_f32_16x16x32_bf16 v[52:55], v[226:229], v[148:151], v[52:55]
	v_mfma_f32_16x16x32_bf16 v[48:51], v[234:237], v[148:151], v[48:51]
	v_mfma_f32_16x16x32_bf16 v[36:39], v[226:229], v[156:159], v[36:39]
	v_mfma_f32_16x16x32_bf16 v[32:35], v[234:237], v[156:159], v[32:35]
	v_mfma_f32_16x16x32_bf16 v[20:23], v[226:229], v[210:213], v[20:23]
	v_mfma_f32_16x16x32_bf16 v[16:19], v[234:237], v[210:213], v[16:19]
	v_mfma_f32_16x16x32_bf16 v[4:7], v[226:229], v[218:221], v[4:7]
	v_mfma_f32_16x16x32_bf16 v[0:3], v[234:237], v[218:221], v[0:3]
	v_mfma_f32_16x16x32_bf16 v[52:55], v[230:233], v[152:155], v[52:55]
	v_mfma_f32_16x16x32_bf16 v[48:51], v[238:241], v[152:155], v[48:51]
	v_mfma_f32_16x16x32_bf16 v[36:39], v[230:233], v[180:183], v[36:39]
	v_mfma_f32_16x16x32_bf16 v[32:35], v[238:241], v[180:183], v[32:35]
	v_mfma_f32_16x16x32_bf16 v[20:23], v[230:233], v[214:217], v[20:23]
	v_mfma_f32_16x16x32_bf16 v[16:19], v[238:241], v[214:217], v[16:19]
	v_mfma_f32_16x16x32_bf16 v[4:7], v[230:233], v[222:225], v[4:7]
	v_mfma_f32_16x16x32_bf16 v[0:3], v[238:241], v[222:225], v[0:3]
	s_add_i32 s10, 0, 0x18000
	s_barrier
	s_add_u32 s20, s20, 0x80000
	s_addc_u32 s21, s21, 0
	s_mov_b32 m0, s89
	v_lshl_add_u64 v[226:227], s[20:21], 0, v[174:175]
	ds_read_b128 v[148:151], v209 offset:32768
	ds_read_b128 v[152:155], v209 offset:33792
	ds_read_b128 v[156:159], v209 offset:34816
	ds_read_b128 v[180:183], v209 offset:35840
	ds_read_b128 v[210:213], v209 offset:36864
	ds_read_b128 v[214:217], v209 offset:37888
	ds_read_b128 v[218:221], v209 offset:38912
	ds_read_b128 v[222:225], v209 offset:39936
	global_load_lds_dwordx4 v[226:227], off
	v_lshl_add_u64 v[226:227], s[20:21], 0, v[170:171]
	s_mov_b32 m0, s90
	s_nop 0
	global_load_lds_dwordx4 v[226:227], off
	s_waitcnt lgkmcnt(8)
	s_waitcnt vmcnt(10)
	s_barrier
	s_waitcnt lgkmcnt(0)
	v_mfma_f32_16x16x32_bf16 v[144:147], v[108:111], v[148:151], v[144:147]
	v_mfma_f32_16x16x32_bf16 v[136:139], v[132:135], v[148:151], v[136:139]
	v_mfma_f32_16x16x32_bf16 v[116:119], v[108:111], v[156:159], v[116:119]
	v_mfma_f32_16x16x32_bf16 v[112:115], v[132:135], v[156:159], v[112:115]
	v_mfma_f32_16x16x32_bf16 v[92:95], v[108:111], v[210:213], v[92:95]
	v_mfma_f32_16x16x32_bf16 v[88:91], v[132:135], v[210:213], v[88:91]
	v_mfma_f32_16x16x32_bf16 v[76:79], v[108:111], v[218:221], v[76:79]
	v_mfma_f32_16x16x32_bf16 v[72:75], v[132:135], v[218:221], v[72:75]
	v_mfma_f32_16x16x32_bf16 v[144:147], v[120:123], v[152:155], v[144:147]
	v_mfma_f32_16x16x32_bf16 v[136:139], v[140:143], v[152:155], v[136:139]
	v_mfma_f32_16x16x32_bf16 v[116:119], v[120:123], v[180:183], v[116:119]
	v_mfma_f32_16x16x32_bf16 v[112:115], v[140:143], v[180:183], v[112:115]
	v_mfma_f32_16x16x32_bf16 v[92:95], v[120:123], v[214:217], v[92:95]
	v_mfma_f32_16x16x32_bf16 v[88:91], v[140:143], v[214:217], v[88:91]
	v_mfma_f32_16x16x32_bf16 v[76:79], v[120:123], v[222:225], v[76:79]
	v_mfma_f32_16x16x32_bf16 v[72:75], v[140:143], v[222:225], v[72:75]
	s_barrier
	s_add_i32 s11, 0, 0x1c000
	s_add_i32 s10, s10, s69
	v_add_u32_e32 v238, s11, v205
	v_lshl_add_u64 v[184:185], v[184:185], 0, s[28:29]
	s_mov_b32 m0, s10
	ds_read_b128 v[226:229], v238
	ds_read_b128 v[230:233], v238 offset:1024
	ds_read_b128 v[234:237], v238 offset:2048
	ds_read_b128 v[238:241], v238 offset:3072
	global_load_lds_dwordx4 v[184:185], off
	v_lshl_add_u64 v[184:185], v[190:191], 0, s[28:29]
	s_add_i32 m0, s10, 0x2000
	s_nop 0
	global_load_lds_dwordx4 v[184:185], off
	s_waitcnt vmcnt(10)
	s_barrier
	s_waitcnt lgkmcnt(0)
	v_mfma_f32_16x16x32_bf16 v[128:131], v[226:229], v[148:151], v[128:131]
	v_mfma_f32_16x16x32_bf16 v[124:127], v[234:237], v[148:151], v[124:127]
	v_mfma_f32_16x16x32_bf16 v[104:107], v[226:229], v[156:159], v[104:107]
	v_mfma_f32_16x16x32_bf16 v[100:103], v[234:237], v[156:159], v[100:103]
	v_mfma_f32_16x16x32_bf16 v[84:87], v[226:229], v[210:213], v[84:87]
	v_mfma_f32_16x16x32_bf16 v[80:83], v[234:237], v[210:213], v[80:83]
	v_mfma_f32_16x16x32_bf16 v[68:71], v[226:229], v[218:221], v[68:71]
	v_mfma_f32_16x16x32_bf16 v[64:67], v[234:237], v[218:221], v[64:67]
	v_mfma_f32_16x16x32_bf16 v[128:131], v[230:233], v[152:155], v[128:131]
	v_mfma_f32_16x16x32_bf16 v[124:127], v[238:241], v[152:155], v[124:127]
	v_mfma_f32_16x16x32_bf16 v[104:107], v[230:233], v[180:183], v[104:107]
	v_mfma_f32_16x16x32_bf16 v[100:103], v[238:241], v[180:183], v[100:103]
	v_mfma_f32_16x16x32_bf16 v[84:87], v[230:233], v[214:217], v[84:87]
	v_mfma_f32_16x16x32_bf16 v[80:83], v[238:241], v[214:217], v[80:83]
	v_mfma_f32_16x16x32_bf16 v[68:71], v[230:233], v[222:225], v[68:71]
	v_mfma_f32_16x16x32_bf16 v[64:67], v[238:241], v[222:225], v[64:67]
	s_mov_b32 m0, s97
	v_lshl_add_u64 v[184:185], s[16:17], 0, v[174:175]
	s_barrier
; #define PG8_STAGE(bufoff, gbase, voff) do { _Pragma("unroll") for (int _i = 0; _i < 2; ++_i) \
;         __builtin_amdgcn_global_load_lds((const unsigned*)((const char*)(gbase) + (voff)[_i]), (LAS unsigned*)(lds + (bufoff) + ldsw + _i * 8192), 16, 0, 0); } while (0)
; #define PG8_MMA(ai, bj, At, Bt) do { __builtin_amdgcn_s_setprio(1); _Pragma("unroll") for (int m = 0; m < 4; ++m) _Pragma("unroll") for (int n = 0; n < 2; ++n) _Pragma("unroll") for (int k = 0; k < 2; ++k) \
;         acc[ai][bj][m][n] = __builtin_amdgcn_mfma_f32_16x16x32_bf16(Bt[n][k], At[m][k], acc[ai][bj][m][n], 0, 0, 0); __builtin_amdgcn_s_setprio(0); } while (0)
; #define PG8_WAIT_V(n) asm volatile("s_waitcnt vmcnt(" #n ")" ::: "memory")
; #define PG8_WAIT_L(n) asm volatile("s_waitcnt lgkmcnt(" #n ")" ::: "memory")
; #define PG8_BAR __builtin_amdgcn_s_barrier()
; #define PG8_SCHED __builtin_amdgcn_sched_barrier(0)
;     ...
;             PG8_BAR; PG8_WAIT_L(0); PG8_MMA(1, 0, At, B0); PG8_BAR; PG8_SCHED;
;             PG8_STAGE(PG8_SB(1, 1), b3 + hb2, voffB);
;             PG8_WAIT_V(6); PG8_BAR; PG8_MMA(1, 1, At, B1); PG8_BAR;
;     __device__ __forceinline__ void gates(const f32x4 (&acc)[2][2][4][2], const Unit& u, int wr, int wc, int fr, int fq) const {
;         const bool ret = u.pn < 8;
;         const bf16_t* mulp = ret ? (OFp + u.pn * BM) : (Y + (u.pn - 8) * BM);
; #pragma unroll
;         for (int ai = 0; ai < 2; ++ai) {
;             u32x4 yv[4][2]; float rs[4];
; #pragma unroll
;             for (int m = 0; m < 4; ++m) {
;                 const size_t row = (size_t)(u.pm * BM + ai * HALF + wr * 64 + m * 16 + fr);
; #pragma unroll
;                 for (int bj = 0; bj < 2; ++bj) yv[m][bj] = *(const u32x4*)(mulp + row * 2048 + bj * HALF + wc * 32 + 8 * fq);
;                 rs[m] = 1.0f;
;                 if (ret) { const f32x4 sq = *(const f32x4*)(SSp + row * 32 + u.pn * 4); rs[m] = rsqrtf((sq[0] + sq[1] + sq[2] + sq[3]) * (1.0f / 256.0f) + 1e-6f); }
;             }
	ds_read_b128 v[148:151], v209 offset:49152
	ds_read_b128 v[152:155], v209 offset:50176
	ds_read_b128 v[156:159], v209 offset:51200
	ds_read_b128 v[180:183], v209 offset:52224
	ds_read_b128 v[210:213], v209 offset:53248
	ds_read_b128 v[214:217], v209 offset:54272
	ds_read_b128 v[218:221], v209 offset:55296
	ds_read_b128 v[222:225], v209 offset:56320
	global_load_lds_dwordx4 v[184:185], off
	v_lshl_add_u64 v[184:185], s[16:17], 0, v[170:171]
	s_mov_b32 m0, s52
	s_nop 0
	global_load_lds_dwordx4 v[184:185], off
	s_waitcnt vmcnt(10)
	s_barrier
	s_waitcnt lgkmcnt(0)
	v_mfma_f32_16x16x32_bf16 v[60:63], v[108:111], v[148:151], v[60:63]
	v_mfma_f32_16x16x32_bf16 v[56:59], v[132:135], v[148:151], v[56:59]
	v_mfma_f32_16x16x32_bf16 v[44:47], v[108:111], v[156:159], v[44:47]
	v_mfma_f32_16x16x32_bf16 v[40:43], v[132:135], v[156:159], v[40:43]
	v_mfma_f32_16x16x32_bf16 v[28:31], v[108:111], v[210:213], v[28:31]
	v_mfma_f32_16x16x32_bf16 v[24:27], v[132:135], v[210:213], v[24:27]
	v_mfma_f32_16x16x32_bf16 v[12:15], v[108:111], v[218:221], v[12:15]
	v_mfma_f32_16x16x32_bf16 v[8:11], v[132:135], v[218:221], v[8:11]
	v_mfma_f32_16x16x32_bf16 v[60:63], v[120:123], v[152:155], v[60:63]
	v_mfma_f32_16x16x32_bf16 v[56:59], v[140:143], v[152:155], v[56:59]
	v_mfma_f32_16x16x32_bf16 v[44:47], v[120:123], v[180:183], v[44:47]
	v_mfma_f32_16x16x32_bf16 v[40:43], v[140:143], v[180:183], v[40:43]
	v_mfma_f32_16x16x32_bf16 v[28:31], v[120:123], v[214:217], v[28:31]
	v_mfma_f32_16x16x32_bf16 v[24:27], v[140:143], v[214:217], v[24:27]
	v_mfma_f32_16x16x32_bf16 v[12:15], v[120:123], v[222:225], v[12:15]
	v_mfma_f32_16x16x32_bf16 v[8:11], v[140:143], v[222:225], v[8:11]
	s_barrier
	s_add_u32 s14, s14, 0x80080
	s_addc_u32 s15, s15, 0
	s_add_i32 s10, s11, s69
	v_lshl_add_u64 v[108:109], s[14:15], 0, v[172:173]
	s_mov_b32 m0, s10
	s_nop 0
	global_load_lds_dwordx4 v[108:109], off
	v_lshl_add_u64 v[108:109], s[14:15], 0, v[168:169]
	s_add_i32 m0, s10, 0x2000
	s_nop 0
	global_load_lds_dwordx4 v[108:109], off
	v_add_u32_e32 v140, 0x10000, v205
	ds_read_b128 v[108:111], v140
	ds_read_b128 v[120:123], v140 offset:1024
	ds_read_b128 v[132:135], v140 offset:2048
	ds_read_b128 v[140:143], v140 offset:3072
	s_waitcnt vmcnt(10)
	s_barrier
	v_mfma_f32_16x16x32_bf16 v[52:55], v[226:229], v[148:151], v[52:55]
	v_mfma_f32_16x16x32_bf16 v[48:51], v[234:237], v[148:151], v[48:51]
	v_mfma_f32_16x16x32_bf16 v[36:39], v[226:229], v[156:159], v[36:39]
	v_mfma_f32_16x16x32_bf16 v[32:35], v[234:237], v[156:159], v[32:35]
	v_mfma_f32_16x16x32_bf16 v[20:23], v[226:229], v[210:213], v[20:23]
	v_mfma_f32_16x16x32_bf16 v[16:19], v[234:237], v[210:213], v[16:19]
	v_mfma_f32_16x16x32_bf16 v[4:7], v[226:229], v[218:221], v[4:7]
	v_mfma_f32_16x16x32_bf16 v[0:3], v[234:237], v[218:221], v[0:3]
	v_mfma_f32_16x16x32_bf16 v[52:55], v[230:233], v[152:155], v[52:55]
	v_mfma_f32_16x16x32_bf16 v[48:51], v[238:241], v[152:155], v[48:51]
	v_mfma_f32_16x16x32_bf16 v[36:39], v[230:233], v[180:183], v[36:39]
	v_mfma_f32_16x16x32_bf16 v[32:35], v[238:241], v[180:183], v[32:35]
	v_mfma_f32_16x16x32_bf16 v[20:23], v[230:233], v[214:217], v[20:23]
	v_mfma_f32_16x16x32_bf16 v[16:19], v[238:241], v[214:217], v[16:19]
	v_mfma_f32_16x16x32_bf16 v[4:7], v[230:233], v[222:225], v[4:7]
	v_mfma_f32_16x16x32_bf16 v[0:3], v[238:241], v[222:225], v[0:3]
	s_add_i32 s26, s26, 2
	s_add_u32 s2, s2, 0x100
	s_addc_u32 s3, s3, 0
	s_cmp_gt_u32 s26, 29
	s_cbranch_scc0 .Lrot_1132_bar
	s_barrier
	s_waitcnt lgkmcnt(0)
	s_nop 0
	s_lshl_b32 s0, s4, 8
	s_ashr_i32 s1, s0, 31
	s_lshl_b64 s[26:27], s[0:1], 1
	s_add_u32 s6, s93, s26
	s_addc_u32 s7, s94, s27
	s_addk_i32 s0, 0xf800
	s_mov_b32 s1, s23
	s_lshl_b64 s[0:1], s[0:1], 1
	s_add_u32 s8, s91, s0
	s_addc_u32 s9, s92, s1
	s_cmp_lt_i32 s4, 8
	s_cselect_b64 s[0:1], -1, 0
	s_and_b64 s[2:3], s[0:1], exec
	s_cselect_b32 s3, s6, s8
	s_cselect_b32 s2, s7, s9
	s_add_u32 s6, s3, s22
	s_addc_u32 s7, s2, 0
	s_lshl_b32 s2, s5, 8
	v_add_u32_e32 v180, s2, v204
	v_ashrrev_i32_e32 v181, 31, v180
	v_lshl_add_u64 v[182:183], s[6:7], 0, v[160:161]
	v_lshlrev_b64 v[96:97], 12, v[180:181]
	v_lshl_add_u64 v[96:97], v[182:183], 0, v[96:97]
	global_load_dwordx4 v[156:159], v[96:97], off
	global_load_dwordx4 v[152:155], v[96:97], off offset:256
	s_lshl_b32 s6, s4, 2
	s_ashr_i32 s7, s6, 31
	s_lshl_b64 s[6:7], s[6:7], 2
	s_add_u32 s36, s95, s6
	s_addc_u32 s37, s96, s7
	s_cmp_gt_i32 s4, 7
	v_mov_b32_e32 v212, 1.0
	v_mov_b32_e32 v213, 1.0
	s_cbranch_scc1 .LBB0_1135
	v_lshlrev_b64 v[96:97], 7, v[180:181]
	v_lshl_add_u64 v[96:97], s[36:37], 0, v[96:97]
	global_load_dwordx4 v[96:99], v[96:97], off
	s_waitcnt vmcnt(0)
	v_add_f32_e32 v96, v96, v97
	v_add_f32_e32 v96, v98, v96
	v_add_f32_e32 v96, v99, v96
	v_fmamk_f32 v96, v96, 0x3b800000, v194
	v_mul_f32_e32 v97, 0x4b800000, v96
	v_cmp_gt_f32_e32 vcc, s55, v96
	s_nop 1
	v_cndmask_b32_e32 v96, v96, v97, vcc
	v_rsq_f32_e32 v96, v96
	s_nop 0
	v_mul_f32_e32 v97, 0x45800000, v96
	v_cndmask_b32_e32 v213, v96, v97, vcc

; #define PG8_STAGE_A(bufoff, ptr, half, rev) do { if (REVA && (rev)) { const char* _p = (ptr) - ((half) ? hstepA : 0); PG8_STAGE(bufoff, _p, voffAr); } else { const char* _p = (ptr) + ((half) ? hstepA : 0); PG8_STAGE(bufoff, _p, voffA); } } while (0)
; #define PG8_LDA(dst, b, h) do { _Pragma("unroll") for (int m = 0; m < 4; ++m) _Pragma("unroll") for (int k = 0; k < 2; ++k) dst[m][k] = *(const LAS bf16x8*)(lds + PG8_SA(b, h) + aoff + m * 2048 + k * 1024); } while (0)
; #define PG8_LDB(dst, b, h) do { _Pragma("unroll") for (int n = 0; n < 2; ++n) _Pragma("unroll") for (int k = 0; k < 2; ++k) dst[n][k] = *(const LAS bf16x8*)(lds + PG8_SB(b, h) + boff + n * 2048 + k * 1024); } while (0)
; #define PG8_SCHED __builtin_amdgcn_sched_barrier(0)
;     ...
;         const bool has_next = next_unit(ui + 1, nM, nN, MP, nxt, rot);
;         const char* nA = has_next ? nxt.a : cA; const char* nB = has_next ? nxt.b : cB; const char* nAr = has_next ? nxt.ar : cAr; const size_t nHb = has_next ? nxt.hb : cHb;
;         for (int t = 0; t < nt; t += 2) {
;             const bool last = (t == nt - 2);
;             const char* a1 = PG8_APTR(cA, cAr, t + 1); const bool r1 = REVA && ((t + 1) & 4);
;             const char* a2 = last ? nA : PG8_APTR(cA, cAr, t + 2); const bool r2 = REVA && !last && ((t + 2) & 4);
;             const char* a3 = last ? nA + kstep : PG8_APTR(cA, cAr, t + 3); const bool r3 = REVA && !last && ((t + 3) & 4);
;             const char* b2 = last ? nB : cB + (size_t)(t + 2) * kstep; const char* b3 = b2 + kstep; const size_t hb2 = last ? nHb : cHb;
;             PG8_LDB(B0, 0, 0); PG8_SCHED; PG8_LDA(At, 0, 0); PG8_STAGE_A(PG8_SA(1, 1), a1, 1, r1);
;     ...
; #pragma unroll
;         for (int a = 0; a < 2; ++a)
; #pragma unroll
;             for (int b = 0; b < 2; ++b)
; #pragma unroll
;                 for (int m = 0; m < 4; ++m)
; #pragma unroll
;                     for (int n = 0; n < 2; ++n) acc[a][b][m][n] = (f32x4){0.f, 0.f, 0.f, 0.f};
;         cur = nxt; cA = nA; cB = nB; cAr = nAr; cHb = nHb; ++ui;
.LBB0_1228:
	s_add_u32 s3, s36, 0x80
	s_addc_u32 s27, s37, 0
	s_add_u32 s14, s0, 0x100080
	s_addc_u32 s15, s1, 0
	s_add_u32 s69, s20, 0x100
	v_mov_b32_e32 v0, 0
	v_lshl_add_u64 v[128:129], s[14:15], 0, v[154:155]
	v_lshl_add_u64 v[130:131], s[14:15], 0, v[156:157]
	s_addc_u32 s70, s21, 0
	s_mov_b32 s71, -2
	s_mov_b64 s[42:43], 0
	v_mov_b32_e32 v1, v0
	v_pk_mov_b32 v[2:3], v[0:1], v[0:1]
	v_pk_mov_b32 v[4:5], v[0:1], v[0:1]
	v_pk_mov_b32 v[6:7], v[0:1], v[0:1]
	v_pk_mov_b32 v[8:9], v[0:1], v[0:1]
	v_pk_mov_b32 v[10:11], v[0:1], v[0:1]
	v_pk_mov_b32 v[12:13], v[0:1], v[0:1]
	v_pk_mov_b32 v[14:15], v[0:1], v[0:1]
	v_pk_mov_b32 v[16:17], v[0:1], v[0:1]
	v_pk_mov_b32 v[18:19], v[0:1], v[0:1]
	v_pk_mov_b32 v[20:21], v[0:1], v[0:1]
	v_pk_mov_b32 v[22:23], v[0:1], v[0:1]
	v_pk_mov_b32 v[24:25], v[0:1], v[0:1]
	v_pk_mov_b32 v[26:27], v[0:1], v[0:1]
	v_pk_mov_b32 v[28:29], v[0:1], v[0:1]
	v_pk_mov_b32 v[30:31], v[0:1], v[0:1]
	v_pk_mov_b32 v[32:33], v[0:1], v[0:1]
	v_pk_mov_b32 v[34:35], v[0:1], v[0:1]
	v_pk_mov_b32 v[36:37], v[0:1], v[0:1]
	v_pk_mov_b32 v[38:39], v[0:1], v[0:1]
	v_pk_mov_b32 v[40:41], v[0:1], v[0:1]
	v_pk_mov_b32 v[42:43], v[0:1], v[0:1]
	v_pk_mov_b32 v[44:45], v[0:1], v[0:1]
	v_pk_mov_b32 v[46:47], v[0:1], v[0:1]
	v_pk_mov_b32 v[48:49], v[0:1], v[0:1]
	v_pk_mov_b32 v[50:51], v[0:1], v[0:1]
	v_pk_mov_b32 v[52:53], v[0:1], v[0:1]
	v_pk_mov_b32 v[54:55], v[0:1], v[0:1]
	v_pk_mov_b32 v[56:57], v[0:1], v[0:1]
	v_pk_mov_b32 v[58:59], v[0:1], v[0:1]
	v_pk_mov_b32 v[60:61], v[0:1], v[0:1]
	v_pk_mov_b32 v[62:63], v[0:1], v[0:1]
	v_pk_mov_b32 v[64:65], v[0:1], v[0:1]
	v_pk_mov_b32 v[66:67], v[0:1], v[0:1]
	v_pk_mov_b32 v[68:69], v[0:1], v[0:1]
	v_pk_mov_b32 v[70:71], v[0:1], v[0:1]
	v_pk_mov_b32 v[72:73], v[0:1], v[0:1]
	v_pk_mov_b32 v[74:75], v[0:1], v[0:1]
	v_pk_mov_b32 v[76:77], v[0:1], v[0:1]
	v_pk_mov_b32 v[78:79], v[0:1], v[0:1]
	v_pk_mov_b32 v[80:81], v[0:1], v[0:1]
	v_pk_mov_b32 v[82:83], v[0:1], v[0:1]
	v_pk_mov_b32 v[84:85], v[0:1], v[0:1]
	v_pk_mov_b32 v[86:87], v[0:1], v[0:1]
	v_pk_mov_b32 v[88:89], v[0:1], v[0:1]
	v_pk_mov_b32 v[90:91], v[0:1], v[0:1]
	v_pk_mov_b32 v[92:93], v[0:1], v[0:1]
	v_pk_mov_b32 v[94:95], v[0:1], v[0:1]
	v_pk_mov_b32 v[96:97], v[0:1], v[0:1]
	v_pk_mov_b32 v[98:99], v[0:1], v[0:1]
	v_pk_mov_b32 v[100:101], v[0:1], v[0:1]
	v_pk_mov_b32 v[102:103], v[0:1], v[0:1]
	v_pk_mov_b32 v[104:105], v[0:1], v[0:1]
	v_pk_mov_b32 v[106:107], v[0:1], v[0:1]
	v_pk_mov_b32 v[108:109], v[0:1], v[0:1]
	v_pk_mov_b32 v[110:111], v[0:1], v[0:1]
	v_pk_mov_b32 v[112:113], v[0:1], v[0:1]
	v_pk_mov_b32 v[114:115], v[0:1], v[0:1]
	v_pk_mov_b32 v[116:117], v[0:1], v[0:1]
	v_pk_mov_b32 v[118:119], v[0:1], v[0:1]
	v_pk_mov_b32 v[120:121], v[0:1], v[0:1]
	v_pk_mov_b32 v[122:123], v[0:1], v[0:1]
	v_pk_mov_b32 v[124:125], v[0:1], v[0:1]
	v_pk_mov_b32 v[126:127], v[0:1], v[0:1]
	v_add_u32_e32 v158, 0x10000, v171
	ds_read_b128 v[132:135], v158
	ds_read_b128 v[136:139], v158 offset:1024
	ds_read_b128 v[140:143], v158 offset:2048
	ds_read_b128 v[174:177], v158 offset:3072
	s_branch .LBB0_1229

; #define PG8_STAGE(bufoff, gbase, voff) do { _Pragma("unroll") for (int _i = 0; _i < 2; ++_i) \
;         __builtin_amdgcn_global_load_lds((const unsigned*)((const char*)(gbase) + (voff)[_i]), (LAS unsigned*)(lds + (bufoff) + ldsw + _i * 8192), 16, 0, 0); } while (0)
; #define PG8_STAGE_A(bufoff, ptr, half, rev) do { if (REVA && (rev)) { const char* _p = (ptr) - ((half) ? hstepA : 0); PG8_STAGE(bufoff, _p, voffAr); } else { const char* _p = (ptr) + ((half) ? hstepA : 0); PG8_STAGE(bufoff, _p, voffA); } } while (0)
; #define PG8_LDA(dst, b, h) do { _Pragma("unroll") for (int m = 0; m < 4; ++m) _Pragma("unroll") for (int k = 0; k < 2; ++k) dst[m][k] = *(const LAS bf16x8*)(lds + PG8_SA(b, h) + aoff + m * 2048 + k * 1024); } while (0)
; #define PG8_LDB(dst, b, h) do { _Pragma("unroll") for (int n = 0; n < 2; ++n) _Pragma("unroll") for (int k = 0; k < 2; ++k) dst[n][k] = *(const LAS bf16x8*)(lds + PG8_SB(b, h) + boff + n * 2048 + k * 1024); } while (0)
; #define PG8_WAIT_V(n) asm volatile("s_waitcnt vmcnt(" #n ")" ::: "memory")
; #define PG8_WAIT_L(n) asm volatile("s_waitcnt lgkmcnt(" #n ")" ::: "memory")
; #define PG8_BAR __builtin_amdgcn_s_barrier()
;     ...
;         for (int t = 0; t < nt; t += 2) {
;             const bool last = (t == nt - 2);
;             const char* a1 = PG8_APTR(cA, cAr, t + 1); const bool r1 = REVA && ((t + 1) & 4);
;             const char* a2 = last ? nA : PG8_APTR(cA, cAr, t + 2); const bool r2 = REVA && !last && ((t + 2) & 4);
;             const char* a3 = last ? nA + kstep : PG8_APTR(cA, cAr, t + 3); const bool r3 = REVA && !last && ((t + 3) & 4);
;             const char* b2 = last ? nB : cB + (size_t)(t + 2) * kstep; const char* b3 = b2 + kstep; const size_t hb2 = last ? nHb : cHb;
;             PG8_LDB(B0, 0, 0); PG8_SCHED; PG8_LDA(At, 0, 0); PG8_STAGE_A(PG8_SA(1, 1), a1, 1, r1);
;             PG8_WAIT_L(8); PG8_BAR; PG8_WAIT_L(0); PG8_MMA(0, 0, At, B0); PG8_BAR; PG8_SCHED;
;             PG8_LDB(B1, 0, 1); PG8_STAGE(PG8_SB(0, 0), b2, voffB);
;             PG8_BAR; PG8_WAIT_L(0); PG8_MMA(0, 1, At, B1); PG8_BAR;
;             PG8_LDA(At, 0, 1); PG8_STAGE_A(PG8_SA(0, 0), a2, 0, r2);
;             PG8_BAR; PG8_WAIT_L(0); PG8_MMA(1, 0, At, B0); PG8_BAR; PG8_SCHED;
;             PG8_STAGE(PG8_SB(0, 1), b2 + hb2, voffB);
;             PG8_WAIT_V(6); PG8_BAR; PG8_MMA(1, 1, At, B1); PG8_BAR;
.LBB0_1229:
	s_add_u32 s10, s0, s42
	s_addc_u32 s11, s1, s43
	s_add_u32 s16, s10, 0x100
	s_addc_u32 s17, s11, 0
	s_add_u32 s10, s10, 0x180
	s_addc_u32 s11, s11, 0
	s_add_u32 s14, s69, s42
	s_addc_u32 s15, s70, s43
	s_add_i32 s78, 0, 0x10000
	s_cmpk_eq_i32 s42, 0x1f00
	s_cselect_b32 s15, s39, s15
	s_cselect_b32 s14, s38, s14
	s_cselect_b32 s21, s37, s17
	s_cselect_b32 s20, s36, s16
	s_cselect_b32 s17, s27, s11
	s_cselect_b32 s16, s3, s10
	v_lshl_add_u64 v[158:159], v[128:129], 0, s[42:43]
	s_add_i32 m0, s48, 0xc000
	ds_read_b128 v[178:181], v172
	ds_read_b128 v[182:185], v172 offset:1024
	ds_read_b128 v[204:207], v172 offset:2048
	ds_read_b128 v[208:211], v172 offset:3072
	ds_read_b128 v[212:215], v172 offset:4096
	ds_read_b128 v[216:219], v172 offset:5120
	ds_read_b128 v[220:223], v172 offset:6144
	ds_read_b128 v[224:227], v172 offset:7168
	global_load_lds_dwordx4 v[158:159], off
	v_lshl_add_u64 v[158:159], v[130:131], 0, s[42:43]
	s_add_i32 m0, s48, 0xe000
	s_nop 0
	global_load_lds_dwordx4 v[158:159], off
	s_waitcnt lgkmcnt(8)
	s_waitcnt vmcnt(10)
	s_barrier
	s_waitcnt lgkmcnt(0)
	v_mfma_f32_16x16x32_bf16 v[124:127], v[132:135], v[178:181], v[124:127]
	v_mfma_f32_16x16x32_bf16 v[120:123], v[140:143], v[178:181], v[120:123]
	v_mfma_f32_16x16x32_bf16 v[112:115], v[132:135], v[204:207], v[112:115]
	v_mfma_f32_16x16x32_bf16 v[108:111], v[140:143], v[204:207], v[108:111]
	v_mfma_f32_16x16x32_bf16 v[92:95], v[132:135], v[212:215], v[92:95]
	v_mfma_f32_16x16x32_bf16 v[88:91], v[140:143], v[212:215], v[88:91]
	v_mfma_f32_16x16x32_bf16 v[84:87], v[132:135], v[220:223], v[84:87]
	v_mfma_f32_16x16x32_bf16 v[76:79], v[140:143], v[220:223], v[76:79]
	v_mfma_f32_16x16x32_bf16 v[124:127], v[136:139], v[182:185], v[124:127]
	v_mfma_f32_16x16x32_bf16 v[120:123], v[174:177], v[182:185], v[120:123]
	v_mfma_f32_16x16x32_bf16 v[112:115], v[136:139], v[208:211], v[112:115]
	v_mfma_f32_16x16x32_bf16 v[108:111], v[174:177], v[208:211], v[108:111]
	v_mfma_f32_16x16x32_bf16 v[92:95], v[136:139], v[216:219], v[92:95]
	v_mfma_f32_16x16x32_bf16 v[88:91], v[174:177], v[216:219], v[88:91]
	v_mfma_f32_16x16x32_bf16 v[84:87], v[136:139], v[224:227], v[84:87]
	v_mfma_f32_16x16x32_bf16 v[76:79], v[174:177], v[224:227], v[76:79]
	s_barrier
	s_add_i32 s10, 0, 0x14000
	v_add_u32_e32 v158, s10, v171
	s_add_i32 s11, s78, s5
	ds_read_b128 v[228:231], v158
	ds_read_b128 v[232:235], v158 offset:1024
	ds_read_b128 v[236:239], v158 offset:2048
	ds_read_b128 v[240:243], v158 offset:3072
	v_lshl_add_u64 v[158:159], s[14:15], 0, v[150:151]
	s_mov_b32 m0, s11
	v_lshl_add_u64 v[168:169], s[14:15], 0, v[148:149]
	global_load_lds_dwordx4 v[158:159], off
	s_add_i32 m0, s11, 0x2000
	s_nop 0
	global_load_lds_dwordx4 v[168:169], off
	s_waitcnt vmcnt(10)
	s_barrier
	s_waitcnt lgkmcnt(0)
	v_mfma_f32_16x16x32_bf16 v[116:119], v[228:231], v[178:181], v[116:119]
	v_mfma_f32_16x16x32_bf16 v[104:107], v[236:239], v[178:181], v[104:107]
	v_mfma_f32_16x16x32_bf16 v[100:103], v[228:231], v[204:207], v[100:103]
	v_mfma_f32_16x16x32_bf16 v[96:99], v[236:239], v[204:207], v[96:99]
	v_mfma_f32_16x16x32_bf16 v[80:83], v[228:231], v[212:215], v[80:83]
	v_mfma_f32_16x16x32_bf16 v[72:75], v[236:239], v[212:215], v[72:75]
	v_mfma_f32_16x16x32_bf16 v[68:71], v[228:231], v[220:223], v[68:71]
	v_mfma_f32_16x16x32_bf16 v[64:67], v[236:239], v[220:223], v[64:67]
	v_mfma_f32_16x16x32_bf16 v[116:119], v[232:235], v[182:185], v[116:119]
	v_mfma_f32_16x16x32_bf16 v[104:107], v[240:243], v[182:185], v[104:107]
	v_mfma_f32_16x16x32_bf16 v[100:103], v[232:235], v[208:211], v[100:103]
	v_mfma_f32_16x16x32_bf16 v[96:99], v[240:243], v[208:211], v[96:99]
	v_mfma_f32_16x16x32_bf16 v[80:83], v[232:235], v[216:219], v[80:83]
	v_mfma_f32_16x16x32_bf16 v[72:75], v[240:243], v[216:219], v[72:75]
	v_mfma_f32_16x16x32_bf16 v[68:71], v[232:235], v[224:227], v[68:71]
	v_mfma_f32_16x16x32_bf16 v[64:67], v[240:243], v[224:227], v[64:67]
	s_mov_b32 m0, s48
	v_lshl_add_u64 v[190:191], s[20:21], 0, v[150:151]
	s_barrier
	ds_read_b128 v[178:181], v172 offset:16384
	ds_read_b128 v[182:185], v172 offset:17408
	ds_read_b128 v[204:207], v172 offset:18432
	ds_read_b128 v[208:211], v172 offset:19456
	ds_read_b128 v[212:215], v172 offset:20480
	ds_read_b128 v[216:219], v172 offset:21504
	ds_read_b128 v[220:223], v172 offset:22528
	ds_read_b128 v[224:227], v172 offset:23552
	global_load_lds_dwordx4 v[190:191], off
	v_lshl_add_u64 v[190:191], s[20:21], 0, v[148:149]
	s_mov_b32 m0, s49
	s_nop 0
	global_load_lds_dwordx4 v[190:191], off
	s_waitcnt vmcnt(10)
	s_barrier
	s_waitcnt lgkmcnt(0)
	v_mfma_f32_16x16x32_bf16 v[60:63], v[132:135], v[178:181], v[60:63]
	v_mfma_f32_16x16x32_bf16 v[56:59], v[140:143], v[178:181], v[56:59]
	v_mfma_f32_16x16x32_bf16 v[52:55], v[132:135], v[204:207], v[52:55]
	v_mfma_f32_16x16x32_bf16 v[40:43], v[140:143], v[204:207], v[40:43]
	v_mfma_f32_16x16x32_bf16 v[28:31], v[132:135], v[212:215], v[28:31]
	v_mfma_f32_16x16x32_bf16 v[24:27], v[140:143], v[212:215], v[24:27]
	v_mfma_f32_16x16x32_bf16 v[20:23], v[132:135], v[220:223], v[20:23]
	v_mfma_f32_16x16x32_bf16 v[8:11], v[140:143], v[220:223], v[8:11]
	v_mfma_f32_16x16x32_bf16 v[60:63], v[136:139], v[182:185], v[60:63]
	v_mfma_f32_16x16x32_bf16 v[56:59], v[174:177], v[182:185], v[56:59]
	v_mfma_f32_16x16x32_bf16 v[52:55], v[136:139], v[208:211], v[52:55]
	v_mfma_f32_16x16x32_bf16 v[40:43], v[174:177], v[208:211], v[40:43]
	v_mfma_f32_16x16x32_bf16 v[28:31], v[136:139], v[216:219], v[28:31]
	v_mfma_f32_16x16x32_bf16 v[24:27], v[174:177], v[216:219], v[24:27]
	v_mfma_f32_16x16x32_bf16 v[20:23], v[136:139], v[224:227], v[20:23]
	v_mfma_f32_16x16x32_bf16 v[8:11], v[174:177], v[224:227], v[8:11]
	s_barrier
; #define PG8_STAGE(bufoff, gbase, voff) do { _Pragma("unroll") for (int _i = 0; _i < 2; ++_i) \
;         __builtin_amdgcn_global_load_lds((const unsigned*)((const char*)(gbase) + (voff)[_i]), (LAS unsigned*)(lds + (bufoff) + ldsw + _i * 8192), 16, 0, 0); } while (0)
; #define PG8_STAGE_A(bufoff, ptr, half, rev) do { if (REVA && (rev)) { const char* _p = (ptr) - ((half) ? hstepA : 0); PG8_STAGE(bufoff, _p, voffAr); } else { const char* _p = (ptr) + ((half) ? hstepA : 0); PG8_STAGE(bufoff, _p, voffA); } } while (0)
; #define PG8_LDA(dst, b, h) do { _Pragma("unroll") for (int m = 0; m < 4; ++m) _Pragma("unroll") for (int k = 0; k < 2; ++k) dst[m][k] = *(const LAS bf16x8*)(lds + PG8_SA(b, h) + aoff + m * 2048 + k * 1024); } while (0)
; #define PG8_LDB(dst, b, h) do { _Pragma("unroll") for (int n = 0; n < 2; ++n) _Pragma("unroll") for (int k = 0; k < 2; ++k) dst[n][k] = *(const LAS bf16x8*)(lds + PG8_SB(b, h) + boff + n * 2048 + k * 1024); } while (0)
; #define PG8_MMA(ai, bj, At, Bt) do { __builtin_amdgcn_s_setprio(1); _Pragma("unroll") for (int m = 0; m < 4; ++m) _Pragma("unroll") for (int n = 0; n < 2; ++n) _Pragma("unroll") for (int k = 0; k < 2; ++k) \
;         acc[ai][bj][m][n] = __builtin_amdgcn_mfma_f32_16x16x32_bf16(Bt[n][k], At[m][k], acc[ai][bj][m][n], 0, 0, 0); __builtin_amdgcn_s_setprio(0); } while (0)
; #define PG8_WAIT_V(n) asm volatile("s_waitcnt vmcnt(" #n ")" ::: "memory")
; #define PG8_WAIT_L(n) asm volatile("s_waitcnt lgkmcnt(" #n ")" ::: "memory")
; #define PG8_BAR __builtin_amdgcn_s_barrier()
; #define PG8_SCHED __builtin_amdgcn_sched_barrier(0)
;     ...
;             PG8_WAIT_V(6); PG8_BAR; PG8_MMA(1, 1, At, B1); PG8_BAR;
;             PG8_LDB(B0, 1, 0); PG8_SCHED; PG8_LDA(At, 1, 0); PG8_STAGE_A(PG8_SA(0, 1), a2, 1, r2);
;             PG8_WAIT_L(8); PG8_BAR; PG8_WAIT_L(0); PG8_MMA(0, 0, At, B0); PG8_BAR; PG8_SCHED;
;             PG8_LDB(B1, 1, 1); PG8_STAGE(PG8_SB(1, 0), b3, voffB);
;             PG8_BAR; PG8_WAIT_L(0); PG8_MMA(0, 1, At, B1); PG8_BAR;
;             PG8_LDA(At, 1, 1); PG8_STAGE_A(PG8_SA(1, 0), a3, 0, r3);
;             PG8_BAR; PG8_WAIT_L(0); PG8_MMA(1, 0, At, B0); PG8_BAR; PG8_SCHED;
	s_add_u32 s78, s14, 0x100000
	s_addc_u32 s79, s15, 0
	s_add_i32 s10, s10, s5
	v_lshl_add_u64 v[132:133], s[78:79], 0, v[150:151]
	s_mov_b32 m0, s10
	s_nop 0
	global_load_lds_dwordx4 v[132:133], off
	v_lshl_add_u64 v[132:133], s[78:79], 0, v[148:149]
	s_add_i32 m0, s10, 0x2000
	s_nop 0
	global_load_lds_dwordx4 v[132:133], off
	v_add_u32_e32 v173, 0x18000, v171
	ds_read_b128 v[132:135], v173
	ds_read_b128 v[136:139], v173 offset:1024
	ds_read_b128 v[140:143], v173 offset:2048
	ds_read_b128 v[174:177], v173 offset:3072
	s_waitcnt vmcnt(10)
	s_barrier
	v_mfma_f32_16x16x32_bf16 v[48:51], v[228:231], v[178:181], v[48:51]
	v_mfma_f32_16x16x32_bf16 v[44:47], v[236:239], v[178:181], v[44:47]
	v_mfma_f32_16x16x32_bf16 v[36:39], v[228:231], v[204:207], v[36:39]
	v_mfma_f32_16x16x32_bf16 v[32:35], v[236:239], v[204:207], v[32:35]
	v_mfma_f32_16x16x32_bf16 v[16:19], v[228:231], v[212:215], v[16:19]
	v_mfma_f32_16x16x32_bf16 v[12:15], v[236:239], v[212:215], v[12:15]
	v_mfma_f32_16x16x32_bf16 v[4:7], v[228:231], v[220:223], v[4:7]
	v_mfma_f32_16x16x32_bf16 v[0:3], v[236:239], v[220:223], v[0:3]
	v_mfma_f32_16x16x32_bf16 v[48:51], v[232:235], v[182:185], v[48:51]
	v_mfma_f32_16x16x32_bf16 v[44:47], v[240:243], v[182:185], v[44:47]
	v_mfma_f32_16x16x32_bf16 v[36:39], v[232:235], v[208:211], v[36:39]
	v_mfma_f32_16x16x32_bf16 v[32:35], v[240:243], v[208:211], v[32:35]
	v_mfma_f32_16x16x32_bf16 v[16:19], v[232:235], v[216:219], v[16:19]
	v_mfma_f32_16x16x32_bf16 v[12:15], v[240:243], v[216:219], v[12:15]
	v_mfma_f32_16x16x32_bf16 v[4:7], v[232:235], v[224:227], v[4:7]
	v_mfma_f32_16x16x32_bf16 v[0:3], v[240:243], v[224:227], v[0:3]
	s_add_i32 s10, 0, 0x18000
	s_barrier
	s_add_u32 s20, s20, 0x100000
	s_addc_u32 s21, s21, 0
	s_mov_b32 m0, s50
	v_lshl_add_u64 v[190:191], s[20:21], 0, v[150:151]
	ds_read_b128 v[178:181], v172 offset:32768
	ds_read_b128 v[182:185], v172 offset:33792
	ds_read_b128 v[204:207], v172 offset:34816
	ds_read_b128 v[208:211], v172 offset:35840
	ds_read_b128 v[212:215], v172 offset:36864
	ds_read_b128 v[216:219], v172 offset:37888
	ds_read_b128 v[220:223], v172 offset:38912
	ds_read_b128 v[224:227], v172 offset:39936
	global_load_lds_dwordx4 v[190:191], off
	v_lshl_add_u64 v[190:191], s[20:21], 0, v[148:149]
	s_mov_b32 m0, s51
	s_nop 0
	global_load_lds_dwordx4 v[190:191], off
	s_waitcnt lgkmcnt(8)
	s_waitcnt vmcnt(10)
	s_barrier
	s_waitcnt lgkmcnt(0)
	v_mfma_f32_16x16x32_bf16 v[124:127], v[132:135], v[178:181], v[124:127]
	v_mfma_f32_16x16x32_bf16 v[120:123], v[140:143], v[178:181], v[120:123]
	v_mfma_f32_16x16x32_bf16 v[112:115], v[132:135], v[204:207], v[112:115]
	v_mfma_f32_16x16x32_bf16 v[108:111], v[140:143], v[204:207], v[108:111]
	v_mfma_f32_16x16x32_bf16 v[92:95], v[132:135], v[212:215], v[92:95]
	v_mfma_f32_16x16x32_bf16 v[88:91], v[140:143], v[212:215], v[88:91]
	v_mfma_f32_16x16x32_bf16 v[84:87], v[132:135], v[220:223], v[84:87]
	v_mfma_f32_16x16x32_bf16 v[76:79], v[140:143], v[220:223], v[76:79]
	v_mfma_f32_16x16x32_bf16 v[124:127], v[136:139], v[182:185], v[124:127]
	v_mfma_f32_16x16x32_bf16 v[120:123], v[174:177], v[182:185], v[120:123]
	v_mfma_f32_16x16x32_bf16 v[112:115], v[136:139], v[208:211], v[112:115]
	v_mfma_f32_16x16x32_bf16 v[108:111], v[174:177], v[208:211], v[108:111]
	v_mfma_f32_16x16x32_bf16 v[92:95], v[136:139], v[216:219], v[92:95]
	v_mfma_f32_16x16x32_bf16 v[88:91], v[174:177], v[216:219], v[88:91]
	v_mfma_f32_16x16x32_bf16 v[84:87], v[136:139], v[224:227], v[84:87]
	v_mfma_f32_16x16x32_bf16 v[76:79], v[174:177], v[224:227], v[76:79]
	s_barrier
	s_add_i32 s11, 0, 0x1c000
	s_add_i32 s10, s10, s5
	v_add_u32_e32 v173, s11, v171
	v_lshl_add_u64 v[158:159], v[158:159], 0, s[28:29]
	s_mov_b32 m0, s10
	ds_read_b128 v[228:231], v173
	ds_read_b128 v[232:235], v173 offset:1024
	ds_read_b128 v[236:239], v173 offset:2048
	ds_read_b128 v[240:243], v173 offset:3072
	global_load_lds_dwordx4 v[158:159], off
	v_lshl_add_u64 v[158:159], v[168:169], 0, s[28:29]
	s_add_i32 m0, s10, 0x2000
	s_nop 0
	global_load_lds_dwordx4 v[158:159], off
	s_waitcnt vmcnt(10)
	s_barrier
	s_waitcnt lgkmcnt(0)
	v_mfma_f32_16x16x32_bf16 v[116:119], v[228:231], v[178:181], v[116:119]
	v_mfma_f32_16x16x32_bf16 v[104:107], v[236:239], v[178:181], v[104:107]
	v_mfma_f32_16x16x32_bf16 v[100:103], v[228:231], v[204:207], v[100:103]
	v_mfma_f32_16x16x32_bf16 v[96:99], v[236:239], v[204:207], v[96:99]
	v_mfma_f32_16x16x32_bf16 v[80:83], v[228:231], v[212:215], v[80:83]
	v_mfma_f32_16x16x32_bf16 v[72:75], v[236:239], v[212:215], v[72:75]
	v_mfma_f32_16x16x32_bf16 v[68:71], v[228:231], v[220:223], v[68:71]
	v_mfma_f32_16x16x32_bf16 v[64:67], v[236:239], v[220:223], v[64:67]
	v_mfma_f32_16x16x32_bf16 v[116:119], v[232:235], v[182:185], v[116:119]
	v_mfma_f32_16x16x32_bf16 v[104:107], v[240:243], v[182:185], v[104:107]
	v_mfma_f32_16x16x32_bf16 v[100:103], v[232:235], v[208:211], v[100:103]
	v_mfma_f32_16x16x32_bf16 v[96:99], v[240:243], v[208:211], v[96:99]
	v_mfma_f32_16x16x32_bf16 v[80:83], v[232:235], v[216:219], v[80:83]
	v_mfma_f32_16x16x32_bf16 v[72:75], v[240:243], v[216:219], v[72:75]
	v_mfma_f32_16x16x32_bf16 v[68:71], v[232:235], v[224:227], v[68:71]
	v_mfma_f32_16x16x32_bf16 v[64:67], v[240:243], v[224:227], v[64:67]
	s_mov_b32 m0, s66
	v_lshl_add_u64 v[158:159], s[16:17], 0, v[150:151]
	s_barrier
	ds_read_b128 v[178:181], v172 offset:49152
	ds_read_b128 v[182:185], v172 offset:50176
	ds_read_b128 v[204:207], v172 offset:51200
	ds_read_b128 v[208:211], v172 offset:52224
	ds_read_b128 v[212:215], v172 offset:53248
	ds_read_b128 v[216:219], v172 offset:54272
	ds_read_b128 v[220:223], v172 offset:55296
	ds_read_b128 v[224:227], v172 offset:56320
	global_load_lds_dwordx4 v[158:159], off
	v_lshl_add_u64 v[158:159], s[16:17], 0, v[148:149]
	s_mov_b32 m0, s67
	s_nop 0
	global_load_lds_dwordx4 v[158:159], off
	s_waitcnt vmcnt(10)
	s_barrier
; #define PG8_STAGE(bufoff, gbase, voff) do { _Pragma("unroll") for (int _i = 0; _i < 2; ++_i) \
;         __builtin_amdgcn_global_load_lds((const unsigned*)((const char*)(gbase) + (voff)[_i]), (LAS unsigned*)(lds + (bufoff) + ldsw + _i * 8192), 16, 0, 0); } while (0)
; #define PG8_MMA(ai, bj, At, Bt) do { __builtin_amdgcn_s_setprio(1); _Pragma("unroll") for (int m = 0; m < 4; ++m) _Pragma("unroll") for (int n = 0; n < 2; ++n) _Pragma("unroll") for (int k = 0; k < 2; ++k) \
;         acc[ai][bj][m][n] = __builtin_amdgcn_mfma_f32_16x16x32_bf16(Bt[n][k], At[m][k], acc[ai][bj][m][n], 0, 0, 0); __builtin_amdgcn_s_setprio(0); } while (0)
; #define PG8_WAIT_V(n) asm volatile("s_waitcnt vmcnt(" #n ")" ::: "memory")
; #define PG8_WAIT_L(n) asm volatile("s_waitcnt lgkmcnt(" #n ")" ::: "memory")
; #define PG8_BAR __builtin_amdgcn_s_barrier()
; #define PG8_SCHED __builtin_amdgcn_sched_barrier(0)
;     ...
;             PG8_BAR; PG8_WAIT_L(0); PG8_MMA(1, 0, At, B0); PG8_BAR; PG8_SCHED;
;             PG8_STAGE(PG8_SB(1, 1), b3 + hb2, voffB);
;             PG8_WAIT_V(6); PG8_BAR; PG8_MMA(1, 1, At, B1); PG8_BAR;
;     __device__ __forceinline__ void operator()(const f32x4 (&acc)[2][2][4][2], const Unit& u, int wr, int wc, int fr, int fq, int lane) const {
;         const bool lat = u.pm < 128;
;         const int s = lat ? (u.pm >> 4) : 8;
;         const float* gate = modi + s * 6144 + 4096 + u.pn * BM + wc * 32 + 4 * fq;
;         const size_t r0 = lat ? (size_t)u.pm * BM : (size_t)(u.pm - 128) * BM;
;         const float* base = (lat ? baseL : baseC) + u.pn * BM + wc * 32 + 4 * fq;
;         float* out = (lat ? outL : outC) + u.pn * BM + wc * 32 + 4 * fq;
;         f32x4 gv[2][2];
; #pragma unroll
;         for (int bj = 0; bj < 2; ++bj)
; #pragma unroll
;             for (int n = 0; n < 2; ++n) gv[bj][n] = *(const f32x4*)(gate + bj * HALF + n * 16);
	s_waitcnt lgkmcnt(0)
	v_mfma_f32_16x16x32_bf16 v[60:63], v[132:135], v[178:181], v[60:63]
	v_mfma_f32_16x16x32_bf16 v[56:59], v[140:143], v[178:181], v[56:59]
	v_mfma_f32_16x16x32_bf16 v[52:55], v[132:135], v[204:207], v[52:55]
	v_mfma_f32_16x16x32_bf16 v[40:43], v[140:143], v[204:207], v[40:43]
	v_mfma_f32_16x16x32_bf16 v[28:31], v[132:135], v[212:215], v[28:31]
	v_mfma_f32_16x16x32_bf16 v[24:27], v[140:143], v[212:215], v[24:27]
	v_mfma_f32_16x16x32_bf16 v[20:23], v[132:135], v[220:223], v[20:23]
	v_mfma_f32_16x16x32_bf16 v[8:11], v[140:143], v[220:223], v[8:11]
	v_mfma_f32_16x16x32_bf16 v[60:63], v[136:139], v[182:185], v[60:63]
	v_mfma_f32_16x16x32_bf16 v[56:59], v[174:177], v[182:185], v[56:59]
	v_mfma_f32_16x16x32_bf16 v[52:55], v[136:139], v[208:211], v[52:55]
	v_mfma_f32_16x16x32_bf16 v[40:43], v[174:177], v[208:211], v[40:43]
	v_mfma_f32_16x16x32_bf16 v[28:31], v[136:139], v[216:219], v[28:31]
	v_mfma_f32_16x16x32_bf16 v[24:27], v[174:177], v[216:219], v[24:27]
	v_mfma_f32_16x16x32_bf16 v[20:23], v[136:139], v[224:227], v[20:23]
	v_mfma_f32_16x16x32_bf16 v[8:11], v[174:177], v[224:227], v[8:11]
	s_barrier
	s_add_u32 s14, s14, 0x100080
	s_addc_u32 s15, s15, 0
	s_add_i32 s10, s11, s5
	v_lshl_add_u64 v[132:133], s[14:15], 0, v[150:151]
	s_mov_b32 m0, s10
	s_nop 0
	global_load_lds_dwordx4 v[132:133], off
	v_lshl_add_u64 v[132:133], s[14:15], 0, v[148:149]
	s_add_i32 m0, s10, 0x2000
	s_nop 0
	global_load_lds_dwordx4 v[132:133], off
	v_add_u32_e32 v158, 0x10000, v171
	ds_read_b128 v[132:135], v158
	ds_read_b128 v[136:139], v158 offset:1024
	ds_read_b128 v[140:143], v158 offset:2048
	ds_read_b128 v[174:177], v158 offset:3072
	s_waitcnt vmcnt(10)
	s_barrier
	v_mfma_f32_16x16x32_bf16 v[48:51], v[228:231], v[178:181], v[48:51]
	v_mfma_f32_16x16x32_bf16 v[44:47], v[236:239], v[178:181], v[44:47]
	v_mfma_f32_16x16x32_bf16 v[36:39], v[228:231], v[204:207], v[36:39]
	v_mfma_f32_16x16x32_bf16 v[32:35], v[236:239], v[204:207], v[32:35]
	v_mfma_f32_16x16x32_bf16 v[16:19], v[228:231], v[212:215], v[16:19]
	v_mfma_f32_16x16x32_bf16 v[12:15], v[236:239], v[212:215], v[12:15]
	v_mfma_f32_16x16x32_bf16 v[4:7], v[228:231], v[220:223], v[4:7]
	v_mfma_f32_16x16x32_bf16 v[0:3], v[236:239], v[220:223], v[0:3]
	v_mfma_f32_16x16x32_bf16 v[48:51], v[232:235], v[182:185], v[48:51]
	v_mfma_f32_16x16x32_bf16 v[44:47], v[240:243], v[182:185], v[44:47]
	v_mfma_f32_16x16x32_bf16 v[36:39], v[232:235], v[208:211], v[36:39]
	v_mfma_f32_16x16x32_bf16 v[32:35], v[240:243], v[208:211], v[32:35]
	v_mfma_f32_16x16x32_bf16 v[16:19], v[232:235], v[216:219], v[16:19]
	v_mfma_f32_16x16x32_bf16 v[12:15], v[240:243], v[216:219], v[12:15]
	v_mfma_f32_16x16x32_bf16 v[4:7], v[232:235], v[224:227], v[4:7]
	v_mfma_f32_16x16x32_bf16 v[0:3], v[240:243], v[224:227], v[0:3]
	s_add_i32 s71, s71, 2
	s_add_u32 s42, s42, 0x100
	s_addc_u32 s43, s43, 0
	s_cmp_gt_u32 s71, 61
	s_cbranch_scc0 .Lrot_1229_bar
	s_barrier
	s_waitcnt lgkmcnt(0)
	s_cmpk_lt_i32 s9, 0x80
	s_cselect_b64 vcc, -1, 0
	s_cselect_b32 s3, s61, s53
	s_cselect_b32 s10, s60, s52
	s_add_i32 s0, s9, 0xffffff80
	s_cmpk_lt_i32 s9, 0x80
	s_cselect_b32 s0, s9, s0
	s_lshr_b32 s1, s9, 4
	s_cmpk_lt_i32 s9, 0x80
	s_mulk_i32 s1, 0x1800
	s_cselect_b32 s14, s1, 0xc000
	s_ashr_i32 s15, s14, 31
	s_lshl_b64 s[14:15], s[14:15], 2
	s_add_u32 s1, s6, s14
	s_addc_u32 s11, s7, s15
	s_lshl_b32 s8, s8, 8
	s_ashr_i32 s9, s8, 31
	s_lshl_b64 s[8:9], s[8:9], 2
	s_add_u32 s1, s1, s8
	s_addc_u32 s11, s11, s9
	s_add_u32 s14, s1, s22
	s_waitcnt vmcnt(0)
	v_cndmask_b32_e32 v129, v147, v145, vcc
	v_cndmask_b32_e32 v128, v146, v144, vcc
	s_addc_u32 s15, s11, 0
	s_ashr_i32 s1, s0, 31
	v_lshl_add_u64 v[128:129], v[128:129], 0, s[8:9]
	s_add_u32 s8, s10, s8
	s_addc_u32 s3, s3, s9
	s_add_u32 s8, s8, s22
	v_lshl_add_u64 v[130:131], s[14:15], 0, v[160:161]
	s_addc_u32 s9, s3, 0
	s_mov_b32 s3, 0x704000
	s_lshl_b64 s[0:1], s[0:1], 21
	s_mov_b64 s[14:15], 0x704000
	v_lshl_add_u64 v[168:169], v[128:129], 0, s[22:23]
	v_add_co_u32_e32 v128, vcc, s3, v130
	v_lshl_add_u64 v[224:225], s[0:1], 0, v[152:153]
	v_lshl_add_u64 v[158:159], v[130:131], 0, s[14:15]
	v_addc_co_u32_e32 v129, vcc, 0, v131, vcc
	v_lshl_add_u64 v[190:191], v[168:169], 0, v[160:161]
	v_or_b32_e32 v226, 0x20000, v224
	v_mov_b32_e32 v227, v225
	global_load_dwordx4 v[136:139], v[158:159], off offset:64
	global_load_dwordx4 v[132:135], v[158:159], off offset:512
	global_load_dwordx4 v[140:143], v[128:129], off
	s_nop 0
	global_load_dwordx4 v[128:131], v[158:159], off offset:576
	v_lshl_add_u64 v[168:169], v[190:191], 0, v[224:225]
	v_lshl_add_u64 v[158:159], v[190:191], 0, v[226:227]
	global_load_dwordx4 v[174:177], v[168:169], off
	global_load_dwordx4 v[178:181], v[168:169], off offset:64
	global_load_dwordx4 v[182:185], v[168:169], off offset:512
	global_load_dwordx4 v[204:207], v[168:169], off offset:576
	global_load_dwordx4 v[208:211], v[158:159], off
	global_load_dwordx4 v[212:215], v[158:159], off offset:64
	global_load_dwordx4 v[216:219], v[158:159], off offset:512
	global_load_dwordx4 v[220:223], v[158:159], off offset:576
	v_lshl_add_u64 v[228:229], s[8:9], 0, v[160:161]
	v_lshl_add_u64 v[158:159], v[228:229], 0, v[224:225]
	s_waitcnt vmcnt(0)
;     __device__ __forceinline__ void operator()(const f32x4 (&acc)[2][2][4][2], const Unit& u, int wr, int wc, int fr, int fq, int lane) const {
;     ...
; #pragma unroll
;         for (int ai = 0; ai < 2; ++ai)
; #pragma unroll
;           for (int mh = 0; mh < 2; ++mh) {
;             f32x4 bs[2][2][2];
; #pragma unroll
;             for (int m2 = 0; m2 < 2; ++m2) {
;                 const size_t ro = (r0 + ai * HALF + wr * 64 + (mh * 2 + m2) * 16 + fr) * (size_t)D;
; #pragma unroll
;                 for (int bj = 0; bj < 2; ++bj)
; #pragma unroll
;                     for (int n = 0; n < 2; ++n) bs[m2][bj][n] = *(const f32x4*)(base + ro + bj * HALF + n * 16);
;             }
;             __builtin_amdgcn_sched_barrier(0);
; #pragma unroll
;             for (int m2 = 0; m2 < 2; ++m2) {
;                 const size_t ro = (r0 + ai * HALF + wr * 64 + (mh * 2 + m2) * 16 + fr) * (size_t)D;
; #pragma unroll
;                 for (int bj = 0; bj < 2; ++bj)
; #pragma unroll
;                     for (int n = 0; n < 2; ++n) *(f32x4*)(out + ro + bj * HALF + n * 16) = bs[m2][bj][n] + gv[bj][n] * acc[ai][bj][mh * 2 + m2][n];
;             }
;             __builtin_amdgcn_sched_barrier(0);
	v_pk_fma_f32 v[118:119], v[118:119], v[134:135], v[184:185]
	v_pk_fma_f32 v[116:117], v[116:117], v[132:133], v[182:183]
	v_pk_fma_f32 v[106:107], v[106:107], v[130:131], v[206:207]
	v_pk_fma_f32 v[104:105], v[104:105], v[128:129], v[204:205]
	global_store_dwordx4 v[158:159], v[116:119], off offset:512
	global_store_dwordx4 v[158:159], v[104:107], off offset:576
	v_pk_fma_f32 v[126:127], v[126:127], v[142:143], v[176:177]
	v_lshl_add_u64 v[116:117], v[228:229], 0, v[226:227]
	v_pk_fma_f32 v[106:107], v[114:115], v[142:143], v[210:211]
	v_pk_fma_f32 v[104:105], v[112:113], v[140:141], v[208:209]
	v_pk_fma_f32 v[124:125], v[124:125], v[140:141], v[174:175]
	v_pk_fma_f32 v[122:123], v[122:123], v[138:139], v[180:181]
	v_pk_fma_f32 v[120:121], v[120:121], v[136:137], v[178:179]
	global_store_dwordx4 v[116:117], v[104:107], off
	v_pk_fma_f32 v[102:103], v[102:103], v[134:135], v[218:219]
	v_pk_fma_f32 v[100:101], v[100:101], v[132:133], v[216:217]
	v_pk_fma_f32 v[106:107], v[110:111], v[138:139], v[214:215]
	v_pk_fma_f32 v[104:105], v[108:109], v[136:137], v[212:213]
	v_pk_fma_f32 v[98:99], v[98:99], v[130:131], v[222:223]
	v_pk_fma_f32 v[96:97], v[96:97], v[128:129], v[220:221]
	global_store_dwordx4 v[158:159], v[124:127], off
	global_store_dwordx4 v[158:159], v[120:123], off offset:64
	global_store_dwordx4 v[116:117], v[104:107], off offset:64
	global_store_dwordx4 v[116:117], v[100:103], off offset:512
	global_store_dwordx4 v[116:117], v[96:99], off offset:576
	v_or_b32_e32 v174, 0x40000, v224
	v_mov_b32_e32 v175, v225
	v_or_b32_e32 v224, 0x60000, v224
	v_lshl_add_u64 v[108:109], v[190:191], 0, v[174:175]
	v_lshl_add_u64 v[124:125], v[190:191], 0, v[224:225]
	global_load_dwordx4 v[96:99], v[108:109], off
	global_load_dwordx4 v[100:103], v[108:109], off offset:64
	global_load_dwordx4 v[104:107], v[108:109], off offset:512
	s_nop 0
	global_load_dwordx4 v[108:111], v[108:109], off offset:576
	s_nop 0
	global_load_dwordx4 v[112:115], v[124:125], off
	global_load_dwordx4 v[116:119], v[124:125], off offset:64
	global_load_dwordx4 v[120:123], v[124:125], off offset:512
	s_nop 0
	global_load_dwordx4 v[124:127], v[124:125], off offset:576
	v_lshl_add_u64 v[174:175], v[228:229], 0, v[174:175]
	s_waitcnt vmcnt(0)
	v_pk_fma_f32 v[82:83], v[82:83], v[134:135], v[106:107]
	v_pk_fma_f32 v[80:81], v[80:81], v[132:133], v[104:105]
	v_pk_fma_f32 v[74:75], v[74:75], v[130:131], v[110:111]
	v_pk_fma_f32 v[72:73], v[72:73], v[128:129], v[108:109]
	global_store_dwordx4 v[174:175], v[80:83], off offset:512
	global_store_dwordx4 v[174:175], v[72:75], off offset:576
	v_pk_fma_f32 v[94:95], v[94:95], v[142:143], v[98:99]
	v_lshl_add_u64 v[80:81], v[228:229], 0, v[224:225]
	v_pk_fma_f32 v[74:75], v[86:87], v[142:143], v[114:115]
	v_pk_fma_f32 v[72:73], v[84:85], v[140:141], v[112:113]
	v_pk_fma_f32 v[92:93], v[92:93], v[140:141], v[96:97]
	v_pk_fma_f32 v[90:91], v[90:91], v[138:139], v[102:103]
	v_pk_fma_f32 v[88:89], v[88:89], v[136:137], v[100:101]
	global_store_dwordx4 v[80:81], v[72:75], off
	v_pk_fma_f32 v[70:71], v[70:71], v[134:135], v[122:123]
	v_pk_fma_f32 v[68:69], v[68:69], v[132:133], v[120:121]
	v_pk_fma_f32 v[74:75], v[78:79], v[138:139], v[118:119]
	v_pk_fma_f32 v[72:73], v[76:77], v[136:137], v[116:117]
	v_pk_fma_f32 v[66:67], v[66:67], v[130:131], v[126:127]
	v_pk_fma_f32 v[64:65], v[64:65], v[128:129], v[124:125]
	global_store_dwordx4 v[174:175], v[92:95], off
	global_store_dwordx4 v[174:175], v[88:91], off offset:64
	global_store_dwordx4 v[80:81], v[72:75], off offset:64
	global_store_dwordx4 v[80:81], v[68:71], off offset:512
	global_store_dwordx4 v[80:81], v[64:67], off offset:576
	s_mov_b32 s3, 0x100000
	v_add_co_u32_e32 v72, vcc, s3, v168
	s_mov_b32 s8, 0x120000
	s_nop 0
	v_addc_co_u32_e32 v73, vcc, 0, v169, vcc
	s_mov_b64 s[0:1], 0x100000
	s_mov_b64 s[10:11], 0x120000
	v_add_co_u32_e32 v88, vcc, s8, v168
	v_lshl_add_u64 v[76:77], v[168:169], 0, s[0:1]
	v_lshl_add_u64 v[92:93], v[168:169], 0, s[10:11]
	v_addc_co_u32_e32 v89, vcc, 0, v169, vcc
	global_load_dwordx4 v[64:67], v[76:77], off offset:64
	global_load_dwordx4 v[68:71], v[76:77], off offset:512
	s_nop 0
	global_load_dwordx4 v[72:75], v[72:73], off
	s_nop 0
	global_load_dwordx4 v[76:79], v[76:77], off offset:576
	s_nop 0
	global_load_dwordx4 v[80:83], v[92:93], off offset:64
	global_load_dwordx4 v[84:87], v[92:93], off offset:512
	s_nop 0
	global_load_dwordx4 v[88:91], v[88:89], off
	s_nop 0
	global_load_dwordx4 v[92:95], v[92:93], off offset:576
	s_waitcnt vmcnt(0)
; #define PG8_WAIT_V(n) asm volatile("s_waitcnt vmcnt(" #n ")" ::: "memory")
; #define PG8_BAR __builtin_amdgcn_s_barrier()
;     ...
;         E(acc, cur, wr, wc, fr, fq, lane);
;         if (!has_next) break;
; #pragma unroll
;         for (int a = 0; a < 2; ++a)
; #pragma unroll
;             for (int b = 0; b < 2; ++b)
; #pragma unroll
;                 for (int m = 0; m < 4; ++m)
; #pragma unroll
;                     for (int n = 0; n < 2; ++n) acc[a][b][m][n] = (f32x4){0.f, 0.f, 0.f, 0.f};
;         cur = nxt; cA = nA; cB = nB; cAr = nAr; cHb = nHb; ++ui;
;     }
;     PG8_WAIT_V(0);
;     if (wr == 0) PG8_BAR;
;     PG8_BAR;
;     __device__ __forceinline__ void operator()(const f32x4 (&acc)[2][2][4][2], const Unit& u, int wr, int wc, int fr, int fq, int lane) const {
;     ...
; #pragma unroll
;         for (int ai = 0; ai < 2; ++ai)
; #pragma unroll
;           for (int mh = 0; mh < 2; ++mh) {
;             f32x4 bs[2][2][2];
; #pragma unroll
;             for (int m2 = 0; m2 < 2; ++m2) {
;                 const size_t ro = (r0 + ai * HALF + wr * 64 + (mh * 2 + m2) * 16 + fr) * (size_t)D;
; #pragma unroll
;                 for (int bj = 0; bj < 2; ++bj)
; #pragma unroll
;                     for (int n = 0; n < 2; ++n) bs[m2][bj][n] = *(const f32x4*)(base + ro + bj * HALF + n * 16);
;             }
;             __builtin_amdgcn_sched_barrier(0);
; #pragma unroll
;             for (int m2 = 0; m2 < 2; ++m2) {
;                 const size_t ro = (r0 + ai * HALF + wr * 64 + (mh * 2 + m2) * 16 + fr) * (size_t)D;
; #pragma unroll
;                 for (int bj = 0; bj < 2; ++bj)
; #pragma unroll
;                     for (int n = 0; n < 2; ++n) *(f32x4*)(out + ro + bj * HALF + n * 16) = bs[m2][bj][n] + gv[bj][n] * acc[ai][bj][mh * 2 + m2][n];
;             }
;             __builtin_amdgcn_sched_barrier(0);
;           }
	v_pk_fma_f32 v[60:61], v[60:61], v[140:141], v[72:73]
	v_add_co_u32_e32 v72, vcc, s3, v158
	v_lshl_add_u64 v[96:97], v[158:159], 0, s[0:1]
	s_nop 0
	v_addc_co_u32_e32 v73, vcc, 0, v159, vcc
	v_pk_fma_f32 v[50:51], v[50:51], v[134:135], v[70:71]
	v_pk_fma_f32 v[48:49], v[48:49], v[132:133], v[68:69]
	global_store_dwordx4 v[96:97], v[48:51], off offset:512
	v_pk_fma_f32 v[46:47], v[46:47], v[130:131], v[78:79]
	v_pk_fma_f32 v[44:45], v[44:45], v[128:129], v[76:77]
	v_add_co_u32_e32 v50, vcc, s8, v158
	s_mov_b64 s[74:75], 0x100000
	v_pk_fma_f32 v[62:63], v[62:63], v[142:143], v[74:75]
	s_mov_b32 s76, 0x100000
	v_pk_fma_f32 v[58:59], v[58:59], v[138:139], v[66:67]
	v_pk_fma_f32 v[56:57], v[56:57], v[136:137], v[64:65]
	global_store_dwordx4 v[96:97], v[44:47], off offset:576
	v_lshl_add_u64 v[48:49], v[158:159], 0, s[10:11]
	s_mov_b32 s77, 0x120000
	v_pk_fma_f32 v[46:47], v[54:55], v[142:143], v[90:91]
	v_pk_fma_f32 v[44:45], v[52:53], v[140:141], v[88:89]
	v_addc_co_u32_e32 v51, vcc, 0, v159, vcc
	v_pk_fma_f32 v[42:43], v[42:43], v[138:139], v[82:83]
	v_pk_fma_f32 v[40:41], v[40:41], v[136:137], v[80:81]
	v_pk_fma_f32 v[38:39], v[38:39], v[134:135], v[86:87]
	v_pk_fma_f32 v[36:37], v[36:37], v[132:133], v[84:85]
	v_pk_fma_f32 v[34:35], v[34:35], v[130:131], v[94:95]
	v_pk_fma_f32 v[32:33], v[32:33], v[128:129], v[92:93]
	global_store_dwordx4 v[72:73], v[60:63], off
	global_store_dwordx4 v[96:97], v[56:59], off offset:64
	global_store_dwordx4 v[50:51], v[44:47], off
	global_store_dwordx4 v[48:49], v[40:43], off offset:64
	global_store_dwordx4 v[48:49], v[36:39], off offset:512
	global_store_dwordx4 v[48:49], v[32:35], off offset:576
	s_mov_b32 s0, 0x140000
	v_add_co_u32_e32 v40, vcc, s0, v168
	s_mov_b32 s1, 0x160000
	s_nop 0
	v_addc_co_u32_e32 v41, vcc, 0, v169, vcc
	s_mov_b64 s[8:9], 0x140000
	s_mov_b64 s[10:11], 0x160000
	v_add_co_u32_e32 v56, vcc, s1, v168
	v_lshl_add_u64 v[44:45], v[168:169], 0, s[8:9]
	v_lshl_add_u64 v[60:61], v[168:169], 0, s[10:11]
	v_addc_co_u32_e32 v57, vcc, 0, v169, vcc
	global_load_dwordx4 v[32:35], v[44:45], off offset:64
	global_load_dwordx4 v[36:39], v[44:45], off offset:512
	s_nop 0
	global_load_dwordx4 v[40:43], v[40:41], off
	s_nop 0
	global_load_dwordx4 v[44:47], v[44:45], off offset:576
	s_nop 0
	global_load_dwordx4 v[48:51], v[60:61], off offset:64
	global_load_dwordx4 v[52:55], v[60:61], off offset:512
	s_nop 0
	global_load_dwordx4 v[56:59], v[56:57], off
	s_nop 0
	global_load_dwordx4 v[60:63], v[60:61], off offset:576
	s_waitcnt vmcnt(0)
	v_pk_fma_f32 v[28:29], v[28:29], v[140:141], v[40:41]
	v_add_co_u32_e32 v40, vcc, s0, v158
	v_lshl_add_u64 v[64:65], v[158:159], 0, s[8:9]
	s_nop 0
	v_addc_co_u32_e32 v41, vcc, 0, v159, vcc
	v_pk_fma_f32 v[18:19], v[18:19], v[134:135], v[38:39]
	v_pk_fma_f32 v[16:17], v[16:17], v[132:133], v[36:37]
	global_store_dwordx4 v[64:65], v[16:19], off offset:512
	v_pk_fma_f32 v[14:15], v[14:15], v[130:131], v[46:47]
	v_pk_fma_f32 v[12:13], v[12:13], v[128:129], v[44:45]
	v_add_co_u32_e32 v18, vcc, s1, v158
	v_pk_fma_f32 v[30:31], v[30:31], v[142:143], v[42:43]
	s_mov_b32 s18, 0x140000
	v_pk_fma_f32 v[26:27], v[26:27], v[138:139], v[34:35]
	v_pk_fma_f32 v[24:25], v[24:25], v[136:137], v[32:33]
	global_store_dwordx4 v[64:65], v[12:15], off offset:576
	v_lshl_add_u64 v[16:17], v[158:159], 0, s[10:11]
	s_mov_b32 s54, 0x160000
	v_pk_fma_f32 v[14:15], v[22:23], v[142:143], v[58:59]
	v_pk_fma_f32 v[12:13], v[20:21], v[140:141], v[56:57]
	v_addc_co_u32_e32 v19, vcc, 0, v159, vcc
	v_pk_fma_f32 v[10:11], v[10:11], v[138:139], v[50:51]
	v_pk_fma_f32 v[8:9], v[8:9], v[136:137], v[48:49]
	v_pk_fma_f32 v[6:7], v[6:7], v[134:135], v[54:55]
	v_pk_fma_f32 v[4:5], v[4:5], v[132:133], v[52:53]
	v_pk_fma_f32 v[2:3], v[2:3], v[130:131], v[62:63]
	v_pk_fma_f32 v[0:1], v[0:1], v[128:129], v[60:61]
	global_store_dwordx4 v[40:41], v[28:31], off
	global_store_dwordx4 v[64:65], v[24:27], off offset:64
	global_store_dwordx4 v[18:19], v[12:15], off
	global_store_dwordx4 v[16:17], v[8:11], off offset:64
	global_store_dwordx4 v[16:17], v[4:7], off offset:512
	global_store_dwordx4 v[16:17], v[0:3], off offset:576
	s_and_b64 vcc, exec, s[40:41]
	s_mov_b32 s8, s2
	s_mov_b32 s9, s26
	s_mov_b64 s[20:21], s[38:39]
	s_mov_b64 s[0:1], s[36:37]
	s_cbranch_vccz .LBB0_1226
	s_waitcnt vmcnt(0)
	v_readlane_b32 s52, v255, 4
	s_cmpk_gt_u32 s4, 0xff
	v_readlane_b32 s53, v255, 5
	s_cbranch_scc1 .LBB0_1233
	s_barrier
